# P4: all LDS-DMA requests of a step issued in one burst right after its barrier (before the step's MFMAs) instead of interleaved between them
# speedup vs baseline: 1.0087x; 1.0019x over previous
.Lp4f_gloop:
	s_waitcnt lgkmcnt(0)
	v_mfma_f32_32x32x16_bf16 v[50:65], v[236:239], v[220:223], v[50:65]
	v_xor_b32_e32 v244, 0x20, v226
	v_add_u32_e32 v232, v244, v224
	v_add_u32_e32 v244, v244, v225
	v_mfma_f32_32x32x16_bf16 v[34:49], v[240:243], v[220:223], v[34:49]
	ds_read_b128 v[220:223], v232
	ds_read_b128 v[232:235], v232 offset:4096
	v_mfma_f32_32x32x16_bf16 v[18:33], v[236:239], v[228:231], v[18:33]
	ds_read_b128 v[236:239], v244 offset:32768
	ds_read_b128 v[244:247], v244 offset:36864
	v_mfma_f32_32x32x16_bf16 v[2:17], v[240:243], v[228:231], v[2:17]
	s_waitcnt lgkmcnt(0)
	v_mfma_f32_32x32x16_bf16 v[50:65], v[236:239], v[220:223], v[50:65]
	v_xor_b32_e32 v240, 0x40, v226
	v_add_u32_e32 v228, v240, v224
	v_add_u32_e32 v240, v240, v225
	v_mfma_f32_32x32x16_bf16 v[34:49], v[244:247], v[220:223], v[34:49]
	ds_read_b128 v[220:223], v228
	ds_read_b128 v[228:231], v228 offset:4096
	v_mfma_f32_32x32x16_bf16 v[18:33], v[236:239], v[232:235], v[18:33]
	ds_read_b128 v[236:239], v240 offset:32768
	ds_read_b128 v[240:243], v240 offset:36864
	v_mfma_f32_32x32x16_bf16 v[2:17], v[244:247], v[232:235], v[2:17]
	s_waitcnt lgkmcnt(0)
	v_mfma_f32_32x32x16_bf16 v[50:65], v[236:239], v[220:223], v[50:65]
	v_xor_b32_e32 v244, 0x60, v226
	v_add_u32_e32 v232, v244, v224
	v_add_u32_e32 v244, v244, v225
	v_mfma_f32_32x32x16_bf16 v[34:49], v[240:243], v[220:223], v[34:49]
	ds_read_b128 v[220:223], v232
	ds_read_b128 v[232:235], v232 offset:4096
	v_mfma_f32_32x32x16_bf16 v[18:33], v[236:239], v[228:231], v[18:33]
	ds_read_b128 v[236:239], v244 offset:32768
	ds_read_b128 v[244:247], v244 offset:36864
	v_mfma_f32_32x32x16_bf16 v[2:17], v[240:243], v[228:231], v[2:17]
	s_waitcnt vmcnt(0) lgkmcnt(0)
	s_barrier
	s_waitcnt lgkmcnt(0)
	s_add_u32 m0, s30, 0x8000
	s_nop 0
	global_load_lds_dwordx4 v248, s[54:55]
	s_add_u32 m0, s30, 0x9000
	s_nop 0
	global_load_lds_dwordx4 v249, s[54:55]
	s_add_u32 m0, s30, 0xa000
	s_nop 0
	global_load_lds_dwordx4 v250, s[54:55]
	s_add_u32 m0, s30, 0xb000
	s_nop 0
	global_load_lds_dwordx4 v251, s[54:55]
	v_mfma_f32_32x32x16_bf16 v[50:65], v[236:239], v[220:223], v[50:65]
	v_mov_b32_e32 v240, v226
	v_add_u32_e32 v228, v240, v224
	v_add_u32_e32 v240, v240, v225
	v_mfma_f32_32x32x16_bf16 v[34:49], v[244:247], v[220:223], v[34:49]
	ds_read_b128 v[220:223], v228
	ds_read_b128 v[228:231], v228 offset:4096
	v_mfma_f32_32x32x16_bf16 v[18:33], v[236:239], v[232:235], v[18:33]
	ds_read_b128 v[236:239], v240 offset:49152
	ds_read_b128 v[240:243], v240 offset:53248
	v_mfma_f32_32x32x16_bf16 v[2:17], v[244:247], v[232:235], v[2:17]
	s_add_u32 s54, s54, 0x80
	s_addc_u32 s55, s55, 0
	s_waitcnt lgkmcnt(0)
	v_mfma_f32_32x32x16_bf16 v[114:129], v[236:239], v[220:223], v[114:129]
	v_xor_b32_e32 v244, 0x20, v226
	v_add_u32_e32 v232, v244, v224
	v_add_u32_e32 v244, v244, v225
	v_mfma_f32_32x32x16_bf16 v[98:113], v[240:243], v[220:223], v[98:113]
	ds_read_b128 v[220:223], v232
	ds_read_b128 v[232:235], v232 offset:4096
	v_mfma_f32_32x32x16_bf16 v[82:97], v[236:239], v[228:231], v[82:97]
	ds_read_b128 v[236:239], v244 offset:49152
	ds_read_b128 v[244:247], v244 offset:53248
	v_mfma_f32_32x32x16_bf16 v[66:81], v[240:243], v[228:231], v[66:81]
	s_waitcnt lgkmcnt(0)
	v_mfma_f32_32x32x16_bf16 v[114:129], v[236:239], v[220:223], v[114:129]
	v_xor_b32_e32 v240, 0x40, v226
	v_add_u32_e32 v228, v240, v224
	v_add_u32_e32 v240, v240, v225
	v_mfma_f32_32x32x16_bf16 v[98:113], v[244:247], v[220:223], v[98:113]
	ds_read_b128 v[220:223], v228
	ds_read_b128 v[228:231], v228 offset:4096
	v_mfma_f32_32x32x16_bf16 v[82:97], v[236:239], v[232:235], v[82:97]
	ds_read_b128 v[236:239], v240 offset:49152
	ds_read_b128 v[240:243], v240 offset:53248
	v_mfma_f32_32x32x16_bf16 v[66:81], v[244:247], v[232:235], v[66:81]
	s_waitcnt lgkmcnt(0)
	v_mfma_f32_32x32x16_bf16 v[114:129], v[236:239], v[220:223], v[114:129]
	v_xor_b32_e32 v244, 0x60, v226
	v_add_u32_e32 v232, v244, v224
	v_add_u32_e32 v244, v244, v225
	v_mfma_f32_32x32x16_bf16 v[98:113], v[240:243], v[220:223], v[98:113]
	ds_read_b128 v[220:223], v232
	ds_read_b128 v[232:235], v232 offset:4096
	v_mfma_f32_32x32x16_bf16 v[82:97], v[236:239], v[228:231], v[82:97]
	ds_read_b128 v[236:239], v244 offset:49152
	ds_read_b128 v[244:247], v244 offset:53248
	v_mfma_f32_32x32x16_bf16 v[66:81], v[240:243], v[228:231], v[66:81]
	s_waitcnt vmcnt(0) lgkmcnt(0)
	s_barrier
	s_waitcnt lgkmcnt(0)
	s_add_u32 m0, s30, 0xc000
	s_nop 0
	global_load_lds_dwordx4 v248, s[100:101]
	s_add_u32 m0, s30, 0xd000
	s_nop 0
	global_load_lds_dwordx4 v249, s[100:101]
	s_add_u32 m0, s30, 0xe000
	s_nop 0
	global_load_lds_dwordx4 v250, s[100:101]
	s_add_u32 m0, s30, 0xf000
	s_nop 0
	global_load_lds_dwordx4 v251, s[100:101]
	v_mfma_f32_32x32x16_bf16 v[114:129], v[236:239], v[220:223], v[114:129]
	v_mov_b32_e32 v240, v226
	v_add_u32_e32 v228, v240, v224
	v_add_u32_e32 v240, v240, v225
	v_mfma_f32_32x32x16_bf16 v[98:113], v[244:247], v[220:223], v[98:113]
	ds_read_b128 v[220:223], v228
	ds_read_b128 v[228:231], v228 offset:4096
	v_mfma_f32_32x32x16_bf16 v[82:97], v[236:239], v[232:235], v[82:97]
	ds_read_b128 v[236:239], v240 offset:32768
	ds_read_b128 v[240:243], v240 offset:36864
	v_mfma_f32_32x32x16_bf16 v[66:81], v[244:247], v[232:235], v[66:81]
	s_add_u32 s100, s100, 0x80
	s_addc_u32 s101, s101, 0
	s_waitcnt lgkmcnt(0)
	v_mfma_f32_32x32x16_bf16 v[178:193], v[236:239], v[220:223], v[178:193]
	v_xor_b32_e32 v244, 0x20, v226
	v_add_u32_e32 v232, v244, v224
	v_add_u32_e32 v244, v244, v225
	v_mfma_f32_32x32x16_bf16 v[162:177], v[240:243], v[220:223], v[162:177]
	ds_read_b128 v[220:223], v232
	ds_read_b128 v[232:235], v232 offset:4096
	v_mfma_f32_32x32x16_bf16 v[146:161], v[236:239], v[228:231], v[146:161]
	ds_read_b128 v[236:239], v244 offset:32768
	ds_read_b128 v[244:247], v244 offset:36864
	v_mfma_f32_32x32x16_bf16 v[130:145], v[240:243], v[228:231], v[130:145]
	s_waitcnt lgkmcnt(0)
	v_mfma_f32_32x32x16_bf16 v[178:193], v[236:239], v[220:223], v[178:193]
	v_xor_b32_e32 v240, 0x40, v226
	v_add_u32_e32 v228, v240, v224
	v_add_u32_e32 v240, v240, v225
	v_mfma_f32_32x32x16_bf16 v[162:177], v[244:247], v[220:223], v[162:177]
	ds_read_b128 v[220:223], v228
	ds_read_b128 v[228:231], v228 offset:4096
	v_mfma_f32_32x32x16_bf16 v[146:161], v[236:239], v[232:235], v[146:161]
	ds_read_b128 v[236:239], v240 offset:32768
	ds_read_b128 v[240:243], v240 offset:36864
	v_mfma_f32_32x32x16_bf16 v[130:145], v[244:247], v[232:235], v[130:145]
	s_waitcnt lgkmcnt(0)
	v_mfma_f32_32x32x16_bf16 v[178:193], v[236:239], v[220:223], v[178:193]
	v_xor_b32_e32 v244, 0x60, v226
	v_add_u32_e32 v232, v244, v224
	v_add_u32_e32 v244, v244, v225
	v_mfma_f32_32x32x16_bf16 v[162:177], v[240:243], v[220:223], v[162:177]
	ds_read_b128 v[220:223], v232
	ds_read_b128 v[232:235], v232 offset:4096
	v_mfma_f32_32x32x16_bf16 v[146:161], v[236:239], v[228:231], v[146:161]
	ds_read_b128 v[236:239], v244 offset:32768
	ds_read_b128 v[244:247], v244 offset:36864
	v_mfma_f32_32x32x16_bf16 v[130:145], v[240:243], v[228:231], v[130:145]
	s_waitcnt vmcnt(0) lgkmcnt(0)
	s_barrier
	s_waitcnt lgkmcnt(0)
	s_add_u32 m0, s30, 0x8000
	s_nop 0
	global_load_lds_dwordx4 v248, s[52:53]
	s_add_u32 m0, s30, 0x9000
	s_nop 0
	global_load_lds_dwordx4 v249, s[52:53]
	s_add_u32 m0, s30, 0xa000
	s_nop 0
	global_load_lds_dwordx4 v250, s[52:53]
	s_add_u32 m0, s30, 0xb000
	s_nop 0
	global_load_lds_dwordx4 v251, s[52:53]
	s_add_u32 m0, s30, 0x0
	s_nop 0
	global_load_lds_dwordx4 v248, s[98:99]
	s_add_u32 m0, s30, 0x1000
	s_nop 0
	global_load_lds_dwordx4 v249, s[98:99]
	s_add_u32 m0, s30, 0x2000
	s_nop 0
	global_load_lds_dwordx4 v250, s[98:99]
	s_add_u32 m0, s30, 0x3000
	s_nop 0
	global_load_lds_dwordx4 v251, s[98:99]
	v_mfma_f32_32x32x16_bf16 v[178:193], v[236:239], v[220:223], v[178:193]
	v_mov_b32_e32 v240, v226
	v_add_u32_e32 v228, v240, v224
	v_add_u32_e32 v240, v240, v225
	v_mfma_f32_32x32x16_bf16 v[162:177], v[244:247], v[220:223], v[162:177]
	ds_read_b128 v[220:223], v228 offset:16384
	ds_read_b128 v[228:231], v228 offset:20480
	v_mfma_f32_32x32x16_bf16 v[146:161], v[236:239], v[232:235], v[146:161]
	ds_read_b128 v[236:239], v240 offset:49152
	ds_read_b128 v[240:243], v240 offset:53248
	v_mfma_f32_32x32x16_bf16 v[130:145], v[244:247], v[232:235], v[130:145]
	s_add_u32 s52, s52, 0x80
	s_addc_u32 s53, s53, 0
	s_add_u32 s98, s98, 0x80
	s_addc_u32 s99, s99, 0
	s_waitcnt lgkmcnt(0)
	v_mfma_f32_32x32x16_bf16 v[50:65], v[236:239], v[220:223], v[50:65]
	v_xor_b32_e32 v244, 0x20, v226
	v_add_u32_e32 v232, v244, v224
	v_add_u32_e32 v244, v244, v225
	v_mfma_f32_32x32x16_bf16 v[34:49], v[240:243], v[220:223], v[34:49]
	ds_read_b128 v[220:223], v232 offset:16384
	ds_read_b128 v[232:235], v232 offset:20480
	v_mfma_f32_32x32x16_bf16 v[18:33], v[236:239], v[228:231], v[18:33]
	ds_read_b128 v[236:239], v244 offset:49152
	ds_read_b128 v[244:247], v244 offset:53248
	v_mfma_f32_32x32x16_bf16 v[2:17], v[240:243], v[228:231], v[2:17]
	s_waitcnt lgkmcnt(0)
	v_mfma_f32_32x32x16_bf16 v[50:65], v[236:239], v[220:223], v[50:65]
	v_xor_b32_e32 v240, 0x40, v226
	v_add_u32_e32 v228, v240, v224
	v_add_u32_e32 v240, v240, v225
	v_mfma_f32_32x32x16_bf16 v[34:49], v[244:247], v[220:223], v[34:49]
	ds_read_b128 v[220:223], v228 offset:16384
	ds_read_b128 v[228:231], v228 offset:20480
	v_mfma_f32_32x32x16_bf16 v[18:33], v[236:239], v[232:235], v[18:33]
	ds_read_b128 v[236:239], v240 offset:49152
	ds_read_b128 v[240:243], v240 offset:53248
	v_mfma_f32_32x32x16_bf16 v[2:17], v[244:247], v[232:235], v[2:17]
	s_waitcnt lgkmcnt(0)
	v_mfma_f32_32x32x16_bf16 v[50:65], v[236:239], v[220:223], v[50:65]
	v_xor_b32_e32 v244, 0x60, v226
	v_add_u32_e32 v232, v244, v224
	v_add_u32_e32 v244, v244, v225
	v_mfma_f32_32x32x16_bf16 v[34:49], v[240:243], v[220:223], v[34:49]
	ds_read_b128 v[220:223], v232 offset:16384
	ds_read_b128 v[232:235], v232 offset:20480
	v_mfma_f32_32x32x16_bf16 v[18:33], v[236:239], v[228:231], v[18:33]
	ds_read_b128 v[236:239], v244 offset:49152
	ds_read_b128 v[244:247], v244 offset:53248
	v_mfma_f32_32x32x16_bf16 v[2:17], v[240:243], v[228:231], v[2:17]
	s_waitcnt vmcnt(0) lgkmcnt(0)
	s_barrier
	s_waitcnt lgkmcnt(0)
	s_add_u32 m0, s30, 0xc000
	s_nop 0
	global_load_lds_dwordx4 v248, s[54:55]
	s_add_u32 m0, s30, 0xd000
	s_nop 0
	global_load_lds_dwordx4 v249, s[54:55]
	s_add_u32 m0, s30, 0xe000
	s_nop 0
	global_load_lds_dwordx4 v250, s[54:55]
	s_add_u32 m0, s30, 0xf000
	s_nop 0
	global_load_lds_dwordx4 v251, s[54:55]
	v_mfma_f32_32x32x16_bf16 v[50:65], v[236:239], v[220:223], v[50:65]
	v_mov_b32_e32 v240, v226
	v_add_u32_e32 v228, v240, v224
	v_add_u32_e32 v240, v240, v225
	v_mfma_f32_32x32x16_bf16 v[34:49], v[244:247], v[220:223], v[34:49]
	ds_read_b128 v[220:223], v228 offset:16384
	ds_read_b128 v[228:231], v228 offset:20480
	v_mfma_f32_32x32x16_bf16 v[18:33], v[236:239], v[232:235], v[18:33]
	ds_read_b128 v[236:239], v240 offset:32768
	ds_read_b128 v[240:243], v240 offset:36864
	v_mfma_f32_32x32x16_bf16 v[2:17], v[244:247], v[232:235], v[2:17]
	s_add_u32 s54, s54, 0x80
	s_addc_u32 s55, s55, 0
	s_waitcnt lgkmcnt(0)
	v_mfma_f32_32x32x16_bf16 v[114:129], v[236:239], v[220:223], v[114:129]
	v_xor_b32_e32 v244, 0x20, v226
	v_add_u32_e32 v232, v244, v224
	v_add_u32_e32 v244, v244, v225
	v_mfma_f32_32x32x16_bf16 v[98:113], v[240:243], v[220:223], v[98:113]
	ds_read_b128 v[220:223], v232 offset:16384
	ds_read_b128 v[232:235], v232 offset:20480
	v_mfma_f32_32x32x16_bf16 v[82:97], v[236:239], v[228:231], v[82:97]
	ds_read_b128 v[236:239], v244 offset:32768
	ds_read_b128 v[244:247], v244 offset:36864
	v_mfma_f32_32x32x16_bf16 v[66:81], v[240:243], v[228:231], v[66:81]
	s_waitcnt lgkmcnt(0)
	v_mfma_f32_32x32x16_bf16 v[114:129], v[236:239], v[220:223], v[114:129]
	v_xor_b32_e32 v240, 0x40, v226
	v_add_u32_e32 v228, v240, v224
	v_add_u32_e32 v240, v240, v225
	v_mfma_f32_32x32x16_bf16 v[98:113], v[244:247], v[220:223], v[98:113]
	ds_read_b128 v[220:223], v228 offset:16384
	ds_read_b128 v[228:231], v228 offset:20480
	v_mfma_f32_32x32x16_bf16 v[82:97], v[236:239], v[232:235], v[82:97]
	ds_read_b128 v[236:239], v240 offset:32768
	ds_read_b128 v[240:243], v240 offset:36864
	v_mfma_f32_32x32x16_bf16 v[66:81], v[244:247], v[232:235], v[66:81]
	s_waitcnt lgkmcnt(0)
	v_mfma_f32_32x32x16_bf16 v[114:129], v[236:239], v[220:223], v[114:129]
	v_xor_b32_e32 v244, 0x60, v226
	v_add_u32_e32 v232, v244, v224
	v_add_u32_e32 v244, v244, v225
	v_mfma_f32_32x32x16_bf16 v[98:113], v[240:243], v[220:223], v[98:113]
	ds_read_b128 v[220:223], v232 offset:16384
	ds_read_b128 v[232:235], v232 offset:20480
	v_mfma_f32_32x32x16_bf16 v[82:97], v[236:239], v[228:231], v[82:97]
	ds_read_b128 v[236:239], v244 offset:32768
	ds_read_b128 v[244:247], v244 offset:36864
	v_mfma_f32_32x32x16_bf16 v[66:81], v[240:243], v[228:231], v[66:81]
	s_waitcnt vmcnt(0) lgkmcnt(0)
	s_barrier
	s_waitcnt lgkmcnt(0)
	s_add_u32 m0, s30, 0x8000
	s_nop 0
	global_load_lds_dwordx4 v248, s[100:101]
	s_add_u32 m0, s30, 0x9000
	s_nop 0
	global_load_lds_dwordx4 v249, s[100:101]
	s_add_u32 m0, s30, 0xa000
	s_nop 0
	global_load_lds_dwordx4 v250, s[100:101]
	s_add_u32 m0, s30, 0xb000
	s_nop 0
	global_load_lds_dwordx4 v251, s[100:101]
	v_mfma_f32_32x32x16_bf16 v[114:129], v[236:239], v[220:223], v[114:129]
	v_mov_b32_e32 v240, v226
	v_add_u32_e32 v228, v240, v224
	v_add_u32_e32 v240, v240, v225
	v_mfma_f32_32x32x16_bf16 v[98:113], v[244:247], v[220:223], v[98:113]
	ds_read_b128 v[220:223], v228 offset:16384
	ds_read_b128 v[228:231], v228 offset:20480
	v_mfma_f32_32x32x16_bf16 v[82:97], v[236:239], v[232:235], v[82:97]
	ds_read_b128 v[236:239], v240 offset:49152
	ds_read_b128 v[240:243], v240 offset:53248
	v_mfma_f32_32x32x16_bf16 v[66:81], v[244:247], v[232:235], v[66:81]
	s_add_u32 s100, s100, 0x80
	s_addc_u32 s101, s101, 0
	s_waitcnt lgkmcnt(0)
	v_mfma_f32_32x32x16_bf16 v[178:193], v[236:239], v[220:223], v[178:193]
	v_xor_b32_e32 v244, 0x20, v226
	v_add_u32_e32 v232, v244, v224
	v_add_u32_e32 v244, v244, v225
	v_mfma_f32_32x32x16_bf16 v[162:177], v[240:243], v[220:223], v[162:177]
	ds_read_b128 v[220:223], v232 offset:16384
	ds_read_b128 v[232:235], v232 offset:20480
	v_mfma_f32_32x32x16_bf16 v[146:161], v[236:239], v[228:231], v[146:161]
	ds_read_b128 v[236:239], v244 offset:49152
	ds_read_b128 v[244:247], v244 offset:53248
	v_mfma_f32_32x32x16_bf16 v[130:145], v[240:243], v[228:231], v[130:145]
	s_waitcnt lgkmcnt(0)
	v_mfma_f32_32x32x16_bf16 v[178:193], v[236:239], v[220:223], v[178:193]
	v_xor_b32_e32 v240, 0x40, v226
	v_add_u32_e32 v228, v240, v224
	v_add_u32_e32 v240, v240, v225
	v_mfma_f32_32x32x16_bf16 v[162:177], v[244:247], v[220:223], v[162:177]
	ds_read_b128 v[220:223], v228 offset:16384
	ds_read_b128 v[228:231], v228 offset:20480
	v_mfma_f32_32x32x16_bf16 v[146:161], v[236:239], v[232:235], v[146:161]
	ds_read_b128 v[236:239], v240 offset:49152
	ds_read_b128 v[240:243], v240 offset:53248
	v_mfma_f32_32x32x16_bf16 v[130:145], v[244:247], v[232:235], v[130:145]
	s_waitcnt lgkmcnt(0)
	v_mfma_f32_32x32x16_bf16 v[178:193], v[236:239], v[220:223], v[178:193]
	v_xor_b32_e32 v244, 0x60, v226
	v_add_u32_e32 v232, v244, v224
	v_add_u32_e32 v244, v244, v225
	v_mfma_f32_32x32x16_bf16 v[162:177], v[240:243], v[220:223], v[162:177]
	ds_read_b128 v[220:223], v232 offset:16384
	ds_read_b128 v[232:235], v232 offset:20480
	v_mfma_f32_32x32x16_bf16 v[146:161], v[236:239], v[228:231], v[146:161]
	ds_read_b128 v[236:239], v244 offset:49152
	ds_read_b128 v[244:247], v244 offset:53248
	v_mfma_f32_32x32x16_bf16 v[130:145], v[240:243], v[228:231], v[130:145]
	s_waitcnt vmcnt(0) lgkmcnt(0)
	s_barrier
	s_waitcnt lgkmcnt(0)
	s_add_u32 m0, s30, 0xc000
	s_nop 0
	global_load_lds_dwordx4 v248, s[52:53]
	s_add_u32 m0, s30, 0xd000
	s_nop 0
	global_load_lds_dwordx4 v249, s[52:53]
	s_add_u32 m0, s30, 0xe000
	s_nop 0
	global_load_lds_dwordx4 v250, s[52:53]
	s_add_u32 m0, s30, 0xf000
	s_nop 0
	global_load_lds_dwordx4 v251, s[52:53]
	s_add_u32 m0, s30, 0x4000
	s_nop 0
	global_load_lds_dwordx4 v248, s[98:99]
	s_add_u32 m0, s30, 0x5000
	s_nop 0
	global_load_lds_dwordx4 v249, s[98:99]
	s_add_u32 m0, s30, 0x6000
	s_nop 0
	global_load_lds_dwordx4 v250, s[98:99]
	s_add_u32 m0, s30, 0x7000
	s_nop 0
	global_load_lds_dwordx4 v251, s[98:99]
	v_mfma_f32_32x32x16_bf16 v[178:193], v[236:239], v[220:223], v[178:193]
	v_mov_b32_e32 v240, v226
	v_add_u32_e32 v228, v240, v224
	v_add_u32_e32 v240, v240, v225
	v_mfma_f32_32x32x16_bf16 v[162:177], v[244:247], v[220:223], v[162:177]
	ds_read_b128 v[220:223], v228
	ds_read_b128 v[228:231], v228 offset:4096
	v_mfma_f32_32x32x16_bf16 v[146:161], v[236:239], v[232:235], v[146:161]
	ds_read_b128 v[236:239], v240 offset:32768
	ds_read_b128 v[240:243], v240 offset:36864
	v_mfma_f32_32x32x16_bf16 v[130:145], v[244:247], v[232:235], v[130:145]
	s_add_u32 s52, s52, 0x80
	s_addc_u32 s53, s53, 0
	s_add_u32 s98, s98, 0x80
	s_addc_u32 s99, s99, 0
	s_sub_u32 s51, s51, 1
	s_cmp_lg_u32 s51, 0
	s_cbranch_scc1 .Lp4f_gloop
	s_waitcnt lgkmcnt(0)
	v_mfma_f32_32x32x16_bf16 v[50:65], v[236:239], v[220:223], v[50:65]
	v_xor_b32_e32 v244, 0x20, v226
	v_add_u32_e32 v232, v244, v224
	v_add_u32_e32 v244, v244, v225
	v_mfma_f32_32x32x16_bf16 v[34:49], v[240:243], v[220:223], v[34:49]
	ds_read_b128 v[220:223], v232
	ds_read_b128 v[232:235], v232 offset:4096
	v_mfma_f32_32x32x16_bf16 v[18:33], v[236:239], v[228:231], v[18:33]
	ds_read_b128 v[236:239], v244 offset:32768
	ds_read_b128 v[244:247], v244 offset:36864
	v_mfma_f32_32x32x16_bf16 v[2:17], v[240:243], v[228:231], v[2:17]
	s_waitcnt lgkmcnt(0)
	v_mfma_f32_32x32x16_bf16 v[50:65], v[236:239], v[220:223], v[50:65]
	v_xor_b32_e32 v240, 0x40, v226
	v_add_u32_e32 v228, v240, v224
	v_add_u32_e32 v240, v240, v225
	v_mfma_f32_32x32x16_bf16 v[34:49], v[244:247], v[220:223], v[34:49]
	ds_read_b128 v[220:223], v228
	ds_read_b128 v[228:231], v228 offset:4096
	v_mfma_f32_32x32x16_bf16 v[18:33], v[236:239], v[232:235], v[18:33]
	ds_read_b128 v[236:239], v240 offset:32768
	ds_read_b128 v[240:243], v240 offset:36864
	v_mfma_f32_32x32x16_bf16 v[2:17], v[244:247], v[232:235], v[2:17]
	s_waitcnt lgkmcnt(0)
	v_mfma_f32_32x32x16_bf16 v[50:65], v[236:239], v[220:223], v[50:65]
	v_xor_b32_e32 v244, 0x60, v226
	v_add_u32_e32 v232, v244, v224
	v_add_u32_e32 v244, v244, v225
	v_mfma_f32_32x32x16_bf16 v[34:49], v[240:243], v[220:223], v[34:49]
	ds_read_b128 v[220:223], v232
	ds_read_b128 v[232:235], v232 offset:4096
	v_mfma_f32_32x32x16_bf16 v[18:33], v[236:239], v[228:231], v[18:33]
	ds_read_b128 v[236:239], v244 offset:32768
	ds_read_b128 v[244:247], v244 offset:36864
	v_mfma_f32_32x32x16_bf16 v[2:17], v[240:243], v[228:231], v[2:17]
	s_waitcnt vmcnt(0) lgkmcnt(0)
	s_barrier
	s_waitcnt lgkmcnt(0)
	s_add_u32 m0, s30, 0x8000
	s_nop 0
	global_load_lds_dwordx4 v248, s[54:55]
	s_add_u32 m0, s30, 0x9000
	s_nop 0
	global_load_lds_dwordx4 v249, s[54:55]
	s_add_u32 m0, s30, 0xa000
	s_nop 0
	global_load_lds_dwordx4 v250, s[54:55]
	s_add_u32 m0, s30, 0xb000
	s_nop 0
	global_load_lds_dwordx4 v251, s[54:55]
	v_mfma_f32_32x32x16_bf16 v[50:65], v[236:239], v[220:223], v[50:65]
	v_mov_b32_e32 v240, v226
	v_add_u32_e32 v228, v240, v224
	v_add_u32_e32 v240, v240, v225
	v_mfma_f32_32x32x16_bf16 v[34:49], v[244:247], v[220:223], v[34:49]
	ds_read_b128 v[220:223], v228
	ds_read_b128 v[228:231], v228 offset:4096
	v_mfma_f32_32x32x16_bf16 v[18:33], v[236:239], v[232:235], v[18:33]
	ds_read_b128 v[236:239], v240 offset:49152
	ds_read_b128 v[240:243], v240 offset:53248
	v_mfma_f32_32x32x16_bf16 v[2:17], v[244:247], v[232:235], v[2:17]
	s_add_u32 s54, s54, 0x80
	s_addc_u32 s55, s55, 0
	s_waitcnt lgkmcnt(0)
	v_mfma_f32_32x32x16_bf16 v[114:129], v[236:239], v[220:223], v[114:129]
	v_xor_b32_e32 v244, 0x20, v226
	v_add_u32_e32 v232, v244, v224
	v_add_u32_e32 v244, v244, v225
	v_mfma_f32_32x32x16_bf16 v[98:113], v[240:243], v[220:223], v[98:113]
	ds_read_b128 v[220:223], v232
	ds_read_b128 v[232:235], v232 offset:4096
	v_mfma_f32_32x32x16_bf16 v[82:97], v[236:239], v[228:231], v[82:97]
	ds_read_b128 v[236:239], v244 offset:49152
	ds_read_b128 v[244:247], v244 offset:53248
	v_mfma_f32_32x32x16_bf16 v[66:81], v[240:243], v[228:231], v[66:81]
	s_waitcnt lgkmcnt(0)
	v_mfma_f32_32x32x16_bf16 v[114:129], v[236:239], v[220:223], v[114:129]
	v_xor_b32_e32 v240, 0x40, v226
	v_add_u32_e32 v228, v240, v224
	v_add_u32_e32 v240, v240, v225
	v_mfma_f32_32x32x16_bf16 v[98:113], v[244:247], v[220:223], v[98:113]
	ds_read_b128 v[220:223], v228
	ds_read_b128 v[228:231], v228 offset:4096
	v_mfma_f32_32x32x16_bf16 v[82:97], v[236:239], v[232:235], v[82:97]
	ds_read_b128 v[236:239], v240 offset:49152
	ds_read_b128 v[240:243], v240 offset:53248
	v_mfma_f32_32x32x16_bf16 v[66:81], v[244:247], v[232:235], v[66:81]
	s_waitcnt lgkmcnt(0)
	v_mfma_f32_32x32x16_bf16 v[114:129], v[236:239], v[220:223], v[114:129]
	v_xor_b32_e32 v244, 0x60, v226
	v_add_u32_e32 v232, v244, v224
	v_add_u32_e32 v244, v244, v225
	v_mfma_f32_32x32x16_bf16 v[98:113], v[240:243], v[220:223], v[98:113]
	ds_read_b128 v[220:223], v232
	ds_read_b128 v[232:235], v232 offset:4096
	v_mfma_f32_32x32x16_bf16 v[82:97], v[236:239], v[228:231], v[82:97]
	ds_read_b128 v[236:239], v244 offset:49152
	ds_read_b128 v[244:247], v244 offset:53248
	v_mfma_f32_32x32x16_bf16 v[66:81], v[240:243], v[228:231], v[66:81]
	s_waitcnt vmcnt(0) lgkmcnt(0)
	s_barrier
	s_waitcnt lgkmcnt(0)
	s_add_u32 m0, s30, 0xc000
	s_nop 0
	global_load_lds_dwordx4 v248, s[100:101]
	s_add_u32 m0, s30, 0xd000
	s_nop 0
	global_load_lds_dwordx4 v249, s[100:101]
	s_add_u32 m0, s30, 0xe000
	s_nop 0
	global_load_lds_dwordx4 v250, s[100:101]
	s_add_u32 m0, s30, 0xf000
	s_nop 0
	global_load_lds_dwordx4 v251, s[100:101]
	v_mfma_f32_32x32x16_bf16 v[114:129], v[236:239], v[220:223], v[114:129]
	v_mov_b32_e32 v240, v226
	v_add_u32_e32 v228, v240, v224
	v_add_u32_e32 v240, v240, v225
	v_mfma_f32_32x32x16_bf16 v[98:113], v[244:247], v[220:223], v[98:113]
	ds_read_b128 v[220:223], v228
	ds_read_b128 v[228:231], v228 offset:4096
	v_mfma_f32_32x32x16_bf16 v[82:97], v[236:239], v[232:235], v[82:97]
	ds_read_b128 v[236:239], v240 offset:32768
	ds_read_b128 v[240:243], v240 offset:36864
	v_mfma_f32_32x32x16_bf16 v[66:81], v[244:247], v[232:235], v[66:81]
	s_add_u32 s100, s100, 0x80
	s_addc_u32 s101, s101, 0
	s_waitcnt lgkmcnt(0)
	v_mfma_f32_32x32x16_bf16 v[178:193], v[236:239], v[220:223], v[178:193]
	v_xor_b32_e32 v244, 0x20, v226
	v_add_u32_e32 v232, v244, v224
	v_add_u32_e32 v244, v244, v225
	v_mfma_f32_32x32x16_bf16 v[162:177], v[240:243], v[220:223], v[162:177]
	ds_read_b128 v[220:223], v232
	ds_read_b128 v[232:235], v232 offset:4096
	v_mfma_f32_32x32x16_bf16 v[146:161], v[236:239], v[228:231], v[146:161]
	ds_read_b128 v[236:239], v244 offset:32768
	ds_read_b128 v[244:247], v244 offset:36864
	v_mfma_f32_32x32x16_bf16 v[130:145], v[240:243], v[228:231], v[130:145]
	s_waitcnt lgkmcnt(0)
	v_mfma_f32_32x32x16_bf16 v[178:193], v[236:239], v[220:223], v[178:193]
	v_xor_b32_e32 v240, 0x40, v226
	v_add_u32_e32 v228, v240, v224
	v_add_u32_e32 v240, v240, v225
	v_mfma_f32_32x32x16_bf16 v[162:177], v[244:247], v[220:223], v[162:177]
	ds_read_b128 v[220:223], v228
	ds_read_b128 v[228:231], v228 offset:4096
	v_mfma_f32_32x32x16_bf16 v[146:161], v[236:239], v[232:235], v[146:161]
	ds_read_b128 v[236:239], v240 offset:32768
	ds_read_b128 v[240:243], v240 offset:36864
	v_mfma_f32_32x32x16_bf16 v[130:145], v[244:247], v[232:235], v[130:145]
	s_waitcnt lgkmcnt(0)
	v_mfma_f32_32x32x16_bf16 v[178:193], v[236:239], v[220:223], v[178:193]
	v_xor_b32_e32 v244, 0x60, v226
	v_add_u32_e32 v232, v244, v224
	v_add_u32_e32 v244, v244, v225
	v_mfma_f32_32x32x16_bf16 v[162:177], v[240:243], v[220:223], v[162:177]
	ds_read_b128 v[220:223], v232
	ds_read_b128 v[232:235], v232 offset:4096
	v_mfma_f32_32x32x16_bf16 v[146:161], v[236:239], v[228:231], v[146:161]
	ds_read_b128 v[236:239], v244 offset:32768
	ds_read_b128 v[244:247], v244 offset:36864
	v_mfma_f32_32x32x16_bf16 v[130:145], v[240:243], v[228:231], v[130:145]
	s_waitcnt vmcnt(0) lgkmcnt(0)
	s_barrier
	s_waitcnt lgkmcnt(0)
	s_add_u32 m0, s30, 0x8000
	s_nop 0
	global_load_lds_dwordx4 v248, s[52:53]
	s_add_u32 m0, s30, 0x9000
	s_nop 0
	global_load_lds_dwordx4 v249, s[52:53]
	s_add_u32 m0, s30, 0xa000
	s_nop 0
	global_load_lds_dwordx4 v250, s[52:53]
	s_add_u32 m0, s30, 0xb000
	s_nop 0
	global_load_lds_dwordx4 v251, s[52:53]
	v_mfma_f32_32x32x16_bf16 v[178:193], v[236:239], v[220:223], v[178:193]
	v_mov_b32_e32 v240, v226
	v_add_u32_e32 v228, v240, v224
	v_add_u32_e32 v240, v240, v225
	v_mfma_f32_32x32x16_bf16 v[162:177], v[244:247], v[220:223], v[162:177]
	ds_read_b128 v[220:223], v228 offset:16384
	ds_read_b128 v[228:231], v228 offset:20480
	v_mfma_f32_32x32x16_bf16 v[146:161], v[236:239], v[232:235], v[146:161]
	ds_read_b128 v[236:239], v240 offset:49152
	ds_read_b128 v[240:243], v240 offset:53248
	v_mfma_f32_32x32x16_bf16 v[130:145], v[244:247], v[232:235], v[130:145]
	s_add_u32 s52, s52, 0x80
	s_addc_u32 s53, s53, 0
	s_waitcnt lgkmcnt(0)
	v_mfma_f32_32x32x16_bf16 v[50:65], v[236:239], v[220:223], v[50:65]
	v_xor_b32_e32 v244, 0x20, v226
	v_add_u32_e32 v232, v244, v224
	v_add_u32_e32 v244, v244, v225
	v_mfma_f32_32x32x16_bf16 v[34:49], v[240:243], v[220:223], v[34:49]
	ds_read_b128 v[220:223], v232 offset:16384
	ds_read_b128 v[232:235], v232 offset:20480
	v_mfma_f32_32x32x16_bf16 v[18:33], v[236:239], v[228:231], v[18:33]
	ds_read_b128 v[236:239], v244 offset:49152
	ds_read_b128 v[244:247], v244 offset:53248
	v_mfma_f32_32x32x16_bf16 v[2:17], v[240:243], v[228:231], v[2:17]
	s_waitcnt lgkmcnt(0)
	v_mfma_f32_32x32x16_bf16 v[50:65], v[236:239], v[220:223], v[50:65]
	v_xor_b32_e32 v240, 0x40, v226
	v_add_u32_e32 v228, v240, v224
	v_add_u32_e32 v240, v240, v225
	v_mfma_f32_32x32x16_bf16 v[34:49], v[244:247], v[220:223], v[34:49]
	ds_read_b128 v[220:223], v228 offset:16384
	ds_read_b128 v[228:231], v228 offset:20480
	v_mfma_f32_32x32x16_bf16 v[18:33], v[236:239], v[232:235], v[18:33]
	ds_read_b128 v[236:239], v240 offset:49152
	ds_read_b128 v[240:243], v240 offset:53248
	v_mfma_f32_32x32x16_bf16 v[2:17], v[244:247], v[232:235], v[2:17]
	s_waitcnt lgkmcnt(0)
	v_mfma_f32_32x32x16_bf16 v[50:65], v[236:239], v[220:223], v[50:65]
	v_xor_b32_e32 v244, 0x60, v226
	v_add_u32_e32 v232, v244, v224
	v_add_u32_e32 v244, v244, v225
	v_mfma_f32_32x32x16_bf16 v[34:49], v[240:243], v[220:223], v[34:49]
	ds_read_b128 v[220:223], v232 offset:16384
	ds_read_b128 v[232:235], v232 offset:20480
	v_mfma_f32_32x32x16_bf16 v[18:33], v[236:239], v[228:231], v[18:33]
	ds_read_b128 v[236:239], v244 offset:49152
	ds_read_b128 v[244:247], v244 offset:53248
	v_mfma_f32_32x32x16_bf16 v[2:17], v[240:243], v[228:231], v[2:17]
	s_waitcnt vmcnt(0) lgkmcnt(0)
	s_barrier
	s_waitcnt lgkmcnt(0)
	s_add_u32 m0, s30, 0xc000
	s_nop 0
	global_load_lds_dwordx4 v248, s[54:55]
	s_add_u32 m0, s30, 0xd000
	s_nop 0
	global_load_lds_dwordx4 v249, s[54:55]
	s_add_u32 m0, s30, 0xe000
	s_nop 0
	global_load_lds_dwordx4 v250, s[54:55]
	s_add_u32 m0, s30, 0xf000
	s_nop 0
	global_load_lds_dwordx4 v251, s[54:55]
	v_mfma_f32_32x32x16_bf16 v[50:65], v[236:239], v[220:223], v[50:65]
	v_mov_b32_e32 v240, v226
	v_add_u32_e32 v228, v240, v224
	v_add_u32_e32 v240, v240, v225
	v_mfma_f32_32x32x16_bf16 v[34:49], v[244:247], v[220:223], v[34:49]
	ds_read_b128 v[220:223], v228 offset:16384
	ds_read_b128 v[228:231], v228 offset:20480
	v_mfma_f32_32x32x16_bf16 v[18:33], v[236:239], v[232:235], v[18:33]
	ds_read_b128 v[236:239], v240 offset:32768
	ds_read_b128 v[240:243], v240 offset:36864
	v_mfma_f32_32x32x16_bf16 v[2:17], v[244:247], v[232:235], v[2:17]
	s_add_u32 s54, s54, 0x80
	s_addc_u32 s55, s55, 0
	s_waitcnt lgkmcnt(0)
	v_mfma_f32_32x32x16_bf16 v[114:129], v[236:239], v[220:223], v[114:129]
	v_xor_b32_e32 v244, 0x20, v226
	v_add_u32_e32 v232, v244, v224
	v_add_u32_e32 v244, v244, v225
	v_mfma_f32_32x32x16_bf16 v[98:113], v[240:243], v[220:223], v[98:113]
	ds_read_b128 v[220:223], v232 offset:16384
	ds_read_b128 v[232:235], v232 offset:20480
	v_mfma_f32_32x32x16_bf16 v[82:97], v[236:239], v[228:231], v[82:97]
	ds_read_b128 v[236:239], v244 offset:32768
	ds_read_b128 v[244:247], v244 offset:36864
	v_mfma_f32_32x32x16_bf16 v[66:81], v[240:243], v[228:231], v[66:81]
	s_waitcnt lgkmcnt(0)
	v_mfma_f32_32x32x16_bf16 v[114:129], v[236:239], v[220:223], v[114:129]
	v_xor_b32_e32 v240, 0x40, v226
	v_add_u32_e32 v228, v240, v224
	v_add_u32_e32 v240, v240, v225
	v_mfma_f32_32x32x16_bf16 v[98:113], v[244:247], v[220:223], v[98:113]
	ds_read_b128 v[220:223], v228 offset:16384
	ds_read_b128 v[228:231], v228 offset:20480
	v_mfma_f32_32x32x16_bf16 v[82:97], v[236:239], v[232:235], v[82:97]
	ds_read_b128 v[236:239], v240 offset:32768
	ds_read_b128 v[240:243], v240 offset:36864
	v_mfma_f32_32x32x16_bf16 v[66:81], v[244:247], v[232:235], v[66:81]
	s_waitcnt lgkmcnt(0)
	v_mfma_f32_32x32x16_bf16 v[114:129], v[236:239], v[220:223], v[114:129]
	v_xor_b32_e32 v244, 0x60, v226
	v_add_u32_e32 v232, v244, v224
	v_add_u32_e32 v244, v244, v225
	v_mfma_f32_32x32x16_bf16 v[98:113], v[240:243], v[220:223], v[98:113]
	ds_read_b128 v[220:223], v232 offset:16384
	ds_read_b128 v[232:235], v232 offset:20480
	v_mfma_f32_32x32x16_bf16 v[82:97], v[236:239], v[228:231], v[82:97]
	ds_read_b128 v[236:239], v244 offset:32768
	ds_read_b128 v[244:247], v244 offset:36864
	v_mfma_f32_32x32x16_bf16 v[66:81], v[240:243], v[228:231], v[66:81]
	s_add_u32 s98, s48, 0x0
	s_addc_u32 s99, s49, 0
	s_add_u32 s100, s44, 0x0
	s_addc_u32 s101, s45, 0
	s_waitcnt vmcnt(0) lgkmcnt(0)
	s_barrier
	s_waitcnt lgkmcnt(0)
	s_add_u32 m0, s30, 0x0
	s_nop 0
	global_load_lds_dwordx4 v200, s[98:99]
	s_add_u32 m0, s30, 0x1000
	s_nop 0
	global_load_lds_dwordx4 v201, s[98:99]
	s_add_u32 m0, s30, 0x2000
	s_nop 0
	global_load_lds_dwordx4 v202, s[98:99]
	s_add_u32 m0, s30, 0x3000
	s_nop 0
	global_load_lds_dwordx4 v204, s[98:99]
	s_add_u32 m0, s30, 0x8000
	s_nop 0
	global_load_lds_dwordx4 v200, s[100:101]
	s_add_u32 m0, s30, 0x9000
	s_nop 0
	global_load_lds_dwordx4 v201, s[100:101]
	s_add_u32 m0, s30, 0xa000
	s_nop 0
	global_load_lds_dwordx4 v202, s[100:101]
	s_add_u32 m0, s30, 0xb000
	s_nop 0
	global_load_lds_dwordx4 v204, s[100:101]
	v_mfma_f32_32x32x16_bf16 v[114:129], v[236:239], v[220:223], v[114:129]
	v_mov_b32_e32 v240, v226
	v_add_u32_e32 v228, v240, v224
	v_add_u32_e32 v240, v240, v225
	v_mfma_f32_32x32x16_bf16 v[98:113], v[244:247], v[220:223], v[98:113]
	ds_read_b128 v[220:223], v228 offset:16384
	ds_read_b128 v[228:231], v228 offset:20480
	v_mfma_f32_32x32x16_bf16 v[82:97], v[236:239], v[232:235], v[82:97]
	ds_read_b128 v[236:239], v240 offset:49152
	ds_read_b128 v[240:243], v240 offset:53248
	v_mfma_f32_32x32x16_bf16 v[66:81], v[244:247], v[232:235], v[66:81]
	s_add_u32 s98, s98, 0x80
	s_addc_u32 s99, s99, 0
	s_add_u32 s100, s100, 0x80
	s_addc_u32 s101, s101, 0
	s_waitcnt lgkmcnt(0)
	v_mfma_f32_32x32x16_bf16 v[178:193], v[236:239], v[220:223], v[178:193]
	v_xor_b32_e32 v244, 0x20, v226
	v_add_u32_e32 v232, v244, v224
	v_add_u32_e32 v244, v244, v225
	v_mfma_f32_32x32x16_bf16 v[162:177], v[240:243], v[220:223], v[162:177]
	ds_read_b128 v[220:223], v232 offset:16384
	ds_read_b128 v[232:235], v232 offset:20480
	v_mfma_f32_32x32x16_bf16 v[146:161], v[236:239], v[228:231], v[146:161]
	ds_read_b128 v[236:239], v244 offset:49152
	ds_read_b128 v[244:247], v244 offset:53248
	v_mfma_f32_32x32x16_bf16 v[130:145], v[240:243], v[228:231], v[130:145]
	s_waitcnt lgkmcnt(0)
	v_mfma_f32_32x32x16_bf16 v[178:193], v[236:239], v[220:223], v[178:193]
	v_xor_b32_e32 v240, 0x40, v226
	v_add_u32_e32 v228, v240, v224
	v_add_u32_e32 v240, v240, v225
	v_mfma_f32_32x32x16_bf16 v[162:177], v[244:247], v[220:223], v[162:177]
	ds_read_b128 v[220:223], v228 offset:16384
	ds_read_b128 v[228:231], v228 offset:20480
	v_mfma_f32_32x32x16_bf16 v[146:161], v[236:239], v[232:235], v[146:161]
	ds_read_b128 v[236:239], v240 offset:49152
	ds_read_b128 v[240:243], v240 offset:53248
	v_mfma_f32_32x32x16_bf16 v[130:145], v[244:247], v[232:235], v[130:145]
	s_waitcnt lgkmcnt(0)
	v_mfma_f32_32x32x16_bf16 v[178:193], v[236:239], v[220:223], v[178:193]
	v_xor_b32_e32 v244, 0x60, v226
	v_add_u32_e32 v232, v244, v224
	v_add_u32_e32 v244, v244, v225
	v_mfma_f32_32x32x16_bf16 v[162:177], v[240:243], v[220:223], v[162:177]
	ds_read_b128 v[220:223], v232 offset:16384
	ds_read_b128 v[232:235], v232 offset:20480
	v_mfma_f32_32x32x16_bf16 v[146:161], v[236:239], v[228:231], v[146:161]
	ds_read_b128 v[236:239], v244 offset:49152
	ds_read_b128 v[244:247], v244 offset:53248
	v_mfma_f32_32x32x16_bf16 v[130:145], v[240:243], v[228:231], v[130:145]
	s_waitcnt lgkmcnt(0)
	v_mfma_f32_32x32x16_bf16 v[178:193], v[236:239], v[220:223], v[178:193]
	v_mfma_f32_32x32x16_bf16 v[162:177], v[244:247], v[220:223], v[162:177]
	v_mfma_f32_32x32x16_bf16 v[146:161], v[236:239], v[232:235], v[146:161]
	v_mfma_f32_32x32x16_bf16 v[130:145], v[244:247], v[232:235], v[130:145]
	s_waitcnt lgkmcnt(0)
	s_barrier
	s_add_u32 m0, s30, 0x4000
	s_nop 0
	global_load_lds_dwordx4 v200, s[98:99]
	s_add_u32 m0, s30, 0x5000
	s_nop 0
	global_load_lds_dwordx4 v201, s[98:99]
	s_add_u32 m0, s30, 0x6000
	s_nop 0
	global_load_lds_dwordx4 v202, s[98:99]
	s_add_u32 m0, s30, 0x7000
	s_nop 0
	global_load_lds_dwordx4 v204, s[98:99]
	s_add_u32 m0, s30, 0xc000
	s_nop 0
	global_load_lds_dwordx4 v200, s[100:101]
	s_add_u32 m0, s30, 0xd000
	s_nop 0
	global_load_lds_dwordx4 v201, s[100:101]
	s_add_u32 m0, s30, 0xe000
	s_nop 0
	global_load_lds_dwordx4 v202, s[100:101]
	s_add_u32 m0, s30, 0xf000
	s_nop 0
	global_load_lds_dwordx4 v204, s[100:101]
	s_add_u32 s98, s98, 0x80
	s_addc_u32 s99, s99, 0
	s_add_u32 s100, s100, 0x80
	s_addc_u32 s101, s101, 0
	s_nop 7
	v_mul_f32_e32 v220, 0xbfb8aa3b, v192
	v_mul_f32_e32 v221, 0xbfb8aa3b, v193
	v_mul_f32_e32 v222, 0xbfb8aa3b, v190
	v_mul_f32_e32 v223, 0xbfb8aa3b, v191
	v_exp_f32_e32 v220, v220
	v_exp_f32_e32 v221, v221
	v_exp_f32_e32 v222, v222
	v_exp_f32_e32 v223, v223
	v_add_f32_e32 v220, 1.0, v220
	v_add_f32_e32 v221, 1.0, v221
	v_add_f32_e32 v222, 1.0, v222
	v_add_f32_e32 v223, 1.0, v223
	v_rcp_f32_e32 v228, v220
	v_rcp_f32_e32 v229, v221
	v_rcp_f32_e32 v230, v222
	v_rcp_f32_e32 v231, v223
	v_fma_f32 v232, -v220, v228, 1.0
	v_fma_f32 v233, -v221, v229, 1.0
	v_fma_f32 v234, -v222, v230, 1.0
	v_fma_f32 v235, -v223, v231, 1.0
	v_fmac_f32_e32 v228, v232, v228
	v_fmac_f32_e32 v229, v233, v229
	v_fmac_f32_e32 v230, v234, v230
	v_fmac_f32_e32 v231, v235, v231
	v_div_fixup_f32 v228, v228, v220, 1.0
	v_div_fixup_f32 v229, v229, v221, 1.0
	v_div_fixup_f32 v230, v230, v222, 1.0
	v_div_fixup_f32 v231, v231, v223, 1.0
	v_cvt_pk_bf16_f32 v193, v228, v229
	v_cvt_pk_bf16_f32 v192, v230, v231
	v_mul_f32_e32 v220, 0xbfb8aa3b, v188
	v_mul_f32_e32 v221, 0xbfb8aa3b, v189
	v_mul_f32_e32 v222, 0xbfb8aa3b, v186
	v_mul_f32_e32 v223, 0xbfb8aa3b, v187
	v_exp_f32_e32 v220, v220
	v_exp_f32_e32 v221, v221
	v_exp_f32_e32 v222, v222
	v_exp_f32_e32 v223, v223
	v_add_f32_e32 v220, 1.0, v220
	v_add_f32_e32 v221, 1.0, v221
	v_add_f32_e32 v222, 1.0, v222
	v_add_f32_e32 v223, 1.0, v223
	v_rcp_f32_e32 v228, v220
	v_rcp_f32_e32 v229, v221
	v_rcp_f32_e32 v230, v222
	v_rcp_f32_e32 v231, v223
	v_fma_f32 v232, -v220, v228, 1.0
	v_fma_f32 v233, -v221, v229, 1.0
	v_fma_f32 v234, -v222, v230, 1.0
	v_fma_f32 v235, -v223, v231, 1.0
	v_fmac_f32_e32 v228, v232, v228
	v_fmac_f32_e32 v229, v233, v229
	v_fmac_f32_e32 v230, v234, v230
	v_fmac_f32_e32 v231, v235, v231
	v_div_fixup_f32 v228, v228, v220, 1.0
	v_div_fixup_f32 v229, v229, v221, 1.0
	v_div_fixup_f32 v230, v230, v222, 1.0
	v_div_fixup_f32 v231, v231, v223, 1.0
	v_cvt_pk_bf16_f32 v191, v228, v229
	v_cvt_pk_bf16_f32 v190, v230, v231
	v_mul_f32_e32 v220, 0xbfb8aa3b, v184
	v_mul_f32_e32 v221, 0xbfb8aa3b, v185
	v_mul_f32_e32 v222, 0xbfb8aa3b, v182
	v_mul_f32_e32 v223, 0xbfb8aa3b, v183
	v_exp_f32_e32 v220, v220
	v_exp_f32_e32 v221, v221
	v_exp_f32_e32 v222, v222
	v_exp_f32_e32 v223, v223
	v_add_f32_e32 v220, 1.0, v220
	v_add_f32_e32 v221, 1.0, v221
	v_add_f32_e32 v222, 1.0, v222
	v_add_f32_e32 v223, 1.0, v223
	v_rcp_f32_e32 v228, v220
	v_rcp_f32_e32 v229, v221
	v_rcp_f32_e32 v230, v222
	v_rcp_f32_e32 v231, v223
	v_fma_f32 v232, -v220, v228, 1.0
	v_fma_f32 v233, -v221, v229, 1.0
	v_fma_f32 v234, -v222, v230, 1.0
	v_fma_f32 v235, -v223, v231, 1.0
	v_fmac_f32_e32 v228, v232, v228
	v_fmac_f32_e32 v229, v233, v229
	v_fmac_f32_e32 v230, v234, v230
	v_fmac_f32_e32 v231, v235, v231
	v_div_fixup_f32 v228, v228, v220, 1.0
	v_div_fixup_f32 v229, v229, v221, 1.0
	v_div_fixup_f32 v230, v230, v222, 1.0
	v_div_fixup_f32 v231, v231, v223, 1.0
	v_cvt_pk_bf16_f32 v189, v228, v229
	v_cvt_pk_bf16_f32 v188, v230, v231
	v_mul_f32_e32 v220, 0xbfb8aa3b, v180
	v_mul_f32_e32 v221, 0xbfb8aa3b, v181
	v_mul_f32_e32 v222, 0xbfb8aa3b, v178
	v_mul_f32_e32 v223, 0xbfb8aa3b, v179
	v_exp_f32_e32 v220, v220
	v_exp_f32_e32 v221, v221
	v_exp_f32_e32 v222, v222
	v_exp_f32_e32 v223, v223
	v_add_f32_e32 v220, 1.0, v220
	v_add_f32_e32 v221, 1.0, v221
	v_add_f32_e32 v222, 1.0, v222
	v_add_f32_e32 v223, 1.0, v223
	v_rcp_f32_e32 v228, v220
	v_rcp_f32_e32 v229, v221
	v_rcp_f32_e32 v230, v222
	v_rcp_f32_e32 v231, v223
	v_fma_f32 v232, -v220, v228, 1.0
	v_fma_f32 v233, -v221, v229, 1.0
	v_fma_f32 v234, -v222, v230, 1.0
	v_fma_f32 v235, -v223, v231, 1.0
	v_fmac_f32_e32 v228, v232, v228
	v_fmac_f32_e32 v229, v233, v229
	v_fmac_f32_e32 v230, v234, v230
	v_fmac_f32_e32 v231, v235, v231
	v_div_fixup_f32 v228, v228, v220, 1.0
	v_div_fixup_f32 v229, v229, v221, 1.0
	v_div_fixup_f32 v230, v230, v222, 1.0
	v_div_fixup_f32 v231, v231, v223, 1.0
	v_cvt_pk_bf16_f32 v187, v228, v229
	v_cvt_pk_bf16_f32 v186, v230, v231
	v_mul_f32_e32 v220, 0xbfb8aa3b, v176
	v_mul_f32_e32 v221, 0xbfb8aa3b, v177
	v_mul_f32_e32 v222, 0xbfb8aa3b, v174
	v_mul_f32_e32 v223, 0xbfb8aa3b, v175
	v_exp_f32_e32 v220, v220
	v_exp_f32_e32 v221, v221
	v_exp_f32_e32 v222, v222
	v_exp_f32_e32 v223, v223
	v_add_f32_e32 v220, 1.0, v220
	v_add_f32_e32 v221, 1.0, v221
	v_add_f32_e32 v222, 1.0, v222
	v_add_f32_e32 v223, 1.0, v223
	v_rcp_f32_e32 v228, v220
	v_rcp_f32_e32 v229, v221
	v_rcp_f32_e32 v230, v222
	v_rcp_f32_e32 v231, v223
	v_fma_f32 v232, -v220, v228, 1.0
	v_fma_f32 v233, -v221, v229, 1.0
	v_fma_f32 v234, -v222, v230, 1.0
	v_fma_f32 v235, -v223, v231, 1.0
	v_fmac_f32_e32 v228, v232, v228
	v_fmac_f32_e32 v229, v233, v229
	v_fmac_f32_e32 v230, v234, v230
	v_fmac_f32_e32 v231, v235, v231
	v_div_fixup_f32 v228, v228, v220, 1.0
	v_div_fixup_f32 v229, v229, v221, 1.0
	v_div_fixup_f32 v230, v230, v222, 1.0
	v_div_fixup_f32 v231, v231, v223, 1.0
	v_cvt_pk_bf16_f32 v185, v228, v229
	v_cvt_pk_bf16_f32 v184, v230, v231
	v_mul_f32_e32 v220, 0xbfb8aa3b, v172
	v_mul_f32_e32 v221, 0xbfb8aa3b, v173
	v_mul_f32_e32 v222, 0xbfb8aa3b, v170
	v_mul_f32_e32 v223, 0xbfb8aa3b, v171
	v_exp_f32_e32 v220, v220
	v_exp_f32_e32 v221, v221
	v_exp_f32_e32 v222, v222
	v_exp_f32_e32 v223, v223
	v_add_f32_e32 v220, 1.0, v220
	v_add_f32_e32 v221, 1.0, v221
	v_add_f32_e32 v222, 1.0, v222
	v_add_f32_e32 v223, 1.0, v223
	v_rcp_f32_e32 v228, v220
	v_rcp_f32_e32 v229, v221
	v_rcp_f32_e32 v230, v222
	v_rcp_f32_e32 v231, v223
	v_fma_f32 v232, -v220, v228, 1.0
	v_fma_f32 v233, -v221, v229, 1.0
	v_fma_f32 v234, -v222, v230, 1.0
	v_fma_f32 v235, -v223, v231, 1.0
	v_fmac_f32_e32 v228, v232, v228
	v_fmac_f32_e32 v229, v233, v229
	v_fmac_f32_e32 v230, v234, v230
	v_fmac_f32_e32 v231, v235, v231
	v_div_fixup_f32 v228, v228, v220, 1.0
	v_div_fixup_f32 v229, v229, v221, 1.0
	v_div_fixup_f32 v230, v230, v222, 1.0
	v_div_fixup_f32 v231, v231, v223, 1.0
	v_cvt_pk_bf16_f32 v183, v228, v229
	v_cvt_pk_bf16_f32 v182, v230, v231
	v_mul_f32_e32 v220, 0xbfb8aa3b, v168
	v_mul_f32_e32 v221, 0xbfb8aa3b, v169
	v_mul_f32_e32 v222, 0xbfb8aa3b, v166
	v_mul_f32_e32 v223, 0xbfb8aa3b, v167
	v_exp_f32_e32 v220, v220
	v_exp_f32_e32 v221, v221
	v_exp_f32_e32 v222, v222
	v_exp_f32_e32 v223, v223
	v_add_f32_e32 v220, 1.0, v220
	v_add_f32_e32 v221, 1.0, v221
	v_add_f32_e32 v222, 1.0, v222
	v_add_f32_e32 v223, 1.0, v223
	v_rcp_f32_e32 v228, v220
	v_rcp_f32_e32 v229, v221
	v_rcp_f32_e32 v230, v222
	v_rcp_f32_e32 v231, v223
	v_fma_f32 v232, -v220, v228, 1.0
	v_fma_f32 v233, -v221, v229, 1.0
	v_fma_f32 v234, -v222, v230, 1.0
	v_fma_f32 v235, -v223, v231, 1.0
	v_fmac_f32_e32 v228, v232, v228
	v_fmac_f32_e32 v229, v233, v229
	v_fmac_f32_e32 v230, v234, v230
	v_fmac_f32_e32 v231, v235, v231
	v_div_fixup_f32 v228, v228, v220, 1.0
	v_div_fixup_f32 v229, v229, v221, 1.0
	v_div_fixup_f32 v230, v230, v222, 1.0
	v_div_fixup_f32 v231, v231, v223, 1.0
	v_cvt_pk_bf16_f32 v181, v228, v229
	v_cvt_pk_bf16_f32 v180, v230, v231
	v_mul_f32_e32 v220, 0xbfb8aa3b, v164
	v_mul_f32_e32 v221, 0xbfb8aa3b, v165
	v_mul_f32_e32 v222, 0xbfb8aa3b, v162
	v_mul_f32_e32 v223, 0xbfb8aa3b, v163
	v_exp_f32_e32 v220, v220
	v_exp_f32_e32 v221, v221
	v_exp_f32_e32 v222, v222
	v_exp_f32_e32 v223, v223
	v_add_f32_e32 v220, 1.0, v220
	v_add_f32_e32 v221, 1.0, v221
	v_add_f32_e32 v222, 1.0, v222
	v_add_f32_e32 v223, 1.0, v223
	v_rcp_f32_e32 v228, v220
	v_rcp_f32_e32 v229, v221
	v_rcp_f32_e32 v230, v222
	v_rcp_f32_e32 v231, v223
	v_fma_f32 v232, -v220, v228, 1.0
	v_fma_f32 v233, -v221, v229, 1.0
	v_fma_f32 v234, -v222, v230, 1.0
	v_fma_f32 v235, -v223, v231, 1.0
	v_fmac_f32_e32 v228, v232, v228
	v_fmac_f32_e32 v229, v233, v229
	v_fmac_f32_e32 v230, v234, v230
	v_fmac_f32_e32 v231, v235, v231
	v_div_fixup_f32 v228, v228, v220, 1.0
	v_div_fixup_f32 v229, v229, v221, 1.0
	v_div_fixup_f32 v230, v230, v222, 1.0
	v_div_fixup_f32 v231, v231, v223, 1.0
	v_cvt_pk_bf16_f32 v179, v228, v229
	v_cvt_pk_bf16_f32 v178, v230, v231
	v_mul_f32_e32 v220, 0xbfb8aa3b, v160
	v_mul_f32_e32 v221, 0xbfb8aa3b, v161
	v_mul_f32_e32 v222, 0xbfb8aa3b, v158
	v_mul_f32_e32 v223, 0xbfb8aa3b, v159
	v_exp_f32_e32 v220, v220
	v_exp_f32_e32 v221, v221
	v_exp_f32_e32 v222, v222
	v_exp_f32_e32 v223, v223
	v_add_f32_e32 v220, 1.0, v220
	v_add_f32_e32 v221, 1.0, v221
	v_add_f32_e32 v222, 1.0, v222
	v_add_f32_e32 v223, 1.0, v223
	v_rcp_f32_e32 v228, v220
	v_rcp_f32_e32 v229, v221
	v_rcp_f32_e32 v230, v222
	v_rcp_f32_e32 v231, v223
	v_fma_f32 v232, -v220, v228, 1.0
	v_fma_f32 v233, -v221, v229, 1.0
	v_fma_f32 v234, -v222, v230, 1.0
	v_fma_f32 v235, -v223, v231, 1.0
	v_fmac_f32_e32 v228, v232, v228
	v_fmac_f32_e32 v229, v233, v229
	v_fmac_f32_e32 v230, v234, v230
	v_fmac_f32_e32 v231, v235, v231
	v_div_fixup_f32 v228, v228, v220, 1.0
	v_div_fixup_f32 v229, v229, v221, 1.0
	v_div_fixup_f32 v230, v230, v222, 1.0
	v_div_fixup_f32 v231, v231, v223, 1.0
	v_cvt_pk_bf16_f32 v177, v228, v229
	v_cvt_pk_bf16_f32 v176, v230, v231
	v_mul_f32_e32 v220, 0xbfb8aa3b, v156
	v_mul_f32_e32 v221, 0xbfb8aa3b, v157
	v_mul_f32_e32 v222, 0xbfb8aa3b, v154
	v_mul_f32_e32 v223, 0xbfb8aa3b, v155
	v_exp_f32_e32 v220, v220
	v_exp_f32_e32 v221, v221
	v_exp_f32_e32 v222, v222
	v_exp_f32_e32 v223, v223
	v_add_f32_e32 v220, 1.0, v220
	v_add_f32_e32 v221, 1.0, v221
	v_add_f32_e32 v222, 1.0, v222
	v_add_f32_e32 v223, 1.0, v223
	v_rcp_f32_e32 v228, v220
	v_rcp_f32_e32 v229, v221
	v_rcp_f32_e32 v230, v222
	v_rcp_f32_e32 v231, v223
	v_fma_f32 v232, -v220, v228, 1.0
	v_fma_f32 v233, -v221, v229, 1.0
	v_fma_f32 v234, -v222, v230, 1.0
	v_fma_f32 v235, -v223, v231, 1.0
	v_fmac_f32_e32 v228, v232, v228
	v_fmac_f32_e32 v229, v233, v229
	v_fmac_f32_e32 v230, v234, v230
	v_fmac_f32_e32 v231, v235, v231
	v_div_fixup_f32 v228, v228, v220, 1.0
	v_div_fixup_f32 v229, v229, v221, 1.0
	v_div_fixup_f32 v230, v230, v222, 1.0
	v_div_fixup_f32 v231, v231, v223, 1.0
	v_cvt_pk_bf16_f32 v175, v228, v229
	v_cvt_pk_bf16_f32 v174, v230, v231
	v_mul_f32_e32 v220, 0xbfb8aa3b, v152
	v_mul_f32_e32 v221, 0xbfb8aa3b, v153
	v_mul_f32_e32 v222, 0xbfb8aa3b, v150
	v_mul_f32_e32 v223, 0xbfb8aa3b, v151
	v_exp_f32_e32 v220, v220
	v_exp_f32_e32 v221, v221
	v_exp_f32_e32 v222, v222
	v_exp_f32_e32 v223, v223
	v_add_f32_e32 v220, 1.0, v220
	v_add_f32_e32 v221, 1.0, v221
	v_add_f32_e32 v222, 1.0, v222
	v_add_f32_e32 v223, 1.0, v223
	v_rcp_f32_e32 v228, v220
	v_rcp_f32_e32 v229, v221
	v_rcp_f32_e32 v230, v222
	v_rcp_f32_e32 v231, v223
	v_fma_f32 v232, -v220, v228, 1.0
	v_fma_f32 v233, -v221, v229, 1.0
	v_fma_f32 v234, -v222, v230, 1.0
	v_fma_f32 v235, -v223, v231, 1.0
	v_fmac_f32_e32 v228, v232, v228
	v_fmac_f32_e32 v229, v233, v229
	v_fmac_f32_e32 v230, v234, v230
	v_fmac_f32_e32 v231, v235, v231
	v_div_fixup_f32 v228, v228, v220, 1.0
	v_div_fixup_f32 v229, v229, v221, 1.0
	v_div_fixup_f32 v230, v230, v222, 1.0
	v_div_fixup_f32 v231, v231, v223, 1.0
	v_cvt_pk_bf16_f32 v173, v228, v229
	v_cvt_pk_bf16_f32 v172, v230, v231
	v_mul_f32_e32 v220, 0xbfb8aa3b, v148
	v_mul_f32_e32 v221, 0xbfb8aa3b, v149
	v_mul_f32_e32 v222, 0xbfb8aa3b, v146
	v_mul_f32_e32 v223, 0xbfb8aa3b, v147
	v_exp_f32_e32 v220, v220
	v_exp_f32_e32 v221, v221
	v_exp_f32_e32 v222, v222
	v_exp_f32_e32 v223, v223
	v_add_f32_e32 v220, 1.0, v220
	v_add_f32_e32 v221, 1.0, v221
	v_add_f32_e32 v222, 1.0, v222
	v_add_f32_e32 v223, 1.0, v223
	v_rcp_f32_e32 v228, v220
	v_rcp_f32_e32 v229, v221
	v_rcp_f32_e32 v230, v222
	v_rcp_f32_e32 v231, v223
	v_fma_f32 v232, -v220, v228, 1.0
	v_fma_f32 v233, -v221, v229, 1.0
	v_fma_f32 v234, -v222, v230, 1.0
	v_fma_f32 v235, -v223, v231, 1.0
	v_fmac_f32_e32 v228, v232, v228
	v_fmac_f32_e32 v229, v233, v229
	v_fmac_f32_e32 v230, v234, v230
	v_fmac_f32_e32 v231, v235, v231
	v_div_fixup_f32 v228, v228, v220, 1.0
	v_div_fixup_f32 v229, v229, v221, 1.0
	v_div_fixup_f32 v230, v230, v222, 1.0
	v_div_fixup_f32 v231, v231, v223, 1.0
	v_cvt_pk_bf16_f32 v171, v228, v229
	v_cvt_pk_bf16_f32 v170, v230, v231
	v_mul_f32_e32 v220, 0xbfb8aa3b, v144
	v_mul_f32_e32 v221, 0xbfb8aa3b, v145
	v_mul_f32_e32 v222, 0xbfb8aa3b, v142
	v_mul_f32_e32 v223, 0xbfb8aa3b, v143
	v_exp_f32_e32 v220, v220
	v_exp_f32_e32 v221, v221
	v_exp_f32_e32 v222, v222
	v_exp_f32_e32 v223, v223
	v_add_f32_e32 v220, 1.0, v220
	v_add_f32_e32 v221, 1.0, v221
	v_add_f32_e32 v222, 1.0, v222
	v_add_f32_e32 v223, 1.0, v223
	v_rcp_f32_e32 v228, v220
	v_rcp_f32_e32 v229, v221
	v_rcp_f32_e32 v230, v222
	v_rcp_f32_e32 v231, v223
	v_fma_f32 v232, -v220, v228, 1.0
	v_fma_f32 v233, -v221, v229, 1.0
	v_fma_f32 v234, -v222, v230, 1.0
	v_fma_f32 v235, -v223, v231, 1.0
	v_fmac_f32_e32 v228, v232, v228
	v_fmac_f32_e32 v229, v233, v229
	v_fmac_f32_e32 v230, v234, v230
	v_fmac_f32_e32 v231, v235, v231
	v_div_fixup_f32 v228, v228, v220, 1.0
	v_div_fixup_f32 v229, v229, v221, 1.0
	v_div_fixup_f32 v230, v230, v222, 1.0
	v_div_fixup_f32 v231, v231, v223, 1.0
	v_cvt_pk_bf16_f32 v169, v228, v229
	v_cvt_pk_bf16_f32 v168, v230, v231
	v_mul_f32_e32 v220, 0xbfb8aa3b, v140
	v_mul_f32_e32 v221, 0xbfb8aa3b, v141
	v_mul_f32_e32 v222, 0xbfb8aa3b, v138
	v_mul_f32_e32 v223, 0xbfb8aa3b, v139
	v_exp_f32_e32 v220, v220
	v_exp_f32_e32 v221, v221
	v_exp_f32_e32 v222, v222
	v_exp_f32_e32 v223, v223
	v_add_f32_e32 v220, 1.0, v220
	v_add_f32_e32 v221, 1.0, v221
	v_add_f32_e32 v222, 1.0, v222
	v_add_f32_e32 v223, 1.0, v223
	v_rcp_f32_e32 v228, v220
	v_rcp_f32_e32 v229, v221
	v_rcp_f32_e32 v230, v222
	v_rcp_f32_e32 v231, v223
	v_fma_f32 v232, -v220, v228, 1.0
	v_fma_f32 v233, -v221, v229, 1.0
	v_fma_f32 v234, -v222, v230, 1.0
	v_fma_f32 v235, -v223, v231, 1.0
	v_fmac_f32_e32 v228, v232, v228
	v_fmac_f32_e32 v229, v233, v229
	v_fmac_f32_e32 v230, v234, v230
	v_fmac_f32_e32 v231, v235, v231
	v_div_fixup_f32 v228, v228, v220, 1.0
	v_div_fixup_f32 v229, v229, v221, 1.0
	v_div_fixup_f32 v230, v230, v222, 1.0
	v_div_fixup_f32 v231, v231, v223, 1.0
	v_cvt_pk_bf16_f32 v167, v228, v229
	v_cvt_pk_bf16_f32 v166, v230, v231
	v_mul_f32_e32 v220, 0xbfb8aa3b, v136
	v_mul_f32_e32 v221, 0xbfb8aa3b, v137
	v_mul_f32_e32 v222, 0xbfb8aa3b, v134
	v_mul_f32_e32 v223, 0xbfb8aa3b, v135
	v_exp_f32_e32 v220, v220
	v_exp_f32_e32 v221, v221
	v_exp_f32_e32 v222, v222
	v_exp_f32_e32 v223, v223
	v_add_f32_e32 v220, 1.0, v220
	v_add_f32_e32 v221, 1.0, v221
	v_add_f32_e32 v222, 1.0, v222
	v_add_f32_e32 v223, 1.0, v223
	v_rcp_f32_e32 v228, v220
	v_rcp_f32_e32 v229, v221
	v_rcp_f32_e32 v230, v222
	v_rcp_f32_e32 v231, v223
	v_fma_f32 v232, -v220, v228, 1.0
	v_fma_f32 v233, -v221, v229, 1.0
	v_fma_f32 v234, -v222, v230, 1.0
	v_fma_f32 v235, -v223, v231, 1.0
	v_fmac_f32_e32 v228, v232, v228
	v_fmac_f32_e32 v229, v233, v229
	v_fmac_f32_e32 v230, v234, v230
	v_fmac_f32_e32 v231, v235, v231
	v_div_fixup_f32 v228, v228, v220, 1.0
	v_div_fixup_f32 v229, v229, v221, 1.0
	v_div_fixup_f32 v230, v230, v222, 1.0
	v_div_fixup_f32 v231, v231, v223, 1.0
	v_cvt_pk_bf16_f32 v165, v228, v229
	v_cvt_pk_bf16_f32 v164, v230, v231
	v_mul_f32_e32 v220, 0xbfb8aa3b, v132
	v_mul_f32_e32 v221, 0xbfb8aa3b, v133
	v_mul_f32_e32 v222, 0xbfb8aa3b, v130
	v_mul_f32_e32 v223, 0xbfb8aa3b, v131
	v_exp_f32_e32 v220, v220
	v_exp_f32_e32 v221, v221
	v_exp_f32_e32 v222, v222
	v_exp_f32_e32 v223, v223
	v_add_f32_e32 v220, 1.0, v220
	v_add_f32_e32 v221, 1.0, v221
	v_add_f32_e32 v222, 1.0, v222
	v_add_f32_e32 v223, 1.0, v223
	v_rcp_f32_e32 v228, v220
	v_rcp_f32_e32 v229, v221
	v_rcp_f32_e32 v230, v222
	v_rcp_f32_e32 v231, v223
	v_fma_f32 v232, -v220, v228, 1.0
	v_fma_f32 v233, -v221, v229, 1.0
	v_fma_f32 v234, -v222, v230, 1.0
	v_fma_f32 v235, -v223, v231, 1.0
	v_fmac_f32_e32 v228, v232, v228
	v_fmac_f32_e32 v229, v233, v229
	v_fmac_f32_e32 v230, v234, v230
	v_fmac_f32_e32 v231, v235, v231
	v_div_fixup_f32 v228, v228, v220, 1.0
	v_div_fixup_f32 v229, v229, v221, 1.0
	v_div_fixup_f32 v230, v230, v222, 1.0
	v_div_fixup_f32 v231, v231, v223, 1.0
	v_cvt_pk_bf16_f32 v163, v228, v229
	v_cvt_pk_bf16_f32 v162, v230, v231
	v_mul_f32_e32 v220, 0xbfb8aa3b, v128
	v_mul_f32_e32 v221, 0xbfb8aa3b, v129
	v_mul_f32_e32 v222, 0xbfb8aa3b, v126
	v_mul_f32_e32 v223, 0xbfb8aa3b, v127
	v_exp_f32_e32 v220, v220
	v_exp_f32_e32 v221, v221
	v_exp_f32_e32 v222, v222
	v_exp_f32_e32 v223, v223
	v_add_f32_e32 v220, 1.0, v220
	v_add_f32_e32 v221, 1.0, v221
	v_add_f32_e32 v222, 1.0, v222
	v_add_f32_e32 v223, 1.0, v223
	v_rcp_f32_e32 v228, v220
	v_rcp_f32_e32 v229, v221
	v_rcp_f32_e32 v230, v222
	v_rcp_f32_e32 v231, v223
	v_fma_f32 v232, -v220, v228, 1.0
	v_fma_f32 v233, -v221, v229, 1.0
	v_fma_f32 v234, -v222, v230, 1.0
	v_fma_f32 v235, -v223, v231, 1.0
	v_fmac_f32_e32 v228, v232, v228
	v_fmac_f32_e32 v229, v233, v229
	v_fmac_f32_e32 v230, v234, v230
	v_fmac_f32_e32 v231, v235, v231
	v_div_fixup_f32 v228, v228, v220, 1.0
	v_div_fixup_f32 v229, v229, v221, 1.0
	v_div_fixup_f32 v230, v230, v222, 1.0
	v_div_fixup_f32 v231, v231, v223, 1.0
	v_cvt_pk_bf16_f32 v161, v228, v229
	v_cvt_pk_bf16_f32 v160, v230, v231
	v_mul_f32_e32 v220, 0xbfb8aa3b, v124
	v_mul_f32_e32 v221, 0xbfb8aa3b, v125
	v_mul_f32_e32 v222, 0xbfb8aa3b, v122
	v_mul_f32_e32 v223, 0xbfb8aa3b, v123
	v_exp_f32_e32 v220, v220
	v_exp_f32_e32 v221, v221
	v_exp_f32_e32 v222, v222
	v_exp_f32_e32 v223, v223
	v_add_f32_e32 v220, 1.0, v220
	v_add_f32_e32 v221, 1.0, v221
	v_add_f32_e32 v222, 1.0, v222
	v_add_f32_e32 v223, 1.0, v223
	v_rcp_f32_e32 v228, v220
	v_rcp_f32_e32 v229, v221
	v_rcp_f32_e32 v230, v222
	v_rcp_f32_e32 v231, v223
	v_fma_f32 v232, -v220, v228, 1.0
	v_fma_f32 v233, -v221, v229, 1.0
	v_fma_f32 v234, -v222, v230, 1.0
	v_fma_f32 v235, -v223, v231, 1.0
	v_fmac_f32_e32 v228, v232, v228
	v_fmac_f32_e32 v229, v233, v229
	v_fmac_f32_e32 v230, v234, v230
	v_fmac_f32_e32 v231, v235, v231
	v_div_fixup_f32 v228, v228, v220, 1.0
	v_div_fixup_f32 v229, v229, v221, 1.0
	v_div_fixup_f32 v230, v230, v222, 1.0
	v_div_fixup_f32 v231, v231, v223, 1.0
	v_cvt_pk_bf16_f32 v159, v228, v229
	v_cvt_pk_bf16_f32 v158, v230, v231
	v_mul_f32_e32 v220, 0xbfb8aa3b, v120
	v_mul_f32_e32 v221, 0xbfb8aa3b, v121
	v_mul_f32_e32 v222, 0xbfb8aa3b, v118
	v_mul_f32_e32 v223, 0xbfb8aa3b, v119
	v_exp_f32_e32 v220, v220
	v_exp_f32_e32 v221, v221
	v_exp_f32_e32 v222, v222
	v_exp_f32_e32 v223, v223
	v_add_f32_e32 v220, 1.0, v220
	v_add_f32_e32 v221, 1.0, v221
	v_add_f32_e32 v222, 1.0, v222
	v_add_f32_e32 v223, 1.0, v223
	v_rcp_f32_e32 v228, v220
	v_rcp_f32_e32 v229, v221
	v_rcp_f32_e32 v230, v222
	v_rcp_f32_e32 v231, v223
	v_fma_f32 v232, -v220, v228, 1.0
	v_fma_f32 v233, -v221, v229, 1.0
	v_fma_f32 v234, -v222, v230, 1.0
	v_fma_f32 v235, -v223, v231, 1.0
	v_fmac_f32_e32 v228, v232, v228
	v_fmac_f32_e32 v229, v233, v229
	v_fmac_f32_e32 v230, v234, v230
	v_fmac_f32_e32 v231, v235, v231
	v_div_fixup_f32 v228, v228, v220, 1.0
	v_div_fixup_f32 v229, v229, v221, 1.0
	v_div_fixup_f32 v230, v230, v222, 1.0
	v_div_fixup_f32 v231, v231, v223, 1.0
	v_cvt_pk_bf16_f32 v157, v228, v229
	v_cvt_pk_bf16_f32 v156, v230, v231
	v_mul_f32_e32 v220, 0xbfb8aa3b, v116
	v_mul_f32_e32 v221, 0xbfb8aa3b, v117
	v_mul_f32_e32 v222, 0xbfb8aa3b, v114
	v_mul_f32_e32 v223, 0xbfb8aa3b, v115
	v_exp_f32_e32 v220, v220
	v_exp_f32_e32 v221, v221
	v_exp_f32_e32 v222, v222
	v_exp_f32_e32 v223, v223
	v_add_f32_e32 v220, 1.0, v220
	v_add_f32_e32 v221, 1.0, v221
	v_add_f32_e32 v222, 1.0, v222
	v_add_f32_e32 v223, 1.0, v223
	v_rcp_f32_e32 v228, v220
	v_rcp_f32_e32 v229, v221
	v_rcp_f32_e32 v230, v222
	v_rcp_f32_e32 v231, v223
	v_fma_f32 v232, -v220, v228, 1.0
	v_fma_f32 v233, -v221, v229, 1.0
	v_fma_f32 v234, -v222, v230, 1.0
	v_fma_f32 v235, -v223, v231, 1.0
	v_fmac_f32_e32 v228, v232, v228
	v_fmac_f32_e32 v229, v233, v229
	v_fmac_f32_e32 v230, v234, v230
	v_fmac_f32_e32 v231, v235, v231
	v_div_fixup_f32 v228, v228, v220, 1.0
	v_div_fixup_f32 v229, v229, v221, 1.0
	v_div_fixup_f32 v230, v230, v222, 1.0
	v_div_fixup_f32 v231, v231, v223, 1.0
	v_cvt_pk_bf16_f32 v155, v228, v229
	v_cvt_pk_bf16_f32 v154, v230, v231
	v_mul_f32_e32 v220, 0xbfb8aa3b, v112
	v_mul_f32_e32 v221, 0xbfb8aa3b, v113
	v_mul_f32_e32 v222, 0xbfb8aa3b, v110
	v_mul_f32_e32 v223, 0xbfb8aa3b, v111
	v_exp_f32_e32 v220, v220
	v_exp_f32_e32 v221, v221
	v_exp_f32_e32 v222, v222
	v_exp_f32_e32 v223, v223
	v_add_f32_e32 v220, 1.0, v220
	v_add_f32_e32 v221, 1.0, v221
	v_add_f32_e32 v222, 1.0, v222
	v_add_f32_e32 v223, 1.0, v223
	v_rcp_f32_e32 v228, v220
	v_rcp_f32_e32 v229, v221
	v_rcp_f32_e32 v230, v222
	v_rcp_f32_e32 v231, v223
	v_fma_f32 v232, -v220, v228, 1.0
	v_fma_f32 v233, -v221, v229, 1.0
	v_fma_f32 v234, -v222, v230, 1.0
	v_fma_f32 v235, -v223, v231, 1.0
	v_fmac_f32_e32 v228, v232, v228
	v_fmac_f32_e32 v229, v233, v229
	v_fmac_f32_e32 v230, v234, v230
	v_fmac_f32_e32 v231, v235, v231
	v_div_fixup_f32 v228, v228, v220, 1.0
	v_div_fixup_f32 v229, v229, v221, 1.0
	v_div_fixup_f32 v230, v230, v222, 1.0
	v_div_fixup_f32 v231, v231, v223, 1.0
	v_cvt_pk_bf16_f32 v153, v228, v229
	v_cvt_pk_bf16_f32 v152, v230, v231
	v_mul_f32_e32 v220, 0xbfb8aa3b, v108
	v_mul_f32_e32 v221, 0xbfb8aa3b, v109
	v_mul_f32_e32 v222, 0xbfb8aa3b, v106
	v_mul_f32_e32 v223, 0xbfb8aa3b, v107
	v_exp_f32_e32 v220, v220
	v_exp_f32_e32 v221, v221
	v_exp_f32_e32 v222, v222
	v_exp_f32_e32 v223, v223
	v_add_f32_e32 v220, 1.0, v220
	v_add_f32_e32 v221, 1.0, v221
	v_add_f32_e32 v222, 1.0, v222
	v_add_f32_e32 v223, 1.0, v223
	v_rcp_f32_e32 v228, v220
	v_rcp_f32_e32 v229, v221
	v_rcp_f32_e32 v230, v222
	v_rcp_f32_e32 v231, v223
	v_fma_f32 v232, -v220, v228, 1.0
	v_fma_f32 v233, -v221, v229, 1.0
	v_fma_f32 v234, -v222, v230, 1.0
	v_fma_f32 v235, -v223, v231, 1.0
	v_fmac_f32_e32 v228, v232, v228
	v_fmac_f32_e32 v229, v233, v229
	v_fmac_f32_e32 v230, v234, v230
	v_fmac_f32_e32 v231, v235, v231
	v_div_fixup_f32 v228, v228, v220, 1.0
	v_div_fixup_f32 v229, v229, v221, 1.0
	v_div_fixup_f32 v230, v230, v222, 1.0
	v_div_fixup_f32 v231, v231, v223, 1.0
	v_cvt_pk_bf16_f32 v151, v228, v229
	v_cvt_pk_bf16_f32 v150, v230, v231
	v_mul_f32_e32 v220, 0xbfb8aa3b, v104
	v_mul_f32_e32 v221, 0xbfb8aa3b, v105
	v_mul_f32_e32 v222, 0xbfb8aa3b, v102
	v_mul_f32_e32 v223, 0xbfb8aa3b, v103
	v_exp_f32_e32 v220, v220
	v_exp_f32_e32 v221, v221
	v_exp_f32_e32 v222, v222
	v_exp_f32_e32 v223, v223
	v_add_f32_e32 v220, 1.0, v220
	v_add_f32_e32 v221, 1.0, v221
	v_add_f32_e32 v222, 1.0, v222
	v_add_f32_e32 v223, 1.0, v223
	v_rcp_f32_e32 v228, v220
	v_rcp_f32_e32 v229, v221
	v_rcp_f32_e32 v230, v222
	v_rcp_f32_e32 v231, v223
	v_fma_f32 v232, -v220, v228, 1.0
	v_fma_f32 v233, -v221, v229, 1.0
	v_fma_f32 v234, -v222, v230, 1.0
	v_fma_f32 v235, -v223, v231, 1.0
	v_fmac_f32_e32 v228, v232, v228
	v_fmac_f32_e32 v229, v233, v229
	v_fmac_f32_e32 v230, v234, v230
	v_fmac_f32_e32 v231, v235, v231
	v_div_fixup_f32 v228, v228, v220, 1.0
	v_div_fixup_f32 v229, v229, v221, 1.0
	v_div_fixup_f32 v230, v230, v222, 1.0
	v_div_fixup_f32 v231, v231, v223, 1.0
	v_cvt_pk_bf16_f32 v149, v228, v229
	v_cvt_pk_bf16_f32 v148, v230, v231
	v_mul_f32_e32 v220, 0xbfb8aa3b, v100
	v_mul_f32_e32 v221, 0xbfb8aa3b, v101
	v_mul_f32_e32 v222, 0xbfb8aa3b, v98
	v_mul_f32_e32 v223, 0xbfb8aa3b, v99
	v_exp_f32_e32 v220, v220
	v_exp_f32_e32 v221, v221
	v_exp_f32_e32 v222, v222
	v_exp_f32_e32 v223, v223
	v_add_f32_e32 v220, 1.0, v220
	v_add_f32_e32 v221, 1.0, v221
	v_add_f32_e32 v222, 1.0, v222
	v_add_f32_e32 v223, 1.0, v223
	v_rcp_f32_e32 v228, v220
	v_rcp_f32_e32 v229, v221
	v_rcp_f32_e32 v230, v222
	v_rcp_f32_e32 v231, v223
	v_fma_f32 v232, -v220, v228, 1.0
	v_fma_f32 v233, -v221, v229, 1.0
	v_fma_f32 v234, -v222, v230, 1.0
	v_fma_f32 v235, -v223, v231, 1.0
	v_fmac_f32_e32 v228, v232, v228
	v_fmac_f32_e32 v229, v233, v229
	v_fmac_f32_e32 v230, v234, v230
	v_fmac_f32_e32 v231, v235, v231
	v_div_fixup_f32 v228, v228, v220, 1.0
	v_div_fixup_f32 v229, v229, v221, 1.0
	v_div_fixup_f32 v230, v230, v222, 1.0
	v_div_fixup_f32 v231, v231, v223, 1.0
	v_cvt_pk_bf16_f32 v147, v228, v229
	v_cvt_pk_bf16_f32 v146, v230, v231
	v_mul_f32_e32 v220, 0xbfb8aa3b, v96
	v_mul_f32_e32 v221, 0xbfb8aa3b, v97
	v_mul_f32_e32 v222, 0xbfb8aa3b, v94
	v_mul_f32_e32 v223, 0xbfb8aa3b, v95
	v_exp_f32_e32 v220, v220
	v_exp_f32_e32 v221, v221
	v_exp_f32_e32 v222, v222
	v_exp_f32_e32 v223, v223
	v_add_f32_e32 v220, 1.0, v220
	v_add_f32_e32 v221, 1.0, v221
	v_add_f32_e32 v222, 1.0, v222
	v_add_f32_e32 v223, 1.0, v223
	v_rcp_f32_e32 v228, v220
	v_rcp_f32_e32 v229, v221
	v_rcp_f32_e32 v230, v222
	v_rcp_f32_e32 v231, v223
	v_fma_f32 v232, -v220, v228, 1.0
	v_fma_f32 v233, -v221, v229, 1.0
	v_fma_f32 v234, -v222, v230, 1.0
	v_fma_f32 v235, -v223, v231, 1.0
	v_fmac_f32_e32 v228, v232, v228
	v_fmac_f32_e32 v229, v233, v229
	v_fmac_f32_e32 v230, v234, v230
	v_fmac_f32_e32 v231, v235, v231
	v_div_fixup_f32 v228, v228, v220, 1.0
	v_div_fixup_f32 v229, v229, v221, 1.0
	v_div_fixup_f32 v230, v230, v222, 1.0
	v_div_fixup_f32 v231, v231, v223, 1.0
	v_cvt_pk_bf16_f32 v145, v228, v229
	v_cvt_pk_bf16_f32 v144, v230, v231
	v_mul_f32_e32 v220, 0xbfb8aa3b, v92
	v_mul_f32_e32 v221, 0xbfb8aa3b, v93
	v_mul_f32_e32 v222, 0xbfb8aa3b, v90
	v_mul_f32_e32 v223, 0xbfb8aa3b, v91
	v_exp_f32_e32 v220, v220
	v_exp_f32_e32 v221, v221
	v_exp_f32_e32 v222, v222
	v_exp_f32_e32 v223, v223
	v_add_f32_e32 v220, 1.0, v220
	v_add_f32_e32 v221, 1.0, v221
	v_add_f32_e32 v222, 1.0, v222
	v_add_f32_e32 v223, 1.0, v223
	v_rcp_f32_e32 v228, v220
	v_rcp_f32_e32 v229, v221
	v_rcp_f32_e32 v230, v222
	v_rcp_f32_e32 v231, v223
	v_fma_f32 v232, -v220, v228, 1.0
	v_fma_f32 v233, -v221, v229, 1.0
	v_fma_f32 v234, -v222, v230, 1.0
	v_fma_f32 v235, -v223, v231, 1.0
	v_fmac_f32_e32 v228, v232, v228
	v_fmac_f32_e32 v229, v233, v229
	v_fmac_f32_e32 v230, v234, v230
	v_fmac_f32_e32 v231, v235, v231
	v_div_fixup_f32 v228, v228, v220, 1.0
	v_div_fixup_f32 v229, v229, v221, 1.0
	v_div_fixup_f32 v230, v230, v222, 1.0
	v_div_fixup_f32 v231, v231, v223, 1.0
	v_cvt_pk_bf16_f32 v143, v228, v229
	v_cvt_pk_bf16_f32 v142, v230, v231
	v_mul_f32_e32 v220, 0xbfb8aa3b, v88
	v_mul_f32_e32 v221, 0xbfb8aa3b, v89
	v_mul_f32_e32 v222, 0xbfb8aa3b, v86
	v_mul_f32_e32 v223, 0xbfb8aa3b, v87
	v_exp_f32_e32 v220, v220
	v_exp_f32_e32 v221, v221
	v_exp_f32_e32 v222, v222
	v_exp_f32_e32 v223, v223
	v_add_f32_e32 v220, 1.0, v220
	v_add_f32_e32 v221, 1.0, v221
	v_add_f32_e32 v222, 1.0, v222
	v_add_f32_e32 v223, 1.0, v223
	v_rcp_f32_e32 v228, v220
	v_rcp_f32_e32 v229, v221
	v_rcp_f32_e32 v230, v222
	v_rcp_f32_e32 v231, v223
	v_fma_f32 v232, -v220, v228, 1.0
	v_fma_f32 v233, -v221, v229, 1.0
	v_fma_f32 v234, -v222, v230, 1.0
	v_fma_f32 v235, -v223, v231, 1.0
	v_fmac_f32_e32 v228, v232, v228
	v_fmac_f32_e32 v229, v233, v229
	v_fmac_f32_e32 v230, v234, v230
	v_fmac_f32_e32 v231, v235, v231
	v_div_fixup_f32 v228, v228, v220, 1.0
	v_div_fixup_f32 v229, v229, v221, 1.0
	v_div_fixup_f32 v230, v230, v222, 1.0
	v_div_fixup_f32 v231, v231, v223, 1.0
	v_cvt_pk_bf16_f32 v141, v228, v229
	v_cvt_pk_bf16_f32 v140, v230, v231
	v_mul_f32_e32 v220, 0xbfb8aa3b, v84
	v_mul_f32_e32 v221, 0xbfb8aa3b, v85
	v_mul_f32_e32 v222, 0xbfb8aa3b, v82
	v_mul_f32_e32 v223, 0xbfb8aa3b, v83
	v_exp_f32_e32 v220, v220
	v_exp_f32_e32 v221, v221
	v_exp_f32_e32 v222, v222
	v_exp_f32_e32 v223, v223
	v_add_f32_e32 v220, 1.0, v220
	v_add_f32_e32 v221, 1.0, v221
	v_add_f32_e32 v222, 1.0, v222
	v_add_f32_e32 v223, 1.0, v223
	v_rcp_f32_e32 v228, v220
	v_rcp_f32_e32 v229, v221
	v_rcp_f32_e32 v230, v222
	v_rcp_f32_e32 v231, v223
	v_fma_f32 v232, -v220, v228, 1.0
	v_fma_f32 v233, -v221, v229, 1.0
	v_fma_f32 v234, -v222, v230, 1.0
	v_fma_f32 v235, -v223, v231, 1.0
	v_fmac_f32_e32 v228, v232, v228
	v_fmac_f32_e32 v229, v233, v229
	v_fmac_f32_e32 v230, v234, v230
	v_fmac_f32_e32 v231, v235, v231
	v_div_fixup_f32 v228, v228, v220, 1.0
	v_div_fixup_f32 v229, v229, v221, 1.0
	v_div_fixup_f32 v230, v230, v222, 1.0
	v_div_fixup_f32 v231, v231, v223, 1.0
	v_cvt_pk_bf16_f32 v139, v228, v229
	v_cvt_pk_bf16_f32 v138, v230, v231
	v_mul_f32_e32 v220, 0xbfb8aa3b, v80
	v_mul_f32_e32 v221, 0xbfb8aa3b, v81
	v_mul_f32_e32 v222, 0xbfb8aa3b, v78
	v_mul_f32_e32 v223, 0xbfb8aa3b, v79
	v_exp_f32_e32 v220, v220
	v_exp_f32_e32 v221, v221
	v_exp_f32_e32 v222, v222
	v_exp_f32_e32 v223, v223
	v_add_f32_e32 v220, 1.0, v220
	v_add_f32_e32 v221, 1.0, v221
	v_add_f32_e32 v222, 1.0, v222
	v_add_f32_e32 v223, 1.0, v223
	v_rcp_f32_e32 v228, v220
	v_rcp_f32_e32 v229, v221
	v_rcp_f32_e32 v230, v222
	v_rcp_f32_e32 v231, v223
	v_fma_f32 v232, -v220, v228, 1.0
	v_fma_f32 v233, -v221, v229, 1.0
	v_fma_f32 v234, -v222, v230, 1.0
	v_fma_f32 v235, -v223, v231, 1.0
	v_fmac_f32_e32 v228, v232, v228
	v_fmac_f32_e32 v229, v233, v229
	v_fmac_f32_e32 v230, v234, v230
	v_fmac_f32_e32 v231, v235, v231
	v_div_fixup_f32 v228, v228, v220, 1.0
	v_div_fixup_f32 v229, v229, v221, 1.0
	v_div_fixup_f32 v230, v230, v222, 1.0
	v_div_fixup_f32 v231, v231, v223, 1.0
	v_cvt_pk_bf16_f32 v137, v228, v229
	v_cvt_pk_bf16_f32 v136, v230, v231
	v_mul_f32_e32 v220, 0xbfb8aa3b, v76
	v_mul_f32_e32 v221, 0xbfb8aa3b, v77
	v_mul_f32_e32 v222, 0xbfb8aa3b, v74
	v_mul_f32_e32 v223, 0xbfb8aa3b, v75
	v_exp_f32_e32 v220, v220
	v_exp_f32_e32 v221, v221
	v_exp_f32_e32 v222, v222
	v_exp_f32_e32 v223, v223
	v_add_f32_e32 v220, 1.0, v220
	v_add_f32_e32 v221, 1.0, v221
	v_add_f32_e32 v222, 1.0, v222
	v_add_f32_e32 v223, 1.0, v223
	v_rcp_f32_e32 v228, v220
	v_rcp_f32_e32 v229, v221
	v_rcp_f32_e32 v230, v222
	v_rcp_f32_e32 v231, v223
	v_fma_f32 v232, -v220, v228, 1.0
	v_fma_f32 v233, -v221, v229, 1.0
	v_fma_f32 v234, -v222, v230, 1.0
	v_fma_f32 v235, -v223, v231, 1.0
	v_fmac_f32_e32 v228, v232, v228
	v_fmac_f32_e32 v229, v233, v229
	v_fmac_f32_e32 v230, v234, v230
	v_fmac_f32_e32 v231, v235, v231
	v_div_fixup_f32 v228, v228, v220, 1.0
	v_div_fixup_f32 v229, v229, v221, 1.0
	v_div_fixup_f32 v230, v230, v222, 1.0
	v_div_fixup_f32 v231, v231, v223, 1.0
	v_cvt_pk_bf16_f32 v135, v228, v229
	v_cvt_pk_bf16_f32 v134, v230, v231
	v_mul_f32_e32 v220, 0xbfb8aa3b, v72
	v_mul_f32_e32 v221, 0xbfb8aa3b, v73
	v_mul_f32_e32 v222, 0xbfb8aa3b, v70
	v_mul_f32_e32 v223, 0xbfb8aa3b, v71
	v_exp_f32_e32 v220, v220
	v_exp_f32_e32 v221, v221
	v_exp_f32_e32 v222, v222
	v_exp_f32_e32 v223, v223
	v_add_f32_e32 v220, 1.0, v220
	v_add_f32_e32 v221, 1.0, v221
	v_add_f32_e32 v222, 1.0, v222
	v_add_f32_e32 v223, 1.0, v223
	v_rcp_f32_e32 v228, v220
	v_rcp_f32_e32 v229, v221
	v_rcp_f32_e32 v230, v222
	v_rcp_f32_e32 v231, v223
	v_fma_f32 v232, -v220, v228, 1.0
	v_fma_f32 v233, -v221, v229, 1.0
	v_fma_f32 v234, -v222, v230, 1.0
	v_fma_f32 v235, -v223, v231, 1.0
	v_fmac_f32_e32 v228, v232, v228
	v_fmac_f32_e32 v229, v233, v229
	v_fmac_f32_e32 v230, v234, v230
	v_fmac_f32_e32 v231, v235, v231
	v_div_fixup_f32 v228, v228, v220, 1.0
	v_div_fixup_f32 v229, v229, v221, 1.0
	v_div_fixup_f32 v230, v230, v222, 1.0
	v_div_fixup_f32 v231, v231, v223, 1.0
	v_cvt_pk_bf16_f32 v133, v228, v229
	v_cvt_pk_bf16_f32 v132, v230, v231
	v_mul_f32_e32 v220, 0xbfb8aa3b, v68
	v_mul_f32_e32 v221, 0xbfb8aa3b, v69
	v_mul_f32_e32 v222, 0xbfb8aa3b, v66
	v_mul_f32_e32 v223, 0xbfb8aa3b, v67
	v_exp_f32_e32 v220, v220
	v_exp_f32_e32 v221, v221
	v_exp_f32_e32 v222, v222
	v_exp_f32_e32 v223, v223
	v_add_f32_e32 v220, 1.0, v220
	v_add_f32_e32 v221, 1.0, v221
	v_add_f32_e32 v222, 1.0, v222
	v_add_f32_e32 v223, 1.0, v223
	v_rcp_f32_e32 v228, v220
	v_rcp_f32_e32 v229, v221
	v_rcp_f32_e32 v230, v222
	v_rcp_f32_e32 v231, v223
	v_fma_f32 v232, -v220, v228, 1.0
	v_fma_f32 v233, -v221, v229, 1.0
	v_fma_f32 v234, -v222, v230, 1.0
	v_fma_f32 v235, -v223, v231, 1.0
	v_fmac_f32_e32 v228, v232, v228
	v_fmac_f32_e32 v229, v233, v229
	v_fmac_f32_e32 v230, v234, v230
	v_fmac_f32_e32 v231, v235, v231
	v_div_fixup_f32 v228, v228, v220, 1.0
	v_div_fixup_f32 v229, v229, v221, 1.0
	v_div_fixup_f32 v230, v230, v222, 1.0
	v_div_fixup_f32 v231, v231, v223, 1.0
	v_cvt_pk_bf16_f32 v131, v228, v229
	v_cvt_pk_bf16_f32 v130, v230, v231
	v_mul_f32_e32 v220, 0xbfb8aa3b, v64
	v_mul_f32_e32 v221, 0xbfb8aa3b, v65
	v_mul_f32_e32 v222, 0xbfb8aa3b, v62
	v_mul_f32_e32 v223, 0xbfb8aa3b, v63
	v_exp_f32_e32 v220, v220
	v_exp_f32_e32 v221, v221
	v_exp_f32_e32 v222, v222
	v_exp_f32_e32 v223, v223
	v_add_f32_e32 v220, 1.0, v220
	v_add_f32_e32 v221, 1.0, v221
	v_add_f32_e32 v222, 1.0, v222
	v_add_f32_e32 v223, 1.0, v223
	v_rcp_f32_e32 v228, v220
	v_rcp_f32_e32 v229, v221
	v_rcp_f32_e32 v230, v222
	v_rcp_f32_e32 v231, v223
	v_fma_f32 v232, -v220, v228, 1.0
	v_fma_f32 v233, -v221, v229, 1.0
	v_fma_f32 v234, -v222, v230, 1.0
	v_fma_f32 v235, -v223, v231, 1.0
	v_fmac_f32_e32 v228, v232, v228
	v_fmac_f32_e32 v229, v233, v229
	v_fmac_f32_e32 v230, v234, v230
	v_fmac_f32_e32 v231, v235, v231
	v_div_fixup_f32 v228, v228, v220, 1.0
	v_div_fixup_f32 v229, v229, v221, 1.0
	v_div_fixup_f32 v230, v230, v222, 1.0
	v_div_fixup_f32 v231, v231, v223, 1.0
	v_cvt_pk_bf16_f32 v129, v228, v229
	v_cvt_pk_bf16_f32 v128, v230, v231
	v_mul_f32_e32 v220, 0xbfb8aa3b, v60
	v_mul_f32_e32 v221, 0xbfb8aa3b, v61
	v_mul_f32_e32 v222, 0xbfb8aa3b, v58
	v_mul_f32_e32 v223, 0xbfb8aa3b, v59
	v_exp_f32_e32 v220, v220
	v_exp_f32_e32 v221, v221
	v_exp_f32_e32 v222, v222
	v_exp_f32_e32 v223, v223
	v_add_f32_e32 v220, 1.0, v220
	v_add_f32_e32 v221, 1.0, v221
	v_add_f32_e32 v222, 1.0, v222
	v_add_f32_e32 v223, 1.0, v223
	v_rcp_f32_e32 v228, v220
	v_rcp_f32_e32 v229, v221
	v_rcp_f32_e32 v230, v222
	v_rcp_f32_e32 v231, v223
	v_fma_f32 v232, -v220, v228, 1.0
	v_fma_f32 v233, -v221, v229, 1.0
	v_fma_f32 v234, -v222, v230, 1.0
	v_fma_f32 v235, -v223, v231, 1.0
	v_fmac_f32_e32 v228, v232, v228
	v_fmac_f32_e32 v229, v233, v229
	v_fmac_f32_e32 v230, v234, v230
	v_fmac_f32_e32 v231, v235, v231
	v_div_fixup_f32 v228, v228, v220, 1.0
	v_div_fixup_f32 v229, v229, v221, 1.0
	v_div_fixup_f32 v230, v230, v222, 1.0
	v_div_fixup_f32 v231, v231, v223, 1.0
	v_cvt_pk_bf16_f32 v127, v228, v229
	v_cvt_pk_bf16_f32 v126, v230, v231
	v_mul_f32_e32 v220, 0xbfb8aa3b, v56
	v_mul_f32_e32 v221, 0xbfb8aa3b, v57
	v_mul_f32_e32 v222, 0xbfb8aa3b, v54
	v_mul_f32_e32 v223, 0xbfb8aa3b, v55
	v_exp_f32_e32 v220, v220
	v_exp_f32_e32 v221, v221
	v_exp_f32_e32 v222, v222
	v_exp_f32_e32 v223, v223
	v_add_f32_e32 v220, 1.0, v220
	v_add_f32_e32 v221, 1.0, v221
	v_add_f32_e32 v222, 1.0, v222
	v_add_f32_e32 v223, 1.0, v223
	v_rcp_f32_e32 v228, v220
	v_rcp_f32_e32 v229, v221
	v_rcp_f32_e32 v230, v222
	v_rcp_f32_e32 v231, v223
	v_fma_f32 v232, -v220, v228, 1.0
	v_fma_f32 v233, -v221, v229, 1.0
	v_fma_f32 v234, -v222, v230, 1.0
	v_fma_f32 v235, -v223, v231, 1.0
	v_fmac_f32_e32 v228, v232, v228
	v_fmac_f32_e32 v229, v233, v229
	v_fmac_f32_e32 v230, v234, v230
	v_fmac_f32_e32 v231, v235, v231
	v_div_fixup_f32 v228, v228, v220, 1.0
	v_div_fixup_f32 v229, v229, v221, 1.0
	v_div_fixup_f32 v230, v230, v222, 1.0
	v_div_fixup_f32 v231, v231, v223, 1.0
	v_cvt_pk_bf16_f32 v125, v228, v229
	v_cvt_pk_bf16_f32 v124, v230, v231
	v_mul_f32_e32 v220, 0xbfb8aa3b, v52
	v_mul_f32_e32 v221, 0xbfb8aa3b, v53
	v_mul_f32_e32 v222, 0xbfb8aa3b, v50
	v_mul_f32_e32 v223, 0xbfb8aa3b, v51
	v_exp_f32_e32 v220, v220
	v_exp_f32_e32 v221, v221
	v_exp_f32_e32 v222, v222
	v_exp_f32_e32 v223, v223
	v_add_f32_e32 v220, 1.0, v220
	v_add_f32_e32 v221, 1.0, v221
	v_add_f32_e32 v222, 1.0, v222
	v_add_f32_e32 v223, 1.0, v223
	v_rcp_f32_e32 v228, v220
	v_rcp_f32_e32 v229, v221
	v_rcp_f32_e32 v230, v222
	v_rcp_f32_e32 v231, v223
	v_fma_f32 v232, -v220, v228, 1.0
	v_fma_f32 v233, -v221, v229, 1.0
	v_fma_f32 v234, -v222, v230, 1.0
	v_fma_f32 v235, -v223, v231, 1.0
	v_fmac_f32_e32 v228, v232, v228
	v_fmac_f32_e32 v229, v233, v229
	v_fmac_f32_e32 v230, v234, v230
	v_fmac_f32_e32 v231, v235, v231
	v_div_fixup_f32 v228, v228, v220, 1.0
	v_div_fixup_f32 v229, v229, v221, 1.0
	v_div_fixup_f32 v230, v230, v222, 1.0
	v_div_fixup_f32 v231, v231, v223, 1.0
	v_cvt_pk_bf16_f32 v123, v228, v229
	v_cvt_pk_bf16_f32 v122, v230, v231
	v_mul_f32_e32 v220, 0xbfb8aa3b, v48
	v_mul_f32_e32 v221, 0xbfb8aa3b, v49
	v_mul_f32_e32 v222, 0xbfb8aa3b, v46
	v_mul_f32_e32 v223, 0xbfb8aa3b, v47
	v_exp_f32_e32 v220, v220
	v_exp_f32_e32 v221, v221
	v_exp_f32_e32 v222, v222
	v_exp_f32_e32 v223, v223
	v_add_f32_e32 v220, 1.0, v220
	v_add_f32_e32 v221, 1.0, v221
	v_add_f32_e32 v222, 1.0, v222
	v_add_f32_e32 v223, 1.0, v223
	v_rcp_f32_e32 v228, v220
	v_rcp_f32_e32 v229, v221
	v_rcp_f32_e32 v230, v222
	v_rcp_f32_e32 v231, v223
	v_fma_f32 v232, -v220, v228, 1.0
	v_fma_f32 v233, -v221, v229, 1.0
	v_fma_f32 v234, -v222, v230, 1.0
	v_fma_f32 v235, -v223, v231, 1.0
	v_fmac_f32_e32 v228, v232, v228
	v_fmac_f32_e32 v229, v233, v229
	v_fmac_f32_e32 v230, v234, v230
	v_fmac_f32_e32 v231, v235, v231
	v_div_fixup_f32 v228, v228, v220, 1.0
	v_div_fixup_f32 v229, v229, v221, 1.0
	v_div_fixup_f32 v230, v230, v222, 1.0
	v_div_fixup_f32 v231, v231, v223, 1.0
	v_cvt_pk_bf16_f32 v121, v228, v229
	v_cvt_pk_bf16_f32 v120, v230, v231
	v_mul_f32_e32 v220, 0xbfb8aa3b, v44
	v_mul_f32_e32 v221, 0xbfb8aa3b, v45
	v_mul_f32_e32 v222, 0xbfb8aa3b, v42
	v_mul_f32_e32 v223, 0xbfb8aa3b, v43
	v_exp_f32_e32 v220, v220
	v_exp_f32_e32 v221, v221
	v_exp_f32_e32 v222, v222
	v_exp_f32_e32 v223, v223
	v_add_f32_e32 v220, 1.0, v220
	v_add_f32_e32 v221, 1.0, v221
	v_add_f32_e32 v222, 1.0, v222
	v_add_f32_e32 v223, 1.0, v223
	v_rcp_f32_e32 v228, v220
	v_rcp_f32_e32 v229, v221
	v_rcp_f32_e32 v230, v222
	v_rcp_f32_e32 v231, v223
	v_fma_f32 v232, -v220, v228, 1.0
	v_fma_f32 v233, -v221, v229, 1.0
	v_fma_f32 v234, -v222, v230, 1.0
	v_fma_f32 v235, -v223, v231, 1.0
	v_fmac_f32_e32 v228, v232, v228
	v_fmac_f32_e32 v229, v233, v229
	v_fmac_f32_e32 v230, v234, v230
	v_fmac_f32_e32 v231, v235, v231
	v_div_fixup_f32 v228, v228, v220, 1.0
	v_div_fixup_f32 v229, v229, v221, 1.0
	v_div_fixup_f32 v230, v230, v222, 1.0
	v_div_fixup_f32 v231, v231, v223, 1.0
	v_cvt_pk_bf16_f32 v119, v228, v229
	v_cvt_pk_bf16_f32 v118, v230, v231
	v_mul_f32_e32 v220, 0xbfb8aa3b, v40
	v_mul_f32_e32 v221, 0xbfb8aa3b, v41
	v_mul_f32_e32 v222, 0xbfb8aa3b, v38
	v_mul_f32_e32 v223, 0xbfb8aa3b, v39
	v_exp_f32_e32 v220, v220
	v_exp_f32_e32 v221, v221
	v_exp_f32_e32 v222, v222
	v_exp_f32_e32 v223, v223
	v_add_f32_e32 v220, 1.0, v220
	v_add_f32_e32 v221, 1.0, v221
	v_add_f32_e32 v222, 1.0, v222
	v_add_f32_e32 v223, 1.0, v223
	v_rcp_f32_e32 v228, v220
	v_rcp_f32_e32 v229, v221
	v_rcp_f32_e32 v230, v222
	v_rcp_f32_e32 v231, v223
	v_fma_f32 v232, -v220, v228, 1.0
	v_fma_f32 v233, -v221, v229, 1.0
	v_fma_f32 v234, -v222, v230, 1.0
	v_fma_f32 v235, -v223, v231, 1.0
	v_fmac_f32_e32 v228, v232, v228
	v_fmac_f32_e32 v229, v233, v229
	v_fmac_f32_e32 v230, v234, v230
	v_fmac_f32_e32 v231, v235, v231
	v_div_fixup_f32 v228, v228, v220, 1.0
	v_div_fixup_f32 v229, v229, v221, 1.0
	v_div_fixup_f32 v230, v230, v222, 1.0
	v_div_fixup_f32 v231, v231, v223, 1.0
	v_cvt_pk_bf16_f32 v117, v228, v229
	v_cvt_pk_bf16_f32 v116, v230, v231
	v_mul_f32_e32 v220, 0xbfb8aa3b, v36
	v_mul_f32_e32 v221, 0xbfb8aa3b, v37
	v_mul_f32_e32 v222, 0xbfb8aa3b, v34
	v_mul_f32_e32 v223, 0xbfb8aa3b, v35
	v_exp_f32_e32 v220, v220
	v_exp_f32_e32 v221, v221
	v_exp_f32_e32 v222, v222
	v_exp_f32_e32 v223, v223
	v_add_f32_e32 v220, 1.0, v220
	v_add_f32_e32 v221, 1.0, v221
	v_add_f32_e32 v222, 1.0, v222
	v_add_f32_e32 v223, 1.0, v223
	v_rcp_f32_e32 v228, v220
	v_rcp_f32_e32 v229, v221
	v_rcp_f32_e32 v230, v222
	v_rcp_f32_e32 v231, v223
	v_fma_f32 v232, -v220, v228, 1.0
	v_fma_f32 v233, -v221, v229, 1.0
	v_fma_f32 v234, -v222, v230, 1.0
	v_fma_f32 v235, -v223, v231, 1.0
	v_fmac_f32_e32 v228, v232, v228
	v_fmac_f32_e32 v229, v233, v229
	v_fmac_f32_e32 v230, v234, v230
	v_fmac_f32_e32 v231, v235, v231
	v_div_fixup_f32 v228, v228, v220, 1.0
	v_div_fixup_f32 v229, v229, v221, 1.0
	v_div_fixup_f32 v230, v230, v222, 1.0
	v_div_fixup_f32 v231, v231, v223, 1.0
	v_cvt_pk_bf16_f32 v115, v228, v229
	v_cvt_pk_bf16_f32 v114, v230, v231
	v_mul_f32_e32 v220, 0xbfb8aa3b, v32
	v_mul_f32_e32 v221, 0xbfb8aa3b, v33
	v_mul_f32_e32 v222, 0xbfb8aa3b, v30
	v_mul_f32_e32 v223, 0xbfb8aa3b, v31
	v_exp_f32_e32 v220, v220
	v_exp_f32_e32 v221, v221
	v_exp_f32_e32 v222, v222
	v_exp_f32_e32 v223, v223
	v_add_f32_e32 v220, 1.0, v220
	v_add_f32_e32 v221, 1.0, v221
	v_add_f32_e32 v222, 1.0, v222
	v_add_f32_e32 v223, 1.0, v223
	v_rcp_f32_e32 v228, v220
	v_rcp_f32_e32 v229, v221
	v_rcp_f32_e32 v230, v222
	v_rcp_f32_e32 v231, v223
	v_fma_f32 v232, -v220, v228, 1.0
	v_fma_f32 v233, -v221, v229, 1.0
	v_fma_f32 v234, -v222, v230, 1.0
	v_fma_f32 v235, -v223, v231, 1.0
	v_fmac_f32_e32 v228, v232, v228
	v_fmac_f32_e32 v229, v233, v229
	v_fmac_f32_e32 v230, v234, v230
	v_fmac_f32_e32 v231, v235, v231
	v_div_fixup_f32 v228, v228, v220, 1.0
	v_div_fixup_f32 v229, v229, v221, 1.0
	v_div_fixup_f32 v230, v230, v222, 1.0
	v_div_fixup_f32 v231, v231, v223, 1.0
	v_cvt_pk_bf16_f32 v113, v228, v229
	v_cvt_pk_bf16_f32 v112, v230, v231
	v_mul_f32_e32 v220, 0xbfb8aa3b, v28
	v_mul_f32_e32 v221, 0xbfb8aa3b, v29
	v_mul_f32_e32 v222, 0xbfb8aa3b, v26
	v_mul_f32_e32 v223, 0xbfb8aa3b, v27
	v_exp_f32_e32 v220, v220
	v_exp_f32_e32 v221, v221
	v_exp_f32_e32 v222, v222
	v_exp_f32_e32 v223, v223
	v_add_f32_e32 v220, 1.0, v220
	v_add_f32_e32 v221, 1.0, v221
	v_add_f32_e32 v222, 1.0, v222
	v_add_f32_e32 v223, 1.0, v223
	v_rcp_f32_e32 v228, v220
	v_rcp_f32_e32 v229, v221
	v_rcp_f32_e32 v230, v222
	v_rcp_f32_e32 v231, v223
	v_fma_f32 v232, -v220, v228, 1.0
	v_fma_f32 v233, -v221, v229, 1.0
	v_fma_f32 v234, -v222, v230, 1.0
	v_fma_f32 v235, -v223, v231, 1.0
	v_fmac_f32_e32 v228, v232, v228
	v_fmac_f32_e32 v229, v233, v229
	v_fmac_f32_e32 v230, v234, v230
	v_fmac_f32_e32 v231, v235, v231
	v_div_fixup_f32 v228, v228, v220, 1.0
	v_div_fixup_f32 v229, v229, v221, 1.0
	v_div_fixup_f32 v230, v230, v222, 1.0
	v_div_fixup_f32 v231, v231, v223, 1.0
	v_cvt_pk_bf16_f32 v111, v228, v229
	v_cvt_pk_bf16_f32 v110, v230, v231
	v_mul_f32_e32 v220, 0xbfb8aa3b, v24
	v_mul_f32_e32 v221, 0xbfb8aa3b, v25
	v_mul_f32_e32 v222, 0xbfb8aa3b, v22
	v_mul_f32_e32 v223, 0xbfb8aa3b, v23
	v_exp_f32_e32 v220, v220
	v_exp_f32_e32 v221, v221
	v_exp_f32_e32 v222, v222
	v_exp_f32_e32 v223, v223
	v_add_f32_e32 v220, 1.0, v220
	v_add_f32_e32 v221, 1.0, v221
	v_add_f32_e32 v222, 1.0, v222
	v_add_f32_e32 v223, 1.0, v223
	v_rcp_f32_e32 v228, v220
	v_rcp_f32_e32 v229, v221
	v_rcp_f32_e32 v230, v222
	v_rcp_f32_e32 v231, v223
	v_fma_f32 v232, -v220, v228, 1.0
	v_fma_f32 v233, -v221, v229, 1.0
	v_fma_f32 v234, -v222, v230, 1.0
	v_fma_f32 v235, -v223, v231, 1.0
	v_fmac_f32_e32 v228, v232, v228
	v_fmac_f32_e32 v229, v233, v229
	v_fmac_f32_e32 v230, v234, v230
	v_fmac_f32_e32 v231, v235, v231
	v_div_fixup_f32 v228, v228, v220, 1.0
	v_div_fixup_f32 v229, v229, v221, 1.0
	v_div_fixup_f32 v230, v230, v222, 1.0
	v_div_fixup_f32 v231, v231, v223, 1.0
	v_cvt_pk_bf16_f32 v109, v228, v229
	v_cvt_pk_bf16_f32 v108, v230, v231
	v_mul_f32_e32 v220, 0xbfb8aa3b, v20
	v_mul_f32_e32 v221, 0xbfb8aa3b, v21
	v_mul_f32_e32 v222, 0xbfb8aa3b, v18
	v_mul_f32_e32 v223, 0xbfb8aa3b, v19
	v_exp_f32_e32 v220, v220
	v_exp_f32_e32 v221, v221
	v_exp_f32_e32 v222, v222
	v_exp_f32_e32 v223, v223
	v_add_f32_e32 v220, 1.0, v220
	v_add_f32_e32 v221, 1.0, v221
	v_add_f32_e32 v222, 1.0, v222
	v_add_f32_e32 v223, 1.0, v223
	v_rcp_f32_e32 v228, v220
	v_rcp_f32_e32 v229, v221
	v_rcp_f32_e32 v230, v222
	v_rcp_f32_e32 v231, v223
	v_fma_f32 v232, -v220, v228, 1.0
	v_fma_f32 v233, -v221, v229, 1.0
	v_fma_f32 v234, -v222, v230, 1.0
	v_fma_f32 v235, -v223, v231, 1.0
	v_fmac_f32_e32 v228, v232, v228
	v_fmac_f32_e32 v229, v233, v229
	v_fmac_f32_e32 v230, v234, v230
	v_fmac_f32_e32 v231, v235, v231
	v_div_fixup_f32 v228, v228, v220, 1.0
	v_div_fixup_f32 v229, v229, v221, 1.0
	v_div_fixup_f32 v230, v230, v222, 1.0
	v_div_fixup_f32 v231, v231, v223, 1.0
	v_cvt_pk_bf16_f32 v107, v228, v229
	v_cvt_pk_bf16_f32 v106, v230, v231
	v_mul_f32_e32 v220, 0xbfb8aa3b, v16
	v_mul_f32_e32 v221, 0xbfb8aa3b, v17
	v_mul_f32_e32 v222, 0xbfb8aa3b, v14
	v_mul_f32_e32 v223, 0xbfb8aa3b, v15
	v_exp_f32_e32 v220, v220
	v_exp_f32_e32 v221, v221
	v_exp_f32_e32 v222, v222
	v_exp_f32_e32 v223, v223
	v_add_f32_e32 v220, 1.0, v220
	v_add_f32_e32 v221, 1.0, v221
	v_add_f32_e32 v222, 1.0, v222
	v_add_f32_e32 v223, 1.0, v223
	v_rcp_f32_e32 v228, v220
	v_rcp_f32_e32 v229, v221
	v_rcp_f32_e32 v230, v222
	v_rcp_f32_e32 v231, v223
	v_fma_f32 v232, -v220, v228, 1.0
	v_fma_f32 v233, -v221, v229, 1.0
	v_fma_f32 v234, -v222, v230, 1.0
	v_fma_f32 v235, -v223, v231, 1.0
	v_fmac_f32_e32 v228, v232, v228
	v_fmac_f32_e32 v229, v233, v229
	v_fmac_f32_e32 v230, v234, v230
	v_fmac_f32_e32 v231, v235, v231
	v_div_fixup_f32 v228, v228, v220, 1.0
	v_div_fixup_f32 v229, v229, v221, 1.0
	v_div_fixup_f32 v230, v230, v222, 1.0
	v_div_fixup_f32 v231, v231, v223, 1.0
	v_cvt_pk_bf16_f32 v105, v228, v229
	v_cvt_pk_bf16_f32 v104, v230, v231
	v_mul_f32_e32 v220, 0xbfb8aa3b, v12
	v_mul_f32_e32 v221, 0xbfb8aa3b, v13
	v_mul_f32_e32 v222, 0xbfb8aa3b, v10
	v_mul_f32_e32 v223, 0xbfb8aa3b, v11
	v_exp_f32_e32 v220, v220
	v_exp_f32_e32 v221, v221
	v_exp_f32_e32 v222, v222
	v_exp_f32_e32 v223, v223
	v_add_f32_e32 v220, 1.0, v220
	v_add_f32_e32 v221, 1.0, v221
	v_add_f32_e32 v222, 1.0, v222
	v_add_f32_e32 v223, 1.0, v223
	v_rcp_f32_e32 v228, v220
	v_rcp_f32_e32 v229, v221
	v_rcp_f32_e32 v230, v222
	v_rcp_f32_e32 v231, v223
	v_fma_f32 v232, -v220, v228, 1.0
	v_fma_f32 v233, -v221, v229, 1.0
	v_fma_f32 v234, -v222, v230, 1.0
	v_fma_f32 v235, -v223, v231, 1.0
	v_fmac_f32_e32 v228, v232, v228
	v_fmac_f32_e32 v229, v233, v229
	v_fmac_f32_e32 v230, v234, v230
	v_fmac_f32_e32 v231, v235, v231
	v_div_fixup_f32 v228, v228, v220, 1.0
	v_div_fixup_f32 v229, v229, v221, 1.0
	v_div_fixup_f32 v230, v230, v222, 1.0
	v_div_fixup_f32 v231, v231, v223, 1.0
	v_cvt_pk_bf16_f32 v103, v228, v229
	v_cvt_pk_bf16_f32 v102, v230, v231
	v_mul_f32_e32 v220, 0xbfb8aa3b, v8
	v_mul_f32_e32 v221, 0xbfb8aa3b, v9
	v_mul_f32_e32 v222, 0xbfb8aa3b, v6
	v_mul_f32_e32 v223, 0xbfb8aa3b, v7
	v_exp_f32_e32 v220, v220
	v_exp_f32_e32 v221, v221
	v_exp_f32_e32 v222, v222
	v_exp_f32_e32 v223, v223
	v_add_f32_e32 v220, 1.0, v220
	v_add_f32_e32 v221, 1.0, v221
	v_add_f32_e32 v222, 1.0, v222
	v_add_f32_e32 v223, 1.0, v223
	v_rcp_f32_e32 v228, v220
	v_rcp_f32_e32 v229, v221
	v_rcp_f32_e32 v230, v222
	v_rcp_f32_e32 v231, v223
	v_fma_f32 v232, -v220, v228, 1.0
	v_fma_f32 v233, -v221, v229, 1.0
	v_fma_f32 v234, -v222, v230, 1.0
	v_fma_f32 v235, -v223, v231, 1.0
	v_fmac_f32_e32 v228, v232, v228
	v_fmac_f32_e32 v229, v233, v229
	v_fmac_f32_e32 v230, v234, v230
	v_fmac_f32_e32 v231, v235, v231
	v_div_fixup_f32 v228, v228, v220, 1.0
	v_div_fixup_f32 v229, v229, v221, 1.0
	v_div_fixup_f32 v230, v230, v222, 1.0
	v_div_fixup_f32 v231, v231, v223, 1.0
	v_cvt_pk_bf16_f32 v101, v228, v229
	v_cvt_pk_bf16_f32 v100, v230, v231
	v_mul_f32_e32 v220, 0xbfb8aa3b, v4
	v_mul_f32_e32 v221, 0xbfb8aa3b, v5
	v_mul_f32_e32 v222, 0xbfb8aa3b, v2
	v_mul_f32_e32 v223, 0xbfb8aa3b, v3
	v_exp_f32_e32 v220, v220
	v_exp_f32_e32 v221, v221
	v_exp_f32_e32 v222, v222
	v_exp_f32_e32 v223, v223
	v_add_f32_e32 v220, 1.0, v220
	v_add_f32_e32 v221, 1.0, v221
	v_add_f32_e32 v222, 1.0, v222
	v_add_f32_e32 v223, 1.0, v223
	v_rcp_f32_e32 v228, v220
	v_rcp_f32_e32 v229, v221
	v_rcp_f32_e32 v230, v222
	v_rcp_f32_e32 v231, v223
	v_fma_f32 v232, -v220, v228, 1.0
	v_fma_f32 v233, -v221, v229, 1.0
	v_fma_f32 v234, -v222, v230, 1.0
	v_fma_f32 v235, -v223, v231, 1.0
	v_fmac_f32_e32 v228, v232, v228
	v_fmac_f32_e32 v229, v233, v229
	v_fmac_f32_e32 v230, v234, v230
	v_fmac_f32_e32 v231, v235, v231
	v_div_fixup_f32 v228, v228, v220, 1.0
	v_div_fixup_f32 v229, v229, v221, 1.0
	v_div_fixup_f32 v230, v230, v222, 1.0
	v_div_fixup_f32 v231, v231, v223, 1.0
	v_cvt_pk_bf16_f32 v99, v228, v229
	v_cvt_pk_bf16_f32 v98, v230, v231
	v_mov_b32_e32 v2, 0
	v_mov_b32_e32 v3, 0
	v_mov_b32_e32 v4, 0
	v_mov_b32_e32 v5, 0
	v_mov_b32_e32 v6, 0
	v_mov_b32_e32 v7, 0
	v_mov_b32_e32 v8, 0
	v_mov_b32_e32 v9, 0
	v_mov_b32_e32 v10, 0
	v_mov_b32_e32 v11, 0
	v_mov_b32_e32 v12, 0
	v_mov_b32_e32 v13, 0
	v_mov_b32_e32 v14, 0
	v_mov_b32_e32 v15, 0
	v_mov_b32_e32 v16, 0
	v_mov_b32_e32 v17, 0
	v_mov_b32_e32 v18, 0
	v_mov_b32_e32 v19, 0
	v_mov_b32_e32 v20, 0
	v_mov_b32_e32 v21, 0
	v_mov_b32_e32 v22, 0
	v_mov_b32_e32 v23, 0
	v_mov_b32_e32 v24, 0
	v_mov_b32_e32 v25, 0
	v_mov_b32_e32 v26, 0
	v_mov_b32_e32 v27, 0
	v_mov_b32_e32 v28, 0
	v_mov_b32_e32 v29, 0
	v_mov_b32_e32 v30, 0
	v_mov_b32_e32 v31, 0
	v_mov_b32_e32 v32, 0
	v_mov_b32_e32 v33, 0
	v_mov_b32_e32 v34, 0
	v_mov_b32_e32 v35, 0
	v_mov_b32_e32 v36, 0
	v_mov_b32_e32 v37, 0
	v_mov_b32_e32 v38, 0
	v_mov_b32_e32 v39, 0
	v_mov_b32_e32 v40, 0
	v_mov_b32_e32 v41, 0
	v_mov_b32_e32 v42, 0
	v_mov_b32_e32 v43, 0
	v_mov_b32_e32 v44, 0
	v_mov_b32_e32 v45, 0
	v_mov_b32_e32 v46, 0
	v_mov_b32_e32 v47, 0
	v_mov_b32_e32 v48, 0
	v_mov_b32_e32 v49, 0
	v_mov_b32_e32 v50, 0
	v_mov_b32_e32 v51, 0
	v_mov_b32_e32 v52, 0
	v_mov_b32_e32 v53, 0
	v_mov_b32_e32 v54, 0
	v_mov_b32_e32 v55, 0
	v_mov_b32_e32 v56, 0
	v_mov_b32_e32 v57, 0
	v_mov_b32_e32 v58, 0
	v_mov_b32_e32 v59, 0
	v_mov_b32_e32 v60, 0
	v_mov_b32_e32 v61, 0
	v_mov_b32_e32 v62, 0
	v_mov_b32_e32 v63, 0
	v_mov_b32_e32 v64, 0
	v_mov_b32_e32 v65, 0
	s_waitcnt vmcnt(8)
	s_barrier
	v_add_u32_e32 v66, v226, v224
	v_add_u32_e32 v70, v226, v225
	ds_read_b128 v[78:81], v66
	ds_read_b128 v[66:69], v66 offset:4096
	ds_read_b128 v[74:77], v70 offset:32768
	ds_read_b128 v[70:73], v70 offset:36864
	s_waitcnt lgkmcnt(0)
	v_mfma_f32_32x32x16_bf16 v[50:65], v[74:77], v[78:81], v[50:65]
	v_xor_b32_e32 v86, 0x20, v226
	v_add_u32_e32 v82, v86, v224
	v_add_u32_e32 v86, v86, v225
	v_mfma_f32_32x32x16_bf16 v[34:49], v[70:73], v[78:81], v[34:49]
	ds_read_b128 v[78:81], v82
	ds_read_b128 v[82:85], v82 offset:4096
	v_mfma_f32_32x32x16_bf16 v[18:33], v[74:77], v[66:69], v[18:33]
	ds_read_b128 v[74:77], v86 offset:32768
	ds_read_b128 v[86:89], v86 offset:36864
	v_mfma_f32_32x32x16_bf16 v[2:17], v[70:73], v[66:69], v[2:17]
	s_waitcnt lgkmcnt(0)
	v_mfma_f32_32x32x16_bf16 v[50:65], v[74:77], v[78:81], v[50:65]
	v_xor_b32_e32 v70, 0x40, v226
	v_add_u32_e32 v66, v70, v224
	v_add_u32_e32 v70, v70, v225
	v_mfma_f32_32x32x16_bf16 v[34:49], v[86:89], v[78:81], v[34:49]
	ds_read_b128 v[78:81], v66
	ds_read_b128 v[66:69], v66 offset:4096
	v_mfma_f32_32x32x16_bf16 v[18:33], v[74:77], v[82:85], v[18:33]
	ds_read_b128 v[74:77], v70 offset:32768
	ds_read_b128 v[70:73], v70 offset:36864
	v_mfma_f32_32x32x16_bf16 v[2:17], v[86:89], v[82:85], v[2:17]
	s_waitcnt lgkmcnt(0)
	v_mfma_f32_32x32x16_bf16 v[50:65], v[74:77], v[78:81], v[50:65]
	v_xor_b32_e32 v86, 0x60, v226
	v_add_u32_e32 v82, v86, v224
	v_add_u32_e32 v86, v86, v225
	v_mfma_f32_32x32x16_bf16 v[34:49], v[70:73], v[78:81], v[34:49]
	ds_read_b128 v[78:81], v82
	ds_read_b128 v[82:85], v82 offset:4096
	v_mfma_f32_32x32x16_bf16 v[18:33], v[74:77], v[66:69], v[18:33]
	ds_read_b128 v[74:77], v86 offset:32768
	ds_read_b128 v[86:89], v86 offset:36864
	v_mfma_f32_32x32x16_bf16 v[2:17], v[70:73], v[66:69], v[2:17]
	s_waitcnt vmcnt(0) lgkmcnt(0)
	s_barrier
	s_waitcnt lgkmcnt(0)
	s_add_u32 m0, s30, 0x0
	s_nop 0
	global_load_lds_dwordx4 v200, s[98:99]
	s_add_u32 m0, s30, 0x1000
	s_nop 0
	global_load_lds_dwordx4 v201, s[98:99]
	s_add_u32 m0, s30, 0x2000
	s_nop 0
	global_load_lds_dwordx4 v202, s[98:99]
	s_add_u32 m0, s30, 0x3000
	s_nop 0
	global_load_lds_dwordx4 v204, s[98:99]
	s_add_u32 m0, s30, 0x8000
	s_nop 0
	global_load_lds_dwordx4 v200, s[100:101]
	s_add_u32 m0, s30, 0x9000
	s_nop 0
	global_load_lds_dwordx4 v201, s[100:101]
	s_add_u32 m0, s30, 0xa000
	s_nop 0
	global_load_lds_dwordx4 v202, s[100:101]
	s_add_u32 m0, s30, 0xb000
	s_nop 0
	global_load_lds_dwordx4 v204, s[100:101]
	v_mfma_f32_32x32x16_bf16 v[50:65], v[74:77], v[78:81], v[50:65]
	v_mov_b32_e32 v70, v226
	v_add_u32_e32 v66, v70, v224
	v_add_u32_e32 v70, v70, v225
	v_mfma_f32_32x32x16_bf16 v[34:49], v[86:89], v[78:81], v[34:49]
	ds_read_b128 v[78:81], v66 offset:16384
	ds_read_b128 v[66:69], v66 offset:20480
	v_mfma_f32_32x32x16_bf16 v[18:33], v[74:77], v[82:85], v[18:33]
	ds_read_b128 v[74:77], v70 offset:49152
	ds_read_b128 v[70:73], v70 offset:53248
	v_mfma_f32_32x32x16_bf16 v[2:17], v[86:89], v[82:85], v[2:17]
	s_add_u32 s98, s98, 0x80
	s_addc_u32 s99, s99, 0
	s_add_u32 s100, s100, 0x80
	s_addc_u32 s101, s101, 0
	s_waitcnt lgkmcnt(0)
	v_mfma_f32_32x32x16_bf16 v[50:65], v[74:77], v[78:81], v[50:65]
	v_xor_b32_e32 v86, 0x20, v226
	v_add_u32_e32 v82, v86, v224
	v_add_u32_e32 v86, v86, v225
	v_mfma_f32_32x32x16_bf16 v[34:49], v[70:73], v[78:81], v[34:49]
	ds_read_b128 v[78:81], v82 offset:16384
	ds_read_b128 v[82:85], v82 offset:20480
	v_mfma_f32_32x32x16_bf16 v[18:33], v[74:77], v[66:69], v[18:33]
	ds_read_b128 v[74:77], v86 offset:49152
	ds_read_b128 v[86:89], v86 offset:53248
	v_mfma_f32_32x32x16_bf16 v[2:17], v[70:73], v[66:69], v[2:17]
	s_waitcnt lgkmcnt(0)
	v_mfma_f32_32x32x16_bf16 v[50:65], v[74:77], v[78:81], v[50:65]
	v_xor_b32_e32 v70, 0x40, v226
	v_add_u32_e32 v66, v70, v224
	v_add_u32_e32 v70, v70, v225
	v_mfma_f32_32x32x16_bf16 v[34:49], v[86:89], v[78:81], v[34:49]
	ds_read_b128 v[78:81], v66 offset:16384
	ds_read_b128 v[66:69], v66 offset:20480
	v_mfma_f32_32x32x16_bf16 v[18:33], v[74:77], v[82:85], v[18:33]
	ds_read_b128 v[74:77], v70 offset:49152
	ds_read_b128 v[70:73], v70 offset:53248
	v_mfma_f32_32x32x16_bf16 v[2:17], v[86:89], v[82:85], v[2:17]
	s_waitcnt lgkmcnt(0)
	v_mfma_f32_32x32x16_bf16 v[50:65], v[74:77], v[78:81], v[50:65]
	v_xor_b32_e32 v86, 0x60, v226
	v_add_u32_e32 v82, v86, v224
	v_add_u32_e32 v86, v86, v225
	v_mfma_f32_32x32x16_bf16 v[34:49], v[70:73], v[78:81], v[34:49]
	ds_read_b128 v[78:81], v82 offset:16384
	ds_read_b128 v[82:85], v82 offset:20480
	v_mfma_f32_32x32x16_bf16 v[18:33], v[74:77], v[66:69], v[18:33]
	ds_read_b128 v[74:77], v86 offset:49152
	ds_read_b128 v[86:89], v86 offset:53248
	v_mfma_f32_32x32x16_bf16 v[2:17], v[70:73], v[66:69], v[2:17]
	s_waitcnt vmcnt(0) lgkmcnt(0)
	s_barrier
	s_waitcnt lgkmcnt(0)
	s_add_u32 m0, s30, 0x4000
	s_nop 0
	global_load_lds_dwordx4 v200, s[98:99]
	s_add_u32 m0, s30, 0x5000
	s_nop 0
	global_load_lds_dwordx4 v201, s[98:99]
	s_add_u32 m0, s30, 0x6000
	s_nop 0
	global_load_lds_dwordx4 v202, s[98:99]
	s_add_u32 m0, s30, 0x7000
	s_nop 0
	global_load_lds_dwordx4 v204, s[98:99]
	s_add_u32 m0, s30, 0xc000
	s_nop 0
	global_load_lds_dwordx4 v200, s[100:101]
	s_add_u32 m0, s30, 0xd000
	s_nop 0
	global_load_lds_dwordx4 v201, s[100:101]
	s_add_u32 m0, s30, 0xe000
	s_nop 0
	global_load_lds_dwordx4 v202, s[100:101]
	s_add_u32 m0, s30, 0xf000
	s_nop 0
	global_load_lds_dwordx4 v204, s[100:101]
	v_mfma_f32_32x32x16_bf16 v[50:65], v[74:77], v[78:81], v[50:65]
	v_mov_b32_e32 v70, v226
	v_add_u32_e32 v66, v70, v224
	v_add_u32_e32 v70, v70, v225
	v_mfma_f32_32x32x16_bf16 v[34:49], v[86:89], v[78:81], v[34:49]
	ds_read_b128 v[78:81], v66
	ds_read_b128 v[66:69], v66 offset:4096
	v_mfma_f32_32x32x16_bf16 v[18:33], v[74:77], v[82:85], v[18:33]
	ds_read_b128 v[74:77], v70 offset:32768
	ds_read_b128 v[70:73], v70 offset:36864
	v_mfma_f32_32x32x16_bf16 v[2:17], v[86:89], v[82:85], v[2:17]
	s_add_u32 s98, s98, 0x80
	s_addc_u32 s99, s99, 0
	s_add_u32 s100, s100, 0x80
	s_addc_u32 s101, s101, 0
	s_waitcnt lgkmcnt(0)
	v_mfma_f32_32x32x16_bf16 v[50:65], v[74:77], v[78:81], v[50:65]
	v_xor_b32_e32 v86, 0x20, v226
	v_add_u32_e32 v82, v86, v224
	v_add_u32_e32 v86, v86, v225
	v_mfma_f32_32x32x16_bf16 v[34:49], v[70:73], v[78:81], v[34:49]
	ds_read_b128 v[78:81], v82
	ds_read_b128 v[82:85], v82 offset:4096
	v_mfma_f32_32x32x16_bf16 v[18:33], v[74:77], v[66:69], v[18:33]
	ds_read_b128 v[74:77], v86 offset:32768
	ds_read_b128 v[86:89], v86 offset:36864
	v_mfma_f32_32x32x16_bf16 v[2:17], v[70:73], v[66:69], v[2:17]
	s_waitcnt lgkmcnt(0)
	v_mfma_f32_32x32x16_bf16 v[50:65], v[74:77], v[78:81], v[50:65]
	v_xor_b32_e32 v70, 0x40, v226
	v_add_u32_e32 v66, v70, v224
	v_add_u32_e32 v70, v70, v225
	v_mfma_f32_32x32x16_bf16 v[34:49], v[86:89], v[78:81], v[34:49]
	ds_read_b128 v[78:81], v66
	ds_read_b128 v[66:69], v66 offset:4096
	v_mfma_f32_32x32x16_bf16 v[18:33], v[74:77], v[82:85], v[18:33]
	ds_read_b128 v[74:77], v70 offset:32768
	ds_read_b128 v[70:73], v70 offset:36864
	v_mfma_f32_32x32x16_bf16 v[2:17], v[86:89], v[82:85], v[2:17]
	s_waitcnt lgkmcnt(0)
	v_mfma_f32_32x32x16_bf16 v[50:65], v[74:77], v[78:81], v[50:65]
	v_xor_b32_e32 v86, 0x60, v226
	v_add_u32_e32 v82, v86, v224
	v_add_u32_e32 v86, v86, v225
	v_mfma_f32_32x32x16_bf16 v[34:49], v[70:73], v[78:81], v[34:49]
	ds_read_b128 v[78:81], v82
	ds_read_b128 v[82:85], v82 offset:4096
	v_mfma_f32_32x32x16_bf16 v[18:33], v[74:77], v[66:69], v[18:33]
	ds_read_b128 v[74:77], v86 offset:32768
	ds_read_b128 v[86:89], v86 offset:36864
	v_mfma_f32_32x32x16_bf16 v[2:17], v[70:73], v[66:69], v[2:17]
	s_waitcnt vmcnt(0) lgkmcnt(0)
	s_barrier
	s_waitcnt lgkmcnt(0)
	s_add_u32 m0, s30, 0x0
	s_nop 0
	global_load_lds_dwordx4 v200, s[98:99]
	s_add_u32 m0, s30, 0x1000
	s_nop 0
	global_load_lds_dwordx4 v201, s[98:99]
	s_add_u32 m0, s30, 0x2000
	s_nop 0
	global_load_lds_dwordx4 v202, s[98:99]
	s_add_u32 m0, s30, 0x3000
	s_nop 0
	global_load_lds_dwordx4 v204, s[98:99]
	s_add_u32 m0, s30, 0x8000
	s_nop 0
	global_load_lds_dwordx4 v200, s[100:101]
	s_add_u32 m0, s30, 0x9000
	s_nop 0
	global_load_lds_dwordx4 v201, s[100:101]
	s_add_u32 m0, s30, 0xa000
	s_nop 0
	global_load_lds_dwordx4 v202, s[100:101]
	s_add_u32 m0, s30, 0xb000
	s_nop 0
	global_load_lds_dwordx4 v204, s[100:101]
	v_mfma_f32_32x32x16_bf16 v[50:65], v[74:77], v[78:81], v[50:65]
	v_mov_b32_e32 v70, v226
	v_add_u32_e32 v66, v70, v224
	v_add_u32_e32 v70, v70, v225
	v_mfma_f32_32x32x16_bf16 v[34:49], v[86:89], v[78:81], v[34:49]
	ds_read_b128 v[78:81], v66 offset:16384
	ds_read_b128 v[66:69], v66 offset:20480
	v_mfma_f32_32x32x16_bf16 v[18:33], v[74:77], v[82:85], v[18:33]
	ds_read_b128 v[74:77], v70 offset:49152
	ds_read_b128 v[70:73], v70 offset:53248
	v_mfma_f32_32x32x16_bf16 v[2:17], v[86:89], v[82:85], v[2:17]
	s_add_u32 s98, s98, 0x80
	s_addc_u32 s99, s99, 0
	s_add_u32 s100, s100, 0x80
	s_addc_u32 s101, s101, 0
	s_waitcnt lgkmcnt(0)
	v_mfma_f32_32x32x16_bf16 v[50:65], v[74:77], v[78:81], v[50:65]
	v_xor_b32_e32 v86, 0x20, v226
	v_add_u32_e32 v82, v86, v224
	v_add_u32_e32 v86, v86, v225
	v_mfma_f32_32x32x16_bf16 v[34:49], v[70:73], v[78:81], v[34:49]
	ds_read_b128 v[78:81], v82 offset:16384
	ds_read_b128 v[82:85], v82 offset:20480
	v_mfma_f32_32x32x16_bf16 v[18:33], v[74:77], v[66:69], v[18:33]
	ds_read_b128 v[74:77], v86 offset:49152
	ds_read_b128 v[86:89], v86 offset:53248
	v_mfma_f32_32x32x16_bf16 v[2:17], v[70:73], v[66:69], v[2:17]
	s_waitcnt lgkmcnt(0)
	v_mfma_f32_32x32x16_bf16 v[50:65], v[74:77], v[78:81], v[50:65]
	v_xor_b32_e32 v70, 0x40, v226
	v_add_u32_e32 v66, v70, v224
	v_add_u32_e32 v70, v70, v225
	v_mfma_f32_32x32x16_bf16 v[34:49], v[86:89], v[78:81], v[34:49]
	ds_read_b128 v[78:81], v66 offset:16384
	ds_read_b128 v[66:69], v66 offset:20480
	v_mfma_f32_32x32x16_bf16 v[18:33], v[74:77], v[82:85], v[18:33]
	ds_read_b128 v[74:77], v70 offset:49152
	ds_read_b128 v[70:73], v70 offset:53248
	v_mfma_f32_32x32x16_bf16 v[2:17], v[86:89], v[82:85], v[2:17]
	s_waitcnt lgkmcnt(0)
	v_mfma_f32_32x32x16_bf16 v[50:65], v[74:77], v[78:81], v[50:65]
	v_xor_b32_e32 v86, 0x60, v226
	v_add_u32_e32 v82, v86, v224
	v_add_u32_e32 v86, v86, v225
	v_mfma_f32_32x32x16_bf16 v[34:49], v[70:73], v[78:81], v[34:49]
	ds_read_b128 v[78:81], v82 offset:16384
	ds_read_b128 v[82:85], v82 offset:20480
	v_mfma_f32_32x32x16_bf16 v[18:33], v[74:77], v[66:69], v[18:33]
	ds_read_b128 v[74:77], v86 offset:49152
	ds_read_b128 v[86:89], v86 offset:53248
	v_mfma_f32_32x32x16_bf16 v[2:17], v[70:73], v[66:69], v[2:17]
	s_waitcnt vmcnt(0) lgkmcnt(0)
	s_barrier
	s_waitcnt lgkmcnt(0)
	s_add_u32 m0, s30, 0x4000
	s_nop 0
	global_load_lds_dwordx4 v200, s[98:99]
	s_add_u32 m0, s30, 0x5000
	s_nop 0
	global_load_lds_dwordx4 v201, s[98:99]
	s_add_u32 m0, s30, 0x6000
	s_nop 0
	global_load_lds_dwordx4 v202, s[98:99]
	s_add_u32 m0, s30, 0x7000
	s_nop 0
	global_load_lds_dwordx4 v204, s[98:99]
	s_add_u32 m0, s30, 0xc000
	s_nop 0
	global_load_lds_dwordx4 v200, s[100:101]
	s_add_u32 m0, s30, 0xd000
	s_nop 0
	global_load_lds_dwordx4 v201, s[100:101]
	s_add_u32 m0, s30, 0xe000
	s_nop 0
	global_load_lds_dwordx4 v202, s[100:101]
	s_add_u32 m0, s30, 0xf000
	s_nop 0
	global_load_lds_dwordx4 v204, s[100:101]
	v_mfma_f32_32x32x16_bf16 v[50:65], v[74:77], v[78:81], v[50:65]
	v_mov_b32_e32 v70, v226
	v_add_u32_e32 v66, v70, v224
	v_add_u32_e32 v70, v70, v225
	v_mfma_f32_32x32x16_bf16 v[34:49], v[86:89], v[78:81], v[34:49]
	ds_read_b128 v[78:81], v66
	ds_read_b128 v[66:69], v66 offset:4096
	v_mfma_f32_32x32x16_bf16 v[18:33], v[74:77], v[82:85], v[18:33]
	ds_read_b128 v[74:77], v70 offset:32768
	ds_read_b128 v[70:73], v70 offset:36864
	v_mfma_f32_32x32x16_bf16 v[2:17], v[86:89], v[82:85], v[2:17]
	s_add_u32 s98, s98, 0x80
	s_addc_u32 s99, s99, 0
	s_add_u32 s100, s100, 0x80
	s_addc_u32 s101, s101, 0
	s_waitcnt lgkmcnt(0)
	v_mfma_f32_32x32x16_bf16 v[50:65], v[74:77], v[78:81], v[50:65]
	v_xor_b32_e32 v86, 0x20, v226
	v_add_u32_e32 v82, v86, v224
	v_add_u32_e32 v86, v86, v225
	v_mfma_f32_32x32x16_bf16 v[34:49], v[70:73], v[78:81], v[34:49]
	ds_read_b128 v[78:81], v82
	ds_read_b128 v[82:85], v82 offset:4096
	v_mfma_f32_32x32x16_bf16 v[18:33], v[74:77], v[66:69], v[18:33]
	ds_read_b128 v[74:77], v86 offset:32768
	ds_read_b128 v[86:89], v86 offset:36864
	v_mfma_f32_32x32x16_bf16 v[2:17], v[70:73], v[66:69], v[2:17]
	s_waitcnt lgkmcnt(0)
	v_mfma_f32_32x32x16_bf16 v[50:65], v[74:77], v[78:81], v[50:65]
	v_xor_b32_e32 v70, 0x40, v226
	v_add_u32_e32 v66, v70, v224
	v_add_u32_e32 v70, v70, v225
	v_mfma_f32_32x32x16_bf16 v[34:49], v[86:89], v[78:81], v[34:49]
	ds_read_b128 v[78:81], v66
	ds_read_b128 v[66:69], v66 offset:4096
	v_mfma_f32_32x32x16_bf16 v[18:33], v[74:77], v[82:85], v[18:33]
	ds_read_b128 v[74:77], v70 offset:32768
	ds_read_b128 v[70:73], v70 offset:36864
	v_mfma_f32_32x32x16_bf16 v[2:17], v[86:89], v[82:85], v[2:17]
	s_waitcnt lgkmcnt(0)
	v_mfma_f32_32x32x16_bf16 v[50:65], v[74:77], v[78:81], v[50:65]
	v_xor_b32_e32 v86, 0x60, v226
	v_add_u32_e32 v82, v86, v224
	v_add_u32_e32 v86, v86, v225
	v_mfma_f32_32x32x16_bf16 v[34:49], v[70:73], v[78:81], v[34:49]
	ds_read_b128 v[78:81], v82
	ds_read_b128 v[82:85], v82 offset:4096
	v_mfma_f32_32x32x16_bf16 v[18:33], v[74:77], v[66:69], v[18:33]
	ds_read_b128 v[74:77], v86 offset:32768
	ds_read_b128 v[86:89], v86 offset:36864
	v_mfma_f32_32x32x16_bf16 v[2:17], v[70:73], v[66:69], v[2:17]
	s_add_u32 s98, s48, 0x300
	s_addc_u32 s99, s49, 0
	s_add_u32 s100, s44, 0x300
	s_addc_u32 s101, s45, 0
	s_waitcnt vmcnt(0) lgkmcnt(0)
	s_barrier
	s_waitcnt lgkmcnt(0)
	s_add_u32 m0, s30, 0x0
	s_nop 0
	global_load_lds_dwordx4 v200, s[98:99]
	s_add_u32 m0, s30, 0x1000
	s_nop 0
	global_load_lds_dwordx4 v201, s[98:99]
	s_add_u32 m0, s30, 0x2000
	s_nop 0
	global_load_lds_dwordx4 v202, s[98:99]
	s_add_u32 m0, s30, 0x3000
	s_nop 0
	global_load_lds_dwordx4 v204, s[98:99]
	s_add_u32 m0, s30, 0x8000
	s_nop 0
	global_load_lds_dwordx4 v200, s[100:101]
	s_add_u32 m0, s30, 0x9000
	s_nop 0
	global_load_lds_dwordx4 v201, s[100:101]
	s_add_u32 m0, s30, 0xa000
	s_nop 0
	global_load_lds_dwordx4 v202, s[100:101]
	s_add_u32 m0, s30, 0xb000
	s_nop 0
	global_load_lds_dwordx4 v204, s[100:101]
	v_mfma_f32_32x32x16_bf16 v[50:65], v[74:77], v[78:81], v[50:65]
	v_mov_b32_e32 v70, v226
	v_add_u32_e32 v66, v70, v224
	v_add_u32_e32 v70, v70, v225
	v_mfma_f32_32x32x16_bf16 v[34:49], v[86:89], v[78:81], v[34:49]
	ds_read_b128 v[78:81], v66 offset:16384
	ds_read_b128 v[66:69], v66 offset:20480
	v_mfma_f32_32x32x16_bf16 v[18:33], v[74:77], v[82:85], v[18:33]
	ds_read_b128 v[74:77], v70 offset:49152
	ds_read_b128 v[70:73], v70 offset:53248
	v_mfma_f32_32x32x16_bf16 v[2:17], v[86:89], v[82:85], v[2:17]
	s_add_u32 s98, s98, 0x80
	s_addc_u32 s99, s99, 0
	s_add_u32 s100, s100, 0x80
	s_addc_u32 s101, s101, 0
	s_waitcnt lgkmcnt(0)
	v_mfma_f32_32x32x16_bf16 v[50:65], v[74:77], v[78:81], v[50:65]
	v_xor_b32_e32 v86, 0x20, v226
	v_add_u32_e32 v82, v86, v224
	v_add_u32_e32 v86, v86, v225
	v_mfma_f32_32x32x16_bf16 v[34:49], v[70:73], v[78:81], v[34:49]
	ds_read_b128 v[78:81], v82 offset:16384
	ds_read_b128 v[82:85], v82 offset:20480
	v_mfma_f32_32x32x16_bf16 v[18:33], v[74:77], v[66:69], v[18:33]
	ds_read_b128 v[74:77], v86 offset:49152
	ds_read_b128 v[86:89], v86 offset:53248
	v_mfma_f32_32x32x16_bf16 v[2:17], v[70:73], v[66:69], v[2:17]
	s_waitcnt lgkmcnt(0)
	v_mfma_f32_32x32x16_bf16 v[50:65], v[74:77], v[78:81], v[50:65]
	v_xor_b32_e32 v70, 0x40, v226
	v_add_u32_e32 v66, v70, v224
	v_add_u32_e32 v70, v70, v225
	v_mfma_f32_32x32x16_bf16 v[34:49], v[86:89], v[78:81], v[34:49]
	ds_read_b128 v[78:81], v66 offset:16384
	ds_read_b128 v[66:69], v66 offset:20480
	v_mfma_f32_32x32x16_bf16 v[18:33], v[74:77], v[82:85], v[18:33]
	ds_read_b128 v[74:77], v70 offset:49152
	ds_read_b128 v[70:73], v70 offset:53248
	v_mfma_f32_32x32x16_bf16 v[2:17], v[86:89], v[82:85], v[2:17]
	s_waitcnt lgkmcnt(0)
	v_mfma_f32_32x32x16_bf16 v[50:65], v[74:77], v[78:81], v[50:65]
	v_xor_b32_e32 v86, 0x60, v226
	v_add_u32_e32 v82, v86, v224
	v_add_u32_e32 v86, v86, v225
	v_mfma_f32_32x32x16_bf16 v[34:49], v[70:73], v[78:81], v[34:49]
	ds_read_b128 v[78:81], v82 offset:16384
	ds_read_b128 v[82:85], v82 offset:20480
	v_mfma_f32_32x32x16_bf16 v[18:33], v[74:77], v[66:69], v[18:33]
	ds_read_b128 v[74:77], v86 offset:49152
	ds_read_b128 v[86:89], v86 offset:53248
	v_mfma_f32_32x32x16_bf16 v[2:17], v[70:73], v[66:69], v[2:17]
	s_waitcnt vmcnt(0) lgkmcnt(0)
	s_barrier
	s_waitcnt lgkmcnt(0)
	s_add_u32 m0, s30, 0x4000
	s_nop 0
	global_load_lds_dwordx4 v200, s[98:99]
	s_add_u32 m0, s30, 0x5000
	s_nop 0
	global_load_lds_dwordx4 v201, s[98:99]
	s_add_u32 m0, s30, 0x6000
	s_nop 0
	global_load_lds_dwordx4 v202, s[98:99]
	s_add_u32 m0, s30, 0x7000
	s_nop 0
	global_load_lds_dwordx4 v204, s[98:99]
	s_add_u32 m0, s30, 0xc000
	s_nop 0
	global_load_lds_dwordx4 v200, s[100:101]
	s_add_u32 m0, s30, 0xd000
	s_nop 0
	global_load_lds_dwordx4 v201, s[100:101]
	s_add_u32 m0, s30, 0xe000
	s_nop 0
	global_load_lds_dwordx4 v202, s[100:101]
	s_add_u32 m0, s30, 0xf000
	s_nop 0
	global_load_lds_dwordx4 v204, s[100:101]
	v_mfma_f32_32x32x16_bf16 v[50:65], v[74:77], v[78:81], v[50:65]
	v_mov_b32_e32 v70, v226
	v_add_u32_e32 v66, v70, v224
	v_add_u32_e32 v70, v70, v225
	v_mfma_f32_32x32x16_bf16 v[34:49], v[86:89], v[78:81], v[34:49]
	ds_read_b128 v[78:81], v66
	ds_read_b128 v[66:69], v66 offset:4096
	v_mfma_f32_32x32x16_bf16 v[18:33], v[74:77], v[82:85], v[18:33]
	ds_read_b128 v[74:77], v70 offset:32768
	ds_read_b128 v[70:73], v70 offset:36864
	v_mfma_f32_32x32x16_bf16 v[2:17], v[86:89], v[82:85], v[2:17]
	s_add_u32 s98, s98, 0x80
	s_addc_u32 s99, s99, 0
	s_add_u32 s100, s100, 0x80
	s_addc_u32 s101, s101, 0
	s_nop 15
	v_lshlrev_b32_e32 v220, 16, v98
	v_and_b32_e32 v221, 0xffff0000, v98
	v_mul_f32_e32 v227, v2, v220
	v_mul_f32_e32 v228, v3, v221
	v_lshlrev_b32_e32 v220, 16, v99
	v_and_b32_e32 v221, 0xffff0000, v99
	v_mul_f32_e32 v229, v4, v220
	v_mul_f32_e32 v230, v5, v221
	v_lshlrev_b32_e32 v220, 16, v100
	v_and_b32_e32 v221, 0xffff0000, v100
	v_mul_f32_e32 v231, v6, v220
	v_mul_f32_e32 v232, v7, v221
	v_lshlrev_b32_e32 v220, 16, v101
	v_and_b32_e32 v221, 0xffff0000, v101
	v_mul_f32_e32 v233, v8, v220
	v_mul_f32_e32 v234, v9, v221
	v_lshlrev_b32_e32 v220, 16, v102
	v_and_b32_e32 v221, 0xffff0000, v102
	v_mul_f32_e32 v235, v10, v220
	v_mul_f32_e32 v236, v11, v221
	v_lshlrev_b32_e32 v220, 16, v103
	v_and_b32_e32 v221, 0xffff0000, v103
	v_mul_f32_e32 v237, v12, v220
	v_mul_f32_e32 v238, v13, v221
	v_lshlrev_b32_e32 v220, 16, v104
	v_and_b32_e32 v221, 0xffff0000, v104
	v_mul_f32_e32 v239, v14, v220
	v_mul_f32_e32 v240, v15, v221
	v_lshlrev_b32_e32 v220, 16, v105
	v_and_b32_e32 v221, 0xffff0000, v105
	v_mul_f32_e32 v241, v16, v220
	v_mul_f32_e32 v242, v17, v221
	v_lshlrev_b32_e32 v220, 16, v106
	v_and_b32_e32 v221, 0xffff0000, v106
	v_mul_f32_e32 v243, v18, v220
	v_mul_f32_e32 v244, v19, v221
	v_lshlrev_b32_e32 v220, 16, v107
	v_and_b32_e32 v221, 0xffff0000, v107
	v_mul_f32_e32 v245, v20, v220
	v_mul_f32_e32 v246, v21, v221
	v_lshlrev_b32_e32 v220, 16, v108
	v_and_b32_e32 v221, 0xffff0000, v108
	v_mul_f32_e32 v247, v22, v220
	v_mul_f32_e32 v248, v23, v221
	v_lshlrev_b32_e32 v220, 16, v109
	v_and_b32_e32 v221, 0xffff0000, v109
	v_mul_f32_e32 v249, v24, v220
	v_mul_f32_e32 v250, v25, v221
	v_lshlrev_b32_e32 v220, 16, v110
	v_and_b32_e32 v221, 0xffff0000, v110
	v_mul_f32_e32 v251, v26, v220
	v_mul_f32_e32 v90, v27, v221
	v_lshlrev_b32_e32 v220, 16, v111
	v_and_b32_e32 v221, 0xffff0000, v111
	v_mul_f32_e32 v91, v28, v220
	v_mul_f32_e32 v92, v29, v221
	v_lshlrev_b32_e32 v220, 16, v112
	v_and_b32_e32 v221, 0xffff0000, v112
	v_mul_f32_e32 v93, v30, v220
	v_mul_f32_e32 v94, v31, v221
	v_lshlrev_b32_e32 v220, 16, v113
	v_and_b32_e32 v221, 0xffff0000, v113
	v_mul_f32_e32 v95, v32, v220
	v_mul_f32_e32 v96, v33, v221
	v_lshlrev_b32_e32 v220, 16, v114
	v_and_b32_e32 v221, 0xffff0000, v114
	v_mul_f32_e32 v98, v34, v220
	v_mul_f32_e32 v99, v35, v221
	v_lshlrev_b32_e32 v220, 16, v115
	v_and_b32_e32 v221, 0xffff0000, v115
	v_mul_f32_e32 v100, v36, v220
	v_mul_f32_e32 v101, v37, v221
	v_lshlrev_b32_e32 v220, 16, v116
	v_and_b32_e32 v221, 0xffff0000, v116
	v_mul_f32_e32 v102, v38, v220
	v_mul_f32_e32 v103, v39, v221
	v_lshlrev_b32_e32 v220, 16, v117
	v_and_b32_e32 v221, 0xffff0000, v117
	v_mul_f32_e32 v104, v40, v220
	v_mul_f32_e32 v105, v41, v221
	v_lshlrev_b32_e32 v220, 16, v118
	v_and_b32_e32 v221, 0xffff0000, v118
	v_mul_f32_e32 v106, v42, v220
	v_mul_f32_e32 v107, v43, v221
	v_lshlrev_b32_e32 v220, 16, v119
	v_and_b32_e32 v221, 0xffff0000, v119
	v_mul_f32_e32 v108, v44, v220
	v_mul_f32_e32 v109, v45, v221
	v_lshlrev_b32_e32 v220, 16, v120
	v_and_b32_e32 v221, 0xffff0000, v120
	v_mul_f32_e32 v110, v46, v220
	v_mul_f32_e32 v111, v47, v221
	v_lshlrev_b32_e32 v220, 16, v121
	v_and_b32_e32 v221, 0xffff0000, v121
	v_mul_f32_e32 v112, v48, v220
	v_mul_f32_e32 v113, v49, v221
	v_lshlrev_b32_e32 v220, 16, v122
	v_and_b32_e32 v221, 0xffff0000, v122
	v_mul_f32_e32 v114, v50, v220
	v_mul_f32_e32 v115, v51, v221
	v_lshlrev_b32_e32 v220, 16, v123
	v_and_b32_e32 v221, 0xffff0000, v123
	v_mul_f32_e32 v116, v52, v220
	v_mul_f32_e32 v117, v53, v221
	v_lshlrev_b32_e32 v220, 16, v124
	v_and_b32_e32 v221, 0xffff0000, v124
	v_mul_f32_e32 v118, v54, v220
	v_mul_f32_e32 v119, v55, v221
	v_lshlrev_b32_e32 v220, 16, v125
	v_and_b32_e32 v221, 0xffff0000, v125
	v_mul_f32_e32 v120, v56, v220
	v_mul_f32_e32 v121, v57, v221
	v_lshlrev_b32_e32 v220, 16, v126
	v_and_b32_e32 v221, 0xffff0000, v126
	v_mul_f32_e32 v122, v58, v220
	v_mul_f32_e32 v123, v59, v221
	v_lshlrev_b32_e32 v220, 16, v127
	v_and_b32_e32 v221, 0xffff0000, v127
	v_mul_f32_e32 v124, v60, v220
	v_mul_f32_e32 v125, v61, v221
	v_lshlrev_b32_e32 v220, 16, v128
	v_and_b32_e32 v221, 0xffff0000, v128
	v_mul_f32_e32 v126, v62, v220
	v_mul_f32_e32 v127, v63, v221
	v_lshlrev_b32_e32 v220, 16, v129
	v_and_b32_e32 v221, 0xffff0000, v129
	v_mul_f32_e32 v128, v64, v220
	v_mul_f32_e32 v129, v65, v221
	v_mov_b32_e32 v2, 0
	v_mov_b32_e32 v3, 0
	v_mov_b32_e32 v4, 0
	v_mov_b32_e32 v5, 0
	v_mov_b32_e32 v6, 0
	v_mov_b32_e32 v7, 0
	v_mov_b32_e32 v8, 0
	v_mov_b32_e32 v9, 0
	v_mov_b32_e32 v10, 0
	v_mov_b32_e32 v11, 0
	v_mov_b32_e32 v12, 0
	v_mov_b32_e32 v13, 0
	v_mov_b32_e32 v14, 0
	v_mov_b32_e32 v15, 0
	v_mov_b32_e32 v16, 0
	v_mov_b32_e32 v17, 0
	v_mov_b32_e32 v18, 0
	v_mov_b32_e32 v19, 0
	v_mov_b32_e32 v20, 0
	v_mov_b32_e32 v21, 0
	v_mov_b32_e32 v22, 0
	v_mov_b32_e32 v23, 0
	v_mov_b32_e32 v24, 0
	v_mov_b32_e32 v25, 0
	v_mov_b32_e32 v26, 0
	v_mov_b32_e32 v27, 0
	v_mov_b32_e32 v28, 0
	v_mov_b32_e32 v29, 0
	v_mov_b32_e32 v30, 0
	v_mov_b32_e32 v31, 0
	v_mov_b32_e32 v32, 0
	v_mov_b32_e32 v33, 0
	v_mov_b32_e32 v34, 0
	v_mov_b32_e32 v35, 0
	v_mov_b32_e32 v36, 0
	v_mov_b32_e32 v37, 0
	v_mov_b32_e32 v38, 0
	v_mov_b32_e32 v39, 0
	v_mov_b32_e32 v40, 0
	v_mov_b32_e32 v41, 0
	v_mov_b32_e32 v42, 0
	v_mov_b32_e32 v43, 0
	v_mov_b32_e32 v44, 0
	v_mov_b32_e32 v45, 0
	v_mov_b32_e32 v46, 0
	v_mov_b32_e32 v47, 0
	v_mov_b32_e32 v48, 0
	v_mov_b32_e32 v49, 0
	v_mov_b32_e32 v50, 0
	v_mov_b32_e32 v51, 0
	v_mov_b32_e32 v52, 0
	v_mov_b32_e32 v53, 0
	v_mov_b32_e32 v54, 0
	v_mov_b32_e32 v55, 0
	v_mov_b32_e32 v56, 0
	v_mov_b32_e32 v57, 0
	v_mov_b32_e32 v58, 0
	v_mov_b32_e32 v59, 0
	v_mov_b32_e32 v60, 0
	v_mov_b32_e32 v61, 0
	v_mov_b32_e32 v62, 0
	v_mov_b32_e32 v63, 0
	v_mov_b32_e32 v64, 0
	v_mov_b32_e32 v65, 0
	s_nop 4
	s_waitcnt lgkmcnt(0)
	v_mfma_f32_32x32x16_bf16 v[50:65], v[74:77], v[78:81], v[50:65]
	v_xor_b32_e32 v86, 0x20, v226
	v_add_u32_e32 v82, v86, v224
	v_add_u32_e32 v86, v86, v225
	v_mfma_f32_32x32x16_bf16 v[34:49], v[70:73], v[78:81], v[34:49]
	ds_read_b128 v[78:81], v82
	ds_read_b128 v[82:85], v82 offset:4096
	v_mfma_f32_32x32x16_bf16 v[18:33], v[74:77], v[66:69], v[18:33]
	ds_read_b128 v[74:77], v86 offset:32768
	ds_read_b128 v[86:89], v86 offset:36864
	v_mfma_f32_32x32x16_bf16 v[2:17], v[70:73], v[66:69], v[2:17]
	s_waitcnt lgkmcnt(0)
	v_mfma_f32_32x32x16_bf16 v[50:65], v[74:77], v[78:81], v[50:65]
	v_xor_b32_e32 v70, 0x40, v226
	v_add_u32_e32 v66, v70, v224
	v_add_u32_e32 v70, v70, v225
	v_mfma_f32_32x32x16_bf16 v[34:49], v[86:89], v[78:81], v[34:49]
	ds_read_b128 v[78:81], v66
	ds_read_b128 v[66:69], v66 offset:4096
	v_mfma_f32_32x32x16_bf16 v[18:33], v[74:77], v[82:85], v[18:33]
	ds_read_b128 v[74:77], v70 offset:32768
	ds_read_b128 v[70:73], v70 offset:36864
	v_mfma_f32_32x32x16_bf16 v[2:17], v[86:89], v[82:85], v[2:17]
	s_waitcnt lgkmcnt(0)
	v_mfma_f32_32x32x16_bf16 v[50:65], v[74:77], v[78:81], v[50:65]
	v_xor_b32_e32 v86, 0x60, v226
	v_add_u32_e32 v82, v86, v224
	v_add_u32_e32 v86, v86, v225
	v_mfma_f32_32x32x16_bf16 v[34:49], v[70:73], v[78:81], v[34:49]
	ds_read_b128 v[78:81], v82
	ds_read_b128 v[82:85], v82 offset:4096
	v_mfma_f32_32x32x16_bf16 v[18:33], v[74:77], v[66:69], v[18:33]
	ds_read_b128 v[74:77], v86 offset:32768
	ds_read_b128 v[86:89], v86 offset:36864
	v_mfma_f32_32x32x16_bf16 v[2:17], v[70:73], v[66:69], v[2:17]
	s_waitcnt vmcnt(0) lgkmcnt(0)
	s_barrier
	s_waitcnt lgkmcnt(0)
	s_add_u32 m0, s30, 0x0
	s_nop 0
	global_load_lds_dwordx4 v200, s[98:99]
	s_add_u32 m0, s30, 0x1000
	s_nop 0
	global_load_lds_dwordx4 v201, s[98:99]
	s_add_u32 m0, s30, 0x2000
	s_nop 0
	global_load_lds_dwordx4 v202, s[98:99]
	s_add_u32 m0, s30, 0x3000
	s_nop 0
	global_load_lds_dwordx4 v204, s[98:99]
	s_add_u32 m0, s30, 0x8000
	s_nop 0
	global_load_lds_dwordx4 v200, s[100:101]
	s_add_u32 m0, s30, 0x9000
	s_nop 0
	global_load_lds_dwordx4 v201, s[100:101]
	s_add_u32 m0, s30, 0xa000
	s_nop 0
	global_load_lds_dwordx4 v202, s[100:101]
	s_add_u32 m0, s30, 0xb000
	s_nop 0
	global_load_lds_dwordx4 v204, s[100:101]
	v_mfma_f32_32x32x16_bf16 v[50:65], v[74:77], v[78:81], v[50:65]
	v_mov_b32_e32 v70, v226
	v_add_u32_e32 v66, v70, v224
	v_add_u32_e32 v70, v70, v225
	v_mfma_f32_32x32x16_bf16 v[34:49], v[86:89], v[78:81], v[34:49]
	ds_read_b128 v[78:81], v66 offset:16384
	ds_read_b128 v[66:69], v66 offset:20480
	v_mfma_f32_32x32x16_bf16 v[18:33], v[74:77], v[82:85], v[18:33]
	ds_read_b128 v[74:77], v70 offset:49152
	ds_read_b128 v[70:73], v70 offset:53248
	v_mfma_f32_32x32x16_bf16 v[2:17], v[86:89], v[82:85], v[2:17]
	s_add_u32 s98, s98, 0x80
	s_addc_u32 s99, s99, 0
	s_add_u32 s100, s100, 0x80
	s_addc_u32 s101, s101, 0
	s_waitcnt lgkmcnt(0)
	v_mfma_f32_32x32x16_bf16 v[50:65], v[74:77], v[78:81], v[50:65]
	v_xor_b32_e32 v86, 0x20, v226
	v_add_u32_e32 v82, v86, v224
	v_add_u32_e32 v86, v86, v225
	v_mfma_f32_32x32x16_bf16 v[34:49], v[70:73], v[78:81], v[34:49]
	ds_read_b128 v[78:81], v82 offset:16384
	ds_read_b128 v[82:85], v82 offset:20480
	v_mfma_f32_32x32x16_bf16 v[18:33], v[74:77], v[66:69], v[18:33]
	ds_read_b128 v[74:77], v86 offset:49152
	ds_read_b128 v[86:89], v86 offset:53248
	v_mfma_f32_32x32x16_bf16 v[2:17], v[70:73], v[66:69], v[2:17]
	s_waitcnt lgkmcnt(0)
	v_mfma_f32_32x32x16_bf16 v[50:65], v[74:77], v[78:81], v[50:65]
	v_xor_b32_e32 v70, 0x40, v226
	v_add_u32_e32 v66, v70, v224
	v_add_u32_e32 v70, v70, v225
	v_mfma_f32_32x32x16_bf16 v[34:49], v[86:89], v[78:81], v[34:49]
	ds_read_b128 v[78:81], v66 offset:16384
	ds_read_b128 v[66:69], v66 offset:20480
	v_mfma_f32_32x32x16_bf16 v[18:33], v[74:77], v[82:85], v[18:33]
	ds_read_b128 v[74:77], v70 offset:49152
	ds_read_b128 v[70:73], v70 offset:53248
	v_mfma_f32_32x32x16_bf16 v[2:17], v[86:89], v[82:85], v[2:17]
	s_waitcnt lgkmcnt(0)
	v_mfma_f32_32x32x16_bf16 v[50:65], v[74:77], v[78:81], v[50:65]
	v_xor_b32_e32 v86, 0x60, v226
	v_add_u32_e32 v82, v86, v224
	v_add_u32_e32 v86, v86, v225
	v_mfma_f32_32x32x16_bf16 v[34:49], v[70:73], v[78:81], v[34:49]
	ds_read_b128 v[78:81], v82 offset:16384
	ds_read_b128 v[82:85], v82 offset:20480
	v_mfma_f32_32x32x16_bf16 v[18:33], v[74:77], v[66:69], v[18:33]
	ds_read_b128 v[74:77], v86 offset:49152
	ds_read_b128 v[86:89], v86 offset:53248
	v_mfma_f32_32x32x16_bf16 v[2:17], v[70:73], v[66:69], v[2:17]
	s_waitcnt vmcnt(0) lgkmcnt(0)
	s_barrier
	s_waitcnt lgkmcnt(0)
	s_add_u32 m0, s30, 0x4000
	s_nop 0
	global_load_lds_dwordx4 v200, s[98:99]
	s_add_u32 m0, s30, 0x5000
	s_nop 0
	global_load_lds_dwordx4 v201, s[98:99]
	s_add_u32 m0, s30, 0x6000
	s_nop 0
	global_load_lds_dwordx4 v202, s[98:99]
	s_add_u32 m0, s30, 0x7000
	s_nop 0
	global_load_lds_dwordx4 v204, s[98:99]
	s_add_u32 m0, s30, 0xc000
	s_nop 0
	global_load_lds_dwordx4 v200, s[100:101]
	s_add_u32 m0, s30, 0xd000
	s_nop 0
	global_load_lds_dwordx4 v201, s[100:101]
	s_add_u32 m0, s30, 0xe000
	s_nop 0
	global_load_lds_dwordx4 v202, s[100:101]
	s_add_u32 m0, s30, 0xf000
	s_nop 0
	global_load_lds_dwordx4 v204, s[100:101]
	v_mfma_f32_32x32x16_bf16 v[50:65], v[74:77], v[78:81], v[50:65]
	v_mov_b32_e32 v70, v226
	v_add_u32_e32 v66, v70, v224
	v_add_u32_e32 v70, v70, v225
	v_mfma_f32_32x32x16_bf16 v[34:49], v[86:89], v[78:81], v[34:49]
	ds_read_b128 v[78:81], v66
	ds_read_b128 v[66:69], v66 offset:4096
	v_mfma_f32_32x32x16_bf16 v[18:33], v[74:77], v[82:85], v[18:33]
	ds_read_b128 v[74:77], v70 offset:32768
	ds_read_b128 v[70:73], v70 offset:36864
	v_mfma_f32_32x32x16_bf16 v[2:17], v[86:89], v[82:85], v[2:17]
	s_add_u32 s98, s98, 0x80
	s_addc_u32 s99, s99, 0
	s_add_u32 s100, s100, 0x80
	s_addc_u32 s101, s101, 0
	s_waitcnt lgkmcnt(0)
	v_mfma_f32_32x32x16_bf16 v[50:65], v[74:77], v[78:81], v[50:65]
	v_xor_b32_e32 v86, 0x20, v226
	v_add_u32_e32 v82, v86, v224
	v_add_u32_e32 v86, v86, v225
	v_mfma_f32_32x32x16_bf16 v[34:49], v[70:73], v[78:81], v[34:49]
	ds_read_b128 v[78:81], v82
	ds_read_b128 v[82:85], v82 offset:4096
	v_mfma_f32_32x32x16_bf16 v[18:33], v[74:77], v[66:69], v[18:33]
	ds_read_b128 v[74:77], v86 offset:32768
	ds_read_b128 v[86:89], v86 offset:36864
	v_mfma_f32_32x32x16_bf16 v[2:17], v[70:73], v[66:69], v[2:17]
	s_waitcnt lgkmcnt(0)
	v_mfma_f32_32x32x16_bf16 v[50:65], v[74:77], v[78:81], v[50:65]
	v_xor_b32_e32 v70, 0x40, v226
	v_add_u32_e32 v66, v70, v224
	v_add_u32_e32 v70, v70, v225
	v_mfma_f32_32x32x16_bf16 v[34:49], v[86:89], v[78:81], v[34:49]
	ds_read_b128 v[78:81], v66
	ds_read_b128 v[66:69], v66 offset:4096
	v_mfma_f32_32x32x16_bf16 v[18:33], v[74:77], v[82:85], v[18:33]
	ds_read_b128 v[74:77], v70 offset:32768
	ds_read_b128 v[70:73], v70 offset:36864
	v_mfma_f32_32x32x16_bf16 v[2:17], v[86:89], v[82:85], v[2:17]
	s_waitcnt lgkmcnt(0)
	v_mfma_f32_32x32x16_bf16 v[50:65], v[74:77], v[78:81], v[50:65]
	v_xor_b32_e32 v86, 0x60, v226
	v_add_u32_e32 v82, v86, v224
	v_add_u32_e32 v86, v86, v225
	v_mfma_f32_32x32x16_bf16 v[34:49], v[70:73], v[78:81], v[34:49]
	ds_read_b128 v[78:81], v82
	ds_read_b128 v[82:85], v82 offset:4096
	v_mfma_f32_32x32x16_bf16 v[18:33], v[74:77], v[66:69], v[18:33]
	ds_read_b128 v[74:77], v86 offset:32768
	ds_read_b128 v[86:89], v86 offset:36864
	v_mfma_f32_32x32x16_bf16 v[2:17], v[70:73], v[66:69], v[2:17]
	s_add_u32 s98, s48, 0x500
	s_addc_u32 s99, s49, 0
	s_add_u32 s100, s44, 0x500
	s_addc_u32 s101, s45, 0
	s_waitcnt vmcnt(0) lgkmcnt(0)
	s_barrier
	s_waitcnt lgkmcnt(0)
	s_add_u32 m0, s30, 0x0
	s_nop 0
	global_load_lds_dwordx4 v200, s[98:99]
	s_add_u32 m0, s30, 0x1000
	s_nop 0
	global_load_lds_dwordx4 v201, s[98:99]
	s_add_u32 m0, s30, 0x2000
	s_nop 0
	global_load_lds_dwordx4 v202, s[98:99]
	s_add_u32 m0, s30, 0x3000
	s_nop 0
	global_load_lds_dwordx4 v204, s[98:99]
	s_add_u32 m0, s30, 0x8000
	s_nop 0
	global_load_lds_dwordx4 v200, s[100:101]
	s_add_u32 m0, s30, 0x9000
	s_nop 0
	global_load_lds_dwordx4 v201, s[100:101]
	s_add_u32 m0, s30, 0xa000
	s_nop 0
	global_load_lds_dwordx4 v202, s[100:101]
	s_add_u32 m0, s30, 0xb000
	s_nop 0
	global_load_lds_dwordx4 v204, s[100:101]
	v_mfma_f32_32x32x16_bf16 v[50:65], v[74:77], v[78:81], v[50:65]
	v_mov_b32_e32 v70, v226
	v_add_u32_e32 v66, v70, v224
	v_add_u32_e32 v70, v70, v225
	v_mfma_f32_32x32x16_bf16 v[34:49], v[86:89], v[78:81], v[34:49]
	ds_read_b128 v[78:81], v66 offset:16384
	ds_read_b128 v[66:69], v66 offset:20480
	v_mfma_f32_32x32x16_bf16 v[18:33], v[74:77], v[82:85], v[18:33]
	ds_read_b128 v[74:77], v70 offset:49152
	ds_read_b128 v[70:73], v70 offset:53248
	v_mfma_f32_32x32x16_bf16 v[2:17], v[86:89], v[82:85], v[2:17]
	s_add_u32 s98, s98, 0x80
	s_addc_u32 s99, s99, 0
	s_add_u32 s100, s100, 0x80
	s_addc_u32 s101, s101, 0
	s_waitcnt lgkmcnt(0)
	v_mfma_f32_32x32x16_bf16 v[50:65], v[74:77], v[78:81], v[50:65]
	v_xor_b32_e32 v86, 0x20, v226
	v_add_u32_e32 v82, v86, v224
	v_add_u32_e32 v86, v86, v225
	v_mfma_f32_32x32x16_bf16 v[34:49], v[70:73], v[78:81], v[34:49]
	ds_read_b128 v[78:81], v82 offset:16384
	ds_read_b128 v[82:85], v82 offset:20480
	v_mfma_f32_32x32x16_bf16 v[18:33], v[74:77], v[66:69], v[18:33]
	ds_read_b128 v[74:77], v86 offset:49152
	ds_read_b128 v[86:89], v86 offset:53248
	v_mfma_f32_32x32x16_bf16 v[2:17], v[70:73], v[66:69], v[2:17]
	s_waitcnt lgkmcnt(0)
	v_mfma_f32_32x32x16_bf16 v[50:65], v[74:77], v[78:81], v[50:65]
	v_xor_b32_e32 v70, 0x40, v226
	v_add_u32_e32 v66, v70, v224
	v_add_u32_e32 v70, v70, v225
	v_mfma_f32_32x32x16_bf16 v[34:49], v[86:89], v[78:81], v[34:49]
	ds_read_b128 v[78:81], v66 offset:16384
	ds_read_b128 v[66:69], v66 offset:20480
	v_mfma_f32_32x32x16_bf16 v[18:33], v[74:77], v[82:85], v[18:33]
	ds_read_b128 v[74:77], v70 offset:49152
	ds_read_b128 v[70:73], v70 offset:53248
	v_mfma_f32_32x32x16_bf16 v[2:17], v[86:89], v[82:85], v[2:17]
	s_waitcnt lgkmcnt(0)
	v_mfma_f32_32x32x16_bf16 v[50:65], v[74:77], v[78:81], v[50:65]
	v_xor_b32_e32 v86, 0x60, v226
	v_add_u32_e32 v82, v86, v224
	v_add_u32_e32 v86, v86, v225
	v_mfma_f32_32x32x16_bf16 v[34:49], v[70:73], v[78:81], v[34:49]
	ds_read_b128 v[78:81], v82 offset:16384
	ds_read_b128 v[82:85], v82 offset:20480
	v_mfma_f32_32x32x16_bf16 v[18:33], v[74:77], v[66:69], v[18:33]
	ds_read_b128 v[74:77], v86 offset:49152
	ds_read_b128 v[86:89], v86 offset:53248
	v_mfma_f32_32x32x16_bf16 v[2:17], v[70:73], v[66:69], v[2:17]
	s_waitcnt vmcnt(0) lgkmcnt(0)
	s_barrier
	s_waitcnt lgkmcnt(0)
	s_add_u32 m0, s30, 0x4000
	s_nop 0
	global_load_lds_dwordx4 v200, s[98:99]
	s_add_u32 m0, s30, 0x5000
	s_nop 0
	global_load_lds_dwordx4 v201, s[98:99]
	s_add_u32 m0, s30, 0x6000
	s_nop 0
	global_load_lds_dwordx4 v202, s[98:99]
	s_add_u32 m0, s30, 0x7000
	s_nop 0
	global_load_lds_dwordx4 v204, s[98:99]
	s_add_u32 m0, s30, 0xc000
	s_nop 0
	global_load_lds_dwordx4 v200, s[100:101]
	s_add_u32 m0, s30, 0xd000
	s_nop 0
	global_load_lds_dwordx4 v201, s[100:101]
	s_add_u32 m0, s30, 0xe000
	s_nop 0
	global_load_lds_dwordx4 v202, s[100:101]
	s_add_u32 m0, s30, 0xf000
	s_nop 0
	global_load_lds_dwordx4 v204, s[100:101]
	v_mfma_f32_32x32x16_bf16 v[50:65], v[74:77], v[78:81], v[50:65]
	v_mov_b32_e32 v70, v226
	v_add_u32_e32 v66, v70, v224
	v_add_u32_e32 v70, v70, v225
	v_mfma_f32_32x32x16_bf16 v[34:49], v[86:89], v[78:81], v[34:49]
	ds_read_b128 v[78:81], v66
	ds_read_b128 v[66:69], v66 offset:4096
	v_mfma_f32_32x32x16_bf16 v[18:33], v[74:77], v[82:85], v[18:33]
	ds_read_b128 v[74:77], v70 offset:32768
	ds_read_b128 v[70:73], v70 offset:36864
	v_mfma_f32_32x32x16_bf16 v[2:17], v[86:89], v[82:85], v[2:17]
	s_add_u32 s98, s98, 0x80
	s_addc_u32 s99, s99, 0
	s_add_u32 s100, s100, 0x80
	s_addc_u32 s101, s101, 0
	s_nop 15
	v_lshlrev_b32_e32 v220, 16, v130
	v_and_b32_e32 v221, 0xffff0000, v130
	v_fmac_f32_e32 v227, v2, v220
	v_fmac_f32_e32 v228, v3, v221
	v_lshlrev_b32_e32 v220, 16, v131
	v_and_b32_e32 v221, 0xffff0000, v131
	v_fmac_f32_e32 v229, v4, v220
	v_fmac_f32_e32 v230, v5, v221
	v_lshlrev_b32_e32 v220, 16, v132
	v_and_b32_e32 v221, 0xffff0000, v132
	v_fmac_f32_e32 v231, v6, v220
	v_fmac_f32_e32 v232, v7, v221
	v_lshlrev_b32_e32 v220, 16, v133
	v_and_b32_e32 v221, 0xffff0000, v133
	v_fmac_f32_e32 v233, v8, v220
	v_fmac_f32_e32 v234, v9, v221
	v_lshlrev_b32_e32 v220, 16, v134
	v_and_b32_e32 v221, 0xffff0000, v134
	v_fmac_f32_e32 v235, v10, v220
	v_fmac_f32_e32 v236, v11, v221
	v_lshlrev_b32_e32 v220, 16, v135
	v_and_b32_e32 v221, 0xffff0000, v135
	v_fmac_f32_e32 v237, v12, v220
	v_fmac_f32_e32 v238, v13, v221
	v_lshlrev_b32_e32 v220, 16, v136
	v_and_b32_e32 v221, 0xffff0000, v136
	v_fmac_f32_e32 v239, v14, v220
	v_fmac_f32_e32 v240, v15, v221
	v_lshlrev_b32_e32 v220, 16, v137
	v_and_b32_e32 v221, 0xffff0000, v137
	v_fmac_f32_e32 v241, v16, v220
	v_fmac_f32_e32 v242, v17, v221
	v_lshlrev_b32_e32 v220, 16, v138
	v_and_b32_e32 v221, 0xffff0000, v138
	v_fmac_f32_e32 v243, v18, v220
	v_fmac_f32_e32 v244, v19, v221
	v_lshlrev_b32_e32 v220, 16, v139
	v_and_b32_e32 v221, 0xffff0000, v139
	v_fmac_f32_e32 v245, v20, v220
	v_fmac_f32_e32 v246, v21, v221
	v_lshlrev_b32_e32 v220, 16, v140
	v_and_b32_e32 v221, 0xffff0000, v140
	v_fmac_f32_e32 v247, v22, v220
	v_fmac_f32_e32 v248, v23, v221
	v_lshlrev_b32_e32 v220, 16, v141
	v_and_b32_e32 v221, 0xffff0000, v141
	v_fmac_f32_e32 v249, v24, v220
	v_fmac_f32_e32 v250, v25, v221
	v_lshlrev_b32_e32 v220, 16, v142
	v_and_b32_e32 v221, 0xffff0000, v142
	v_fmac_f32_e32 v251, v26, v220
	v_fmac_f32_e32 v90, v27, v221
	v_lshlrev_b32_e32 v220, 16, v143
	v_and_b32_e32 v221, 0xffff0000, v143
	v_fmac_f32_e32 v91, v28, v220
	v_fmac_f32_e32 v92, v29, v221
	v_lshlrev_b32_e32 v220, 16, v144
	v_and_b32_e32 v221, 0xffff0000, v144
	v_fmac_f32_e32 v93, v30, v220
	v_fmac_f32_e32 v94, v31, v221
	v_lshlrev_b32_e32 v220, 16, v145
	v_and_b32_e32 v221, 0xffff0000, v145
	v_fmac_f32_e32 v95, v32, v220
	v_fmac_f32_e32 v96, v33, v221
	v_lshlrev_b32_e32 v220, 16, v146
	v_and_b32_e32 v221, 0xffff0000, v146
	v_fmac_f32_e32 v98, v34, v220
	v_fmac_f32_e32 v99, v35, v221
	v_lshlrev_b32_e32 v220, 16, v147
	v_and_b32_e32 v221, 0xffff0000, v147
	v_fmac_f32_e32 v100, v36, v220
	v_fmac_f32_e32 v101, v37, v221
	v_lshlrev_b32_e32 v220, 16, v148
	v_and_b32_e32 v221, 0xffff0000, v148
	v_fmac_f32_e32 v102, v38, v220
	v_fmac_f32_e32 v103, v39, v221
	v_lshlrev_b32_e32 v220, 16, v149
	v_and_b32_e32 v221, 0xffff0000, v149
	v_fmac_f32_e32 v104, v40, v220
	v_fmac_f32_e32 v105, v41, v221
	v_lshlrev_b32_e32 v220, 16, v150
	v_and_b32_e32 v221, 0xffff0000, v150
	v_fmac_f32_e32 v106, v42, v220
	v_fmac_f32_e32 v107, v43, v221
	v_lshlrev_b32_e32 v220, 16, v151
	v_and_b32_e32 v221, 0xffff0000, v151
	v_fmac_f32_e32 v108, v44, v220
	v_fmac_f32_e32 v109, v45, v221
	v_lshlrev_b32_e32 v220, 16, v152
	v_and_b32_e32 v221, 0xffff0000, v152
	v_fmac_f32_e32 v110, v46, v220
	v_fmac_f32_e32 v111, v47, v221
	v_lshlrev_b32_e32 v220, 16, v153
	v_and_b32_e32 v221, 0xffff0000, v153
	v_fmac_f32_e32 v112, v48, v220
	v_fmac_f32_e32 v113, v49, v221
	v_lshlrev_b32_e32 v220, 16, v154
	v_and_b32_e32 v221, 0xffff0000, v154
	v_fmac_f32_e32 v114, v50, v220
	v_fmac_f32_e32 v115, v51, v221
	v_lshlrev_b32_e32 v220, 16, v155
	v_and_b32_e32 v221, 0xffff0000, v155
	v_fmac_f32_e32 v116, v52, v220
	v_fmac_f32_e32 v117, v53, v221
	v_lshlrev_b32_e32 v220, 16, v156
	v_and_b32_e32 v221, 0xffff0000, v156
	v_fmac_f32_e32 v118, v54, v220
	v_fmac_f32_e32 v119, v55, v221
	v_lshlrev_b32_e32 v220, 16, v157
	v_and_b32_e32 v221, 0xffff0000, v157
	v_fmac_f32_e32 v120, v56, v220
	v_fmac_f32_e32 v121, v57, v221
	v_lshlrev_b32_e32 v220, 16, v158
	v_and_b32_e32 v221, 0xffff0000, v158
	v_fmac_f32_e32 v122, v58, v220
	v_fmac_f32_e32 v123, v59, v221
	v_lshlrev_b32_e32 v220, 16, v159
	v_and_b32_e32 v221, 0xffff0000, v159
	v_fmac_f32_e32 v124, v60, v220
	v_fmac_f32_e32 v125, v61, v221
	v_lshlrev_b32_e32 v220, 16, v160
	v_and_b32_e32 v221, 0xffff0000, v160
	v_fmac_f32_e32 v126, v62, v220
	v_fmac_f32_e32 v127, v63, v221
	v_lshlrev_b32_e32 v220, 16, v161
	v_and_b32_e32 v221, 0xffff0000, v161
	v_fmac_f32_e32 v128, v64, v220
	v_fmac_f32_e32 v129, v65, v221
	v_mov_b32_e32 v2, 0
	v_mov_b32_e32 v3, 0
	v_mov_b32_e32 v4, 0
	v_mov_b32_e32 v5, 0
	v_mov_b32_e32 v6, 0
	v_mov_b32_e32 v7, 0
	v_mov_b32_e32 v8, 0
	v_mov_b32_e32 v9, 0
	v_mov_b32_e32 v10, 0
	v_mov_b32_e32 v11, 0
	v_mov_b32_e32 v12, 0
	v_mov_b32_e32 v13, 0
	v_mov_b32_e32 v14, 0
	v_mov_b32_e32 v15, 0
	v_mov_b32_e32 v16, 0
	v_mov_b32_e32 v17, 0
	v_mov_b32_e32 v18, 0
	v_mov_b32_e32 v19, 0
	v_mov_b32_e32 v20, 0
	v_mov_b32_e32 v21, 0
	v_mov_b32_e32 v22, 0
	v_mov_b32_e32 v23, 0
	v_mov_b32_e32 v24, 0
	v_mov_b32_e32 v25, 0
	v_mov_b32_e32 v26, 0
	v_mov_b32_e32 v27, 0
	v_mov_b32_e32 v28, 0
	v_mov_b32_e32 v29, 0
	v_mov_b32_e32 v30, 0
	v_mov_b32_e32 v31, 0
	v_mov_b32_e32 v32, 0
	v_mov_b32_e32 v33, 0
	v_mov_b32_e32 v34, 0
	v_mov_b32_e32 v35, 0
	v_mov_b32_e32 v36, 0
	v_mov_b32_e32 v37, 0
	v_mov_b32_e32 v38, 0
	v_mov_b32_e32 v39, 0
	v_mov_b32_e32 v40, 0
	v_mov_b32_e32 v41, 0
	v_mov_b32_e32 v42, 0
	v_mov_b32_e32 v43, 0
	v_mov_b32_e32 v44, 0
	v_mov_b32_e32 v45, 0
	v_mov_b32_e32 v46, 0
	v_mov_b32_e32 v47, 0
	v_mov_b32_e32 v48, 0
	v_mov_b32_e32 v49, 0
	v_mov_b32_e32 v50, 0
	v_mov_b32_e32 v51, 0
	v_mov_b32_e32 v52, 0
	v_mov_b32_e32 v53, 0
	v_mov_b32_e32 v54, 0
	v_mov_b32_e32 v55, 0
	v_mov_b32_e32 v56, 0
	v_mov_b32_e32 v57, 0
	v_mov_b32_e32 v58, 0
	v_mov_b32_e32 v59, 0
	v_mov_b32_e32 v60, 0
	v_mov_b32_e32 v61, 0
	v_mov_b32_e32 v62, 0
	v_mov_b32_e32 v63, 0
	v_mov_b32_e32 v64, 0
	v_mov_b32_e32 v65, 0
	s_nop 4
	s_waitcnt lgkmcnt(0)
	v_mfma_f32_32x32x16_bf16 v[50:65], v[74:77], v[78:81], v[50:65]
	v_xor_b32_e32 v86, 0x20, v226
	v_add_u32_e32 v82, v86, v224
	v_add_u32_e32 v86, v86, v225
	v_mfma_f32_32x32x16_bf16 v[34:49], v[70:73], v[78:81], v[34:49]
	ds_read_b128 v[78:81], v82
	ds_read_b128 v[82:85], v82 offset:4096
	v_mfma_f32_32x32x16_bf16 v[18:33], v[74:77], v[66:69], v[18:33]
	ds_read_b128 v[74:77], v86 offset:32768
	ds_read_b128 v[86:89], v86 offset:36864
	v_mfma_f32_32x32x16_bf16 v[2:17], v[70:73], v[66:69], v[2:17]
	s_waitcnt lgkmcnt(0)
	v_mfma_f32_32x32x16_bf16 v[50:65], v[74:77], v[78:81], v[50:65]
	v_xor_b32_e32 v70, 0x40, v226
	v_add_u32_e32 v66, v70, v224
	v_add_u32_e32 v70, v70, v225
	v_mfma_f32_32x32x16_bf16 v[34:49], v[86:89], v[78:81], v[34:49]
	ds_read_b128 v[78:81], v66
	ds_read_b128 v[66:69], v66 offset:4096
	v_mfma_f32_32x32x16_bf16 v[18:33], v[74:77], v[82:85], v[18:33]
	ds_read_b128 v[74:77], v70 offset:32768
	ds_read_b128 v[70:73], v70 offset:36864
	v_mfma_f32_32x32x16_bf16 v[2:17], v[86:89], v[82:85], v[2:17]
	s_waitcnt lgkmcnt(0)
	v_mfma_f32_32x32x16_bf16 v[50:65], v[74:77], v[78:81], v[50:65]
	v_xor_b32_e32 v86, 0x60, v226
	v_add_u32_e32 v82, v86, v224
	v_add_u32_e32 v86, v86, v225
	v_mfma_f32_32x32x16_bf16 v[34:49], v[70:73], v[78:81], v[34:49]
	ds_read_b128 v[78:81], v82
	ds_read_b128 v[82:85], v82 offset:4096
	v_mfma_f32_32x32x16_bf16 v[18:33], v[74:77], v[66:69], v[18:33]
	ds_read_b128 v[74:77], v86 offset:32768
	ds_read_b128 v[86:89], v86 offset:36864
	v_mfma_f32_32x32x16_bf16 v[2:17], v[70:73], v[66:69], v[2:17]
	s_waitcnt vmcnt(0) lgkmcnt(0)
	s_barrier
	s_waitcnt lgkmcnt(0)
	s_add_u32 m0, s30, 0x0
	s_nop 0
	global_load_lds_dwordx4 v200, s[98:99]
	s_add_u32 m0, s30, 0x1000
	s_nop 0
	global_load_lds_dwordx4 v201, s[98:99]
	s_add_u32 m0, s30, 0x2000
	s_nop 0
	global_load_lds_dwordx4 v202, s[98:99]
	s_add_u32 m0, s30, 0x3000
	s_nop 0
	global_load_lds_dwordx4 v204, s[98:99]
	s_add_u32 m0, s30, 0x8000
	s_nop 0
	global_load_lds_dwordx4 v200, s[100:101]
	s_add_u32 m0, s30, 0x9000
	s_nop 0
	global_load_lds_dwordx4 v201, s[100:101]
	s_add_u32 m0, s30, 0xa000
	s_nop 0
	global_load_lds_dwordx4 v202, s[100:101]
	s_add_u32 m0, s30, 0xb000
	s_nop 0
	global_load_lds_dwordx4 v204, s[100:101]
	v_mfma_f32_32x32x16_bf16 v[50:65], v[74:77], v[78:81], v[50:65]
	v_mov_b32_e32 v70, v226
	v_add_u32_e32 v66, v70, v224
	v_add_u32_e32 v70, v70, v225
	v_mfma_f32_32x32x16_bf16 v[34:49], v[86:89], v[78:81], v[34:49]
	ds_read_b128 v[78:81], v66 offset:16384
	ds_read_b128 v[66:69], v66 offset:20480
	v_mfma_f32_32x32x16_bf16 v[18:33], v[74:77], v[82:85], v[18:33]
	ds_read_b128 v[74:77], v70 offset:49152
	ds_read_b128 v[70:73], v70 offset:53248
	v_mfma_f32_32x32x16_bf16 v[2:17], v[86:89], v[82:85], v[2:17]
	s_add_u32 s98, s98, 0x80
	s_addc_u32 s99, s99, 0
	s_add_u32 s100, s100, 0x80
	s_addc_u32 s101, s101, 0
	s_waitcnt lgkmcnt(0)
	v_mfma_f32_32x32x16_bf16 v[50:65], v[74:77], v[78:81], v[50:65]
	v_xor_b32_e32 v86, 0x20, v226
	v_add_u32_e32 v82, v86, v224
	v_add_u32_e32 v86, v86, v225
	v_mfma_f32_32x32x16_bf16 v[34:49], v[70:73], v[78:81], v[34:49]
	ds_read_b128 v[78:81], v82 offset:16384
	ds_read_b128 v[82:85], v82 offset:20480
	v_mfma_f32_32x32x16_bf16 v[18:33], v[74:77], v[66:69], v[18:33]
	ds_read_b128 v[74:77], v86 offset:49152
	ds_read_b128 v[86:89], v86 offset:53248
	v_mfma_f32_32x32x16_bf16 v[2:17], v[70:73], v[66:69], v[2:17]
	s_waitcnt lgkmcnt(0)
	v_mfma_f32_32x32x16_bf16 v[50:65], v[74:77], v[78:81], v[50:65]
	v_xor_b32_e32 v70, 0x40, v226
	v_add_u32_e32 v66, v70, v224
	v_add_u32_e32 v70, v70, v225
	v_mfma_f32_32x32x16_bf16 v[34:49], v[86:89], v[78:81], v[34:49]
	ds_read_b128 v[78:81], v66 offset:16384
	ds_read_b128 v[66:69], v66 offset:20480
	v_mfma_f32_32x32x16_bf16 v[18:33], v[74:77], v[82:85], v[18:33]
	ds_read_b128 v[74:77], v70 offset:49152
	ds_read_b128 v[70:73], v70 offset:53248
	v_mfma_f32_32x32x16_bf16 v[2:17], v[86:89], v[82:85], v[2:17]
	s_waitcnt lgkmcnt(0)
	v_mfma_f32_32x32x16_bf16 v[50:65], v[74:77], v[78:81], v[50:65]
	v_xor_b32_e32 v86, 0x60, v226
	v_add_u32_e32 v82, v86, v224
	v_add_u32_e32 v86, v86, v225
	v_mfma_f32_32x32x16_bf16 v[34:49], v[70:73], v[78:81], v[34:49]
	ds_read_b128 v[78:81], v82 offset:16384
	ds_read_b128 v[82:85], v82 offset:20480
	v_mfma_f32_32x32x16_bf16 v[18:33], v[74:77], v[66:69], v[18:33]
	ds_read_b128 v[74:77], v86 offset:49152
	ds_read_b128 v[86:89], v86 offset:53248
	v_mfma_f32_32x32x16_bf16 v[2:17], v[70:73], v[66:69], v[2:17]
	s_waitcnt vmcnt(0) lgkmcnt(0)
	s_barrier
	s_waitcnt lgkmcnt(0)
	s_add_u32 m0, s30, 0x4000
	s_nop 0
	global_load_lds_dwordx4 v200, s[98:99]
	s_add_u32 m0, s30, 0x5000
	s_nop 0
	global_load_lds_dwordx4 v201, s[98:99]
	s_add_u32 m0, s30, 0x6000
	s_nop 0
	global_load_lds_dwordx4 v202, s[98:99]
	s_add_u32 m0, s30, 0x7000
	s_nop 0
	global_load_lds_dwordx4 v204, s[98:99]
	s_add_u32 m0, s30, 0xc000
	s_nop 0
	global_load_lds_dwordx4 v200, s[100:101]
	s_add_u32 m0, s30, 0xd000
	s_nop 0
	global_load_lds_dwordx4 v201, s[100:101]
	s_add_u32 m0, s30, 0xe000
	s_nop 0
	global_load_lds_dwordx4 v202, s[100:101]
	s_add_u32 m0, s30, 0xf000
	s_nop 0
	global_load_lds_dwordx4 v204, s[100:101]
	v_mfma_f32_32x32x16_bf16 v[50:65], v[74:77], v[78:81], v[50:65]
	v_mov_b32_e32 v70, v226
	v_add_u32_e32 v66, v70, v224
	v_add_u32_e32 v70, v70, v225
	v_mfma_f32_32x32x16_bf16 v[34:49], v[86:89], v[78:81], v[34:49]
	ds_read_b128 v[78:81], v66
	ds_read_b128 v[66:69], v66 offset:4096
	v_mfma_f32_32x32x16_bf16 v[18:33], v[74:77], v[82:85], v[18:33]
	ds_read_b128 v[74:77], v70 offset:32768
	ds_read_b128 v[70:73], v70 offset:36864
	v_mfma_f32_32x32x16_bf16 v[2:17], v[86:89], v[82:85], v[2:17]
	s_add_u32 s98, s98, 0x80
	s_addc_u32 s99, s99, 0
	s_add_u32 s100, s100, 0x80
	s_addc_u32 s101, s101, 0
	s_waitcnt lgkmcnt(0)
	v_mfma_f32_32x32x16_bf16 v[50:65], v[74:77], v[78:81], v[50:65]
	v_xor_b32_e32 v86, 0x20, v226
	v_add_u32_e32 v82, v86, v224
	v_add_u32_e32 v86, v86, v225
	v_mfma_f32_32x32x16_bf16 v[34:49], v[70:73], v[78:81], v[34:49]
	ds_read_b128 v[78:81], v82
	ds_read_b128 v[82:85], v82 offset:4096
	v_mfma_f32_32x32x16_bf16 v[18:33], v[74:77], v[66:69], v[18:33]
	ds_read_b128 v[74:77], v86 offset:32768
	ds_read_b128 v[86:89], v86 offset:36864
	v_mfma_f32_32x32x16_bf16 v[2:17], v[70:73], v[66:69], v[2:17]
	s_waitcnt lgkmcnt(0)
	v_mfma_f32_32x32x16_bf16 v[50:65], v[74:77], v[78:81], v[50:65]
	v_xor_b32_e32 v70, 0x40, v226
	v_add_u32_e32 v66, v70, v224
	v_add_u32_e32 v70, v70, v225
	v_mfma_f32_32x32x16_bf16 v[34:49], v[86:89], v[78:81], v[34:49]
	ds_read_b128 v[78:81], v66
	ds_read_b128 v[66:69], v66 offset:4096
	v_mfma_f32_32x32x16_bf16 v[18:33], v[74:77], v[82:85], v[18:33]
	ds_read_b128 v[74:77], v70 offset:32768
	ds_read_b128 v[70:73], v70 offset:36864
	v_mfma_f32_32x32x16_bf16 v[2:17], v[86:89], v[82:85], v[2:17]
	s_waitcnt lgkmcnt(0)
	v_mfma_f32_32x32x16_bf16 v[50:65], v[74:77], v[78:81], v[50:65]
	v_xor_b32_e32 v86, 0x60, v226
	v_add_u32_e32 v82, v86, v224
	v_add_u32_e32 v86, v86, v225
	v_mfma_f32_32x32x16_bf16 v[34:49], v[70:73], v[78:81], v[34:49]
	ds_read_b128 v[78:81], v82
	ds_read_b128 v[82:85], v82 offset:4096
	v_mfma_f32_32x32x16_bf16 v[18:33], v[74:77], v[66:69], v[18:33]
	ds_read_b128 v[74:77], v86 offset:32768
	ds_read_b128 v[86:89], v86 offset:36864
	v_mfma_f32_32x32x16_bf16 v[2:17], v[70:73], v[66:69], v[2:17]
	s_waitcnt vmcnt(0) lgkmcnt(0)
	s_barrier
	s_waitcnt lgkmcnt(0)
	v_mfma_f32_32x32x16_bf16 v[50:65], v[74:77], v[78:81], v[50:65]
	v_mov_b32_e32 v70, v226
	v_add_u32_e32 v66, v70, v224
	v_add_u32_e32 v70, v70, v225
	v_mfma_f32_32x32x16_bf16 v[34:49], v[86:89], v[78:81], v[34:49]
	ds_read_b128 v[78:81], v66 offset:16384
	ds_read_b128 v[66:69], v66 offset:20480
	v_mfma_f32_32x32x16_bf16 v[18:33], v[74:77], v[82:85], v[18:33]
	ds_read_b128 v[74:77], v70 offset:49152
	ds_read_b128 v[70:73], v70 offset:53248
	v_mfma_f32_32x32x16_bf16 v[2:17], v[86:89], v[82:85], v[2:17]
	s_waitcnt lgkmcnt(0)
	v_mfma_f32_32x32x16_bf16 v[50:65], v[74:77], v[78:81], v[50:65]
	v_xor_b32_e32 v86, 0x20, v226
	v_add_u32_e32 v82, v86, v224
	v_add_u32_e32 v86, v86, v225
	v_mfma_f32_32x32x16_bf16 v[34:49], v[70:73], v[78:81], v[34:49]
	ds_read_b128 v[78:81], v82 offset:16384
	ds_read_b128 v[82:85], v82 offset:20480
	v_mfma_f32_32x32x16_bf16 v[18:33], v[74:77], v[66:69], v[18:33]
	ds_read_b128 v[74:77], v86 offset:49152
	ds_read_b128 v[86:89], v86 offset:53248
	v_mfma_f32_32x32x16_bf16 v[2:17], v[70:73], v[66:69], v[2:17]
	s_waitcnt lgkmcnt(0)
	v_mfma_f32_32x32x16_bf16 v[50:65], v[74:77], v[78:81], v[50:65]
	v_xor_b32_e32 v70, 0x40, v226
	v_add_u32_e32 v66, v70, v224
	v_add_u32_e32 v70, v70, v225
	v_mfma_f32_32x32x16_bf16 v[34:49], v[86:89], v[78:81], v[34:49]
	ds_read_b128 v[78:81], v66 offset:16384
	ds_read_b128 v[66:69], v66 offset:20480
	v_mfma_f32_32x32x16_bf16 v[18:33], v[74:77], v[82:85], v[18:33]
	ds_read_b128 v[74:77], v70 offset:49152
	ds_read_b128 v[70:73], v70 offset:53248
	v_mfma_f32_32x32x16_bf16 v[2:17], v[86:89], v[82:85], v[2:17]
	s_waitcnt lgkmcnt(0)
	v_mfma_f32_32x32x16_bf16 v[50:65], v[74:77], v[78:81], v[50:65]
	v_xor_b32_e32 v86, 0x60, v226
	v_add_u32_e32 v82, v86, v224
	v_add_u32_e32 v86, v86, v225
	v_mfma_f32_32x32x16_bf16 v[34:49], v[70:73], v[78:81], v[34:49]
	ds_read_b128 v[78:81], v82 offset:16384
	ds_read_b128 v[82:85], v82 offset:20480
	v_mfma_f32_32x32x16_bf16 v[18:33], v[74:77], v[66:69], v[18:33]
	ds_read_b128 v[74:77], v86 offset:49152
	ds_read_b128 v[86:89], v86 offset:53248
	v_mfma_f32_32x32x16_bf16 v[2:17], v[70:73], v[66:69], v[2:17]
	s_waitcnt lgkmcnt(0)
	v_mfma_f32_32x32x16_bf16 v[50:65], v[74:77], v[78:81], v[50:65]
	v_mfma_f32_32x32x16_bf16 v[34:49], v[86:89], v[78:81], v[34:49]
	v_mfma_f32_32x32x16_bf16 v[18:33], v[74:77], v[82:85], v[18:33]
	v_mfma_f32_32x32x16_bf16 v[2:17], v[86:89], v[82:85], v[2:17]
	s_nop 15
	v_lshlrev_b32_e32 v220, 16, v162
	v_and_b32_e32 v221, 0xffff0000, v162
	v_fma_f32 v2, v2, v220, v227
	v_fma_f32 v3, v3, v221, v228
	v_lshlrev_b32_e32 v220, 16, v163
	v_and_b32_e32 v221, 0xffff0000, v163
	v_fma_f32 v4, v4, v220, v229
	v_fma_f32 v5, v5, v221, v230
	v_lshlrev_b32_e32 v220, 16, v164
	v_and_b32_e32 v221, 0xffff0000, v164
	v_fma_f32 v6, v6, v220, v231
	v_fma_f32 v7, v7, v221, v232
	v_lshlrev_b32_e32 v220, 16, v165
	v_and_b32_e32 v221, 0xffff0000, v165
	v_fma_f32 v8, v8, v220, v233
	v_fma_f32 v9, v9, v221, v234
	v_lshlrev_b32_e32 v220, 16, v166
	v_and_b32_e32 v221, 0xffff0000, v166
	v_fma_f32 v10, v10, v220, v235
	v_fma_f32 v11, v11, v221, v236
	v_lshlrev_b32_e32 v220, 16, v167
	v_and_b32_e32 v221, 0xffff0000, v167
	v_fma_f32 v12, v12, v220, v237
	v_fma_f32 v13, v13, v221, v238
	v_lshlrev_b32_e32 v220, 16, v168
	v_and_b32_e32 v221, 0xffff0000, v168
	v_fma_f32 v14, v14, v220, v239
	v_fma_f32 v15, v15, v221, v240
	v_lshlrev_b32_e32 v220, 16, v169
	v_and_b32_e32 v221, 0xffff0000, v169
	v_fma_f32 v16, v16, v220, v241
	v_fma_f32 v17, v17, v221, v242
	v_lshlrev_b32_e32 v220, 16, v170
	v_and_b32_e32 v221, 0xffff0000, v170
	v_fma_f32 v18, v18, v220, v243
	v_fma_f32 v19, v19, v221, v244
	v_lshlrev_b32_e32 v220, 16, v171
	v_and_b32_e32 v221, 0xffff0000, v171
	v_fma_f32 v20, v20, v220, v245
	v_fma_f32 v21, v21, v221, v246
	v_lshlrev_b32_e32 v220, 16, v172
	v_and_b32_e32 v221, 0xffff0000, v172
	v_fma_f32 v22, v22, v220, v247
	v_fma_f32 v23, v23, v221, v248
	v_lshlrev_b32_e32 v220, 16, v173
	v_and_b32_e32 v221, 0xffff0000, v173
	v_fma_f32 v24, v24, v220, v249
	v_fma_f32 v25, v25, v221, v250
	v_lshlrev_b32_e32 v220, 16, v174
	v_and_b32_e32 v221, 0xffff0000, v174
	v_fma_f32 v26, v26, v220, v251
	v_fma_f32 v27, v27, v221, v90
	v_lshlrev_b32_e32 v220, 16, v175
	v_and_b32_e32 v221, 0xffff0000, v175
	v_fma_f32 v28, v28, v220, v91
	v_fma_f32 v29, v29, v221, v92
	v_lshlrev_b32_e32 v220, 16, v176
	v_and_b32_e32 v221, 0xffff0000, v176
	v_fma_f32 v30, v30, v220, v93
	v_fma_f32 v31, v31, v221, v94
	v_lshlrev_b32_e32 v220, 16, v177
	v_and_b32_e32 v221, 0xffff0000, v177
	v_fma_f32 v32, v32, v220, v95
	v_fma_f32 v33, v33, v221, v96
	v_lshlrev_b32_e32 v220, 16, v178
	v_and_b32_e32 v221, 0xffff0000, v178
	v_fma_f32 v34, v34, v220, v98
	v_fma_f32 v35, v35, v221, v99
	v_lshlrev_b32_e32 v220, 16, v179
	v_and_b32_e32 v221, 0xffff0000, v179
	v_fma_f32 v36, v36, v220, v100
	v_fma_f32 v37, v37, v221, v101
	v_lshlrev_b32_e32 v220, 16, v180
	v_and_b32_e32 v221, 0xffff0000, v180
	v_fma_f32 v38, v38, v220, v102
	v_fma_f32 v39, v39, v221, v103
	v_lshlrev_b32_e32 v220, 16, v181
	v_and_b32_e32 v221, 0xffff0000, v181
	v_fma_f32 v40, v40, v220, v104
	v_fma_f32 v41, v41, v221, v105
	v_lshlrev_b32_e32 v220, 16, v182
	v_and_b32_e32 v221, 0xffff0000, v182
	v_fma_f32 v42, v42, v220, v106
	v_fma_f32 v43, v43, v221, v107
	v_lshlrev_b32_e32 v220, 16, v183
	v_and_b32_e32 v221, 0xffff0000, v183
	v_fma_f32 v44, v44, v220, v108
	v_fma_f32 v45, v45, v221, v109
	v_lshlrev_b32_e32 v220, 16, v184
	v_and_b32_e32 v221, 0xffff0000, v184
	v_fma_f32 v46, v46, v220, v110
	v_fma_f32 v47, v47, v221, v111
	v_lshlrev_b32_e32 v220, 16, v185
	v_and_b32_e32 v221, 0xffff0000, v185
	v_fma_f32 v48, v48, v220, v112
	v_fma_f32 v49, v49, v221, v113
	v_lshlrev_b32_e32 v220, 16, v186
	v_and_b32_e32 v221, 0xffff0000, v186
	v_fma_f32 v50, v50, v220, v114
	v_fma_f32 v51, v51, v221, v115
	v_lshlrev_b32_e32 v220, 16, v187
	v_and_b32_e32 v221, 0xffff0000, v187
	v_fma_f32 v52, v52, v220, v116
	v_fma_f32 v53, v53, v221, v117
	v_lshlrev_b32_e32 v220, 16, v188
	v_and_b32_e32 v221, 0xffff0000, v188
	v_fma_f32 v54, v54, v220, v118
	v_fma_f32 v55, v55, v221, v119
	v_lshlrev_b32_e32 v220, 16, v189
	v_and_b32_e32 v221, 0xffff0000, v189
	v_fma_f32 v56, v56, v220, v120
	v_fma_f32 v57, v57, v221, v121
	v_lshlrev_b32_e32 v220, 16, v190
	v_and_b32_e32 v221, 0xffff0000, v190
	v_fma_f32 v58, v58, v220, v122
	v_fma_f32 v59, v59, v221, v123
	v_lshlrev_b32_e32 v220, 16, v191
	v_and_b32_e32 v221, 0xffff0000, v191
	v_fma_f32 v60, v60, v220, v124
	v_fma_f32 v61, v61, v221, v125
	v_lshlrev_b32_e32 v220, 16, v192
	v_and_b32_e32 v221, 0xffff0000, v192
	v_fma_f32 v62, v62, v220, v126
	v_fma_f32 v63, v63, v221, v127
	v_lshlrev_b32_e32 v220, 16, v193
	v_and_b32_e32 v221, 0xffff0000, v193
	v_fma_f32 v64, v64, v220, v128
	v_fma_f32 v65, v65, v221, v129
	v_mov_b32_e32 v114, v2
	v_mov_b32_e32 v112, v3
	v_mov_b32_e32 v115, v4
	v_mov_b32_e32 v113, v5
	v_mov_b32_e32 v110, v6
	v_mov_b32_e32 v108, v7
	v_mov_b32_e32 v111, v8
	v_mov_b32_e32 v109, v9
	v_mov_b32_e32 v104, v10
	v_mov_b32_e32 v102, v11
	v_mov_b32_e32 v105, v12
	v_mov_b32_e32 v103, v13
	v_mov_b32_e32 v98, v14
	v_mov_b32_e32 v100, v15
	v_mov_b32_e32 v99, v16
	v_mov_b32_e32 v101, v17
	v_mov_b32_e32 v130, v18
	v_mov_b32_e32 v128, v19
	v_mov_b32_e32 v131, v20
	v_mov_b32_e32 v129, v21
	v_mov_b32_e32 v126, v22
	v_mov_b32_e32 v124, v23
	v_mov_b32_e32 v127, v24
	v_mov_b32_e32 v125, v25
	v_mov_b32_e32 v120, v26
	v_mov_b32_e32 v118, v27
	v_mov_b32_e32 v121, v28
	v_mov_b32_e32 v119, v29
	v_mov_b32_e32 v106, v30
	v_mov_b32_e32 v116, v31
	v_mov_b32_e32 v107, v32
	v_mov_b32_e32 v117, v33
	v_mov_b32_e32 v146, v34
	v_mov_b32_e32 v144, v35
	v_mov_b32_e32 v147, v36
	v_mov_b32_e32 v145, v37
	v_mov_b32_e32 v142, v38
	v_mov_b32_e32 v140, v39
	v_mov_b32_e32 v143, v40
	v_mov_b32_e32 v141, v41
	v_mov_b32_e32 v136, v42
	v_mov_b32_e32 v134, v43
	v_mov_b32_e32 v137, v44
	v_mov_b32_e32 v135, v45
	v_mov_b32_e32 v122, v46
	v_mov_b32_e32 v132, v47
	v_mov_b32_e32 v123, v48
	v_mov_b32_e32 v133, v49
	v_mov_b32_e32 v160, v50
	v_mov_b32_e32 v158, v51
	v_mov_b32_e32 v161, v52
	v_mov_b32_e32 v159, v53
	v_mov_b32_e32 v156, v54
	v_mov_b32_e32 v154, v55
	v_mov_b32_e32 v157, v56
	v_mov_b32_e32 v155, v57
	v_mov_b32_e32 v152, v58
	v_mov_b32_e32 v150, v59
	v_mov_b32_e32 v153, v60
	v_mov_b32_e32 v151, v61
	v_mov_b32_e32 v138, v62
	v_mov_b32_e32 v148, v63
	v_mov_b32_e32 v139, v64
	v_mov_b32_e32 v149, v65
	s_branch .LBB0_915
